# EpiRes (w_o / w_down) f32 residual stores: rows r and r+8 exchange chunks via DPP row_ror so each store instruction writes whole 128 B lines (8 rows x 128 B instead of 16 rows x 64 B)
# speedup vs baseline: 1.0193x; 1.0095x over previous
;     DI void operator()(AccRef acc, const Unit& u, int wr, int wc, int fr, int fq) const {
;     ...
; #pragma unroll
;         for (int ai = 0; ai < 2; ++ai) {
;             const int rb = u.pm * 256 + ai * 128 + wr * 64 + fr;
;             int mb, pos0, kv0; row_info(rb, mb, pos0, kv0);
;             f32x4 gt[2][2], gs[2][2];
; #pragma unroll
;             for (int bj = 0; bj < 2; ++bj)
; #pragma unroll
;                 for (int n = 0; n < 2; ++n) {
;                     const int c = u.pn * 256 + bj * 128 + cl + 4 * n;
;                     gt[bj][n] = *(const f32x4*)(gate + (size_t)mb * 6144 + c);
;                     if (ap) { const f32x4 g = *(const f32x4*)(gn + c), s = *(const f32x4*)(scn + (size_t)mb * 6144 + c); gs[bj][n] = g * (s + 1.f); }
;                 }
; #pragma unroll
;             for (int m = 0; m < 4; ++m) {
;                 const int row = rb + 16 * m;
;                 const float* xi = row < MP ? xin_p + (size_t)row * 1024 : xin_s + (size_t)(row - MP) * 1024;
;                 float s = 0.f;
; #pragma unroll
;                 for (int bj = 0; bj < 2; ++bj) {
;                     const int c = u.pn * 256 + bj * 128 + cl;
;                     float v[8];
; #pragma unroll
;                     for (int n = 0; n < 2; ++n) {
;                         const f32x4 x = *(const f32x4*)(xi + c + 4 * n);
;                         const f32x4 y = x + gt[bj][n] * acc[ai][bj][m][n];
.LBB0_1094:
	v_readlane_b32 s3, v253, 32
	v_mbcnt_lo_u32_b32 v100, -1, 0
	v_mbcnt_hi_u32_b32 v100, -1, v100
	s_mov_b32 s3, s30
	v_and_b32_e32 v202, 15, v100
	v_bfe_u32 v204, v100, 4, 2
	s_mov_b32 s12, s36
	s_lshl_b32 s16, s16, 8
	s_lshl_b32 s3, s3, 6
	s_add_i32 s3, s3, s16
	v_add_u32_e32 v192, s3, v202
	s_lshl_b32 s13, s12, 5
	s_lshl_b32 s3, s2, 8
	v_add_u32_e32 v224, 0xffffc000, v192
	s_add_i32 s13, s13, s3
	v_lshrrev_b32_e32 v101, 6, v224
	v_lshl_add_u32 v188, v204, 3, s13
	v_ashrrev_i32_e32 v100, 11, v192
	v_add_u32_e32 v101, 8, v101
	v_cmp_gt_i32_e32 vcc, s94, v192
	v_mov_b64_e32 v[102:103], s[60:61]
	v_ashrrev_i32_e32 v189, 31, v188
	v_cndmask_b32_e32 v104, v101, v100, vcc
	v_mov_b64_e32 v[100:101], s[8:9]
	v_mad_i64_i32 v[100:101], s[16:17], v104, s75, v[100:101]
	v_mad_i64_i32 v[102:103], s[16:17], v104, s75, v[102:103]
	v_lshlrev_b64 v[190:191], 2, v[188:189]
	v_lshl_add_u64 v[104:105], v[100:101], 0, v[190:191]
	v_lshl_add_u64 v[194:195], s[72:73], 0, v[190:191]
	v_lshl_add_u64 v[168:169], v[102:103], 0, v[190:191]
	global_load_dwordx4 v[108:111], v[104:105], off offset:16
	global_load_dwordx4 v[116:119], v[104:105], off
	global_load_dwordx4 v[148:151], v[194:195], off offset:16
	global_load_dwordx4 v[164:167], v[194:195], off
	global_load_dwordx4 v[160:163], v[168:169], off offset:16
	global_load_dwordx4 v[172:175], v[168:169], off
	global_load_dwordx4 v[100:103], v[104:105], off offset:528
	s_nop 0
	global_load_dwordx4 v[104:107], v[104:105], off offset:512
	s_nop 0
	global_load_dwordx4 v[144:147], v[194:195], off offset:528
	global_load_dwordx4 v[156:159], v[194:195], off offset:512
	global_load_dwordx4 v[152:155], v[168:169], off offset:528
	s_nop 0
	global_load_dwordx4 v[168:171], v[168:169], off offset:512
	s_movk_i32 s3, 0x3fff
	v_cmp_lt_i32_e32 vcc, s3, v192
	s_and_saveexec_b64 s[16:17], vcc
	s_xor_b64 s[16:17], exec, s[16:17]
	v_lshlrev_b64 v[196:197], 12, v[224:225]
	v_mov_b32_e32 v193, v225
	v_lshl_add_u64 v[198:199], s[20:21], 0, v[196:197]
	v_lshlrev_b64 v[196:197], 12, v[192:193]
	s_andn2_saveexec_b64 s[16:17], s[16:17]
	v_ashrrev_i32_e32 v193, 31, v192
	v_lshlrev_b64 v[196:197], 12, v[192:193]
	v_lshl_add_u64 v[198:199], s[42:43], 0, v[196:197]
	s_or_b64 exec, exec, s[16:17]
	s_sub_u32 s82, s20, 0x4000000
	s_subb_u32 s83, s21, 0
	s_cmp_ge_u32 s16, 0x4000
	s_cselect_b32 s82, s82, s42
	s_cselect_b32 s83, s83, s43
	v_lshl_add_u32 v206, v192, 12, v190
	v_lshlrev_b32_e32 v213, 4, v204
	v_sub_u32_e32 v206, v206, v213
	v_lshlrev_b32_e32 v213, 11, v192
	v_lshlrev_b32_e32 v209, 6, v192
	v_mov_b32_e32 v207, v206
	v_lshl_add_u32 v208, v188, 1, v213
	global_load_dwordx4 v[232:235], v206, s[82:83] offset:64
	global_load_dwordx4 v[240:243], v206, s[82:83] offset:576
	global_load_dwordx4 v[228:231], v206, s[82:83]
	global_load_dwordx4 v[236:239], v206, s[82:83] offset:512
	v_add_u32_e32 v206, 0x10000, v206
	global_load_dwordx4 v[248:251], v206, s[82:83] offset:64
	global_load_dwordx4 v[220:223], v206, s[82:83] offset:576
	global_load_dwordx4 v[244:247], v206, s[82:83]
	global_load_dwordx4 v[216:219], v206, s[82:83] offset:512
	v_add_u32_e32 v206, 0x10000, v206
	s_waitcnt vmcnt(8)
	v_pk_add_f32 v[172:173], v[172:173], 1.0 op_sel_hi:[1,0]
	v_pk_add_f32 v[154:155], v[154:155], 1.0 op_sel_hi:[1,0]
	v_pk_mul_f32 v[164:165], v[164:165], v[172:173]
	v_pk_add_f32 v[172:173], v[160:161], 1.0 op_sel_hi:[1,0]
	v_pk_add_f32 v[160:161], v[162:163], 1.0 op_sel_hi:[1,0]
	v_pk_mul_f32 v[162:163], v[148:149], v[172:173]
	v_pk_mul_f32 v[160:161], v[150:151], v[160:161]
	v_pk_add_f32 v[148:149], v[170:171], 1.0 op_sel_hi:[1,0]
	v_pk_add_f32 v[150:151], v[168:169], 1.0 op_sel_hi:[1,0]
	v_pk_mul_f32 v[146:147], v[146:147], v[154:155]
	v_lshl_add_u64 v[154:155], v[198:199], 0, v[190:191]
	v_pk_mul_f32 v[148:149], v[158:159], v[148:149]
	v_pk_mul_f32 v[150:151], v[156:157], v[150:151]
	v_pk_add_f32 v[174:175], v[174:175], 1.0 op_sel_hi:[1,0]
	v_pk_add_f32 v[152:153], v[152:153], 1.0 op_sel_hi:[1,0]
	v_pk_mul_f32 v[166:167], v[166:167], v[174:175]
	v_pk_mul_f32 v[144:145], v[144:145], v[152:153]
	v_lshlrev_b64 v[152:153], 11, v[192:193]
	v_lshl_add_u64 v[152:153], s[64:65], 0, v[152:153]
	v_lshlrev_b32_e32 v202, 2, v202
	v_lshl_add_u32 v202, v204, 6, v202
	v_xor_b32_e32 v203, 64, v202
	s_lshl_b32 s2, s2, 2
	v_xor_b32_e32 v202, 0x80, v202
	s_ashr_i32 s3, s2, 31
	s_ashr_i32 s13, s12, 31
	s_lshl_b64 s[2:3], s[2:3], 2
	s_add_u32 s16, s39, s2
	s_addc_u32 s17, s40, s3
	s_lshl_b64 s[2:3], s[12:13], 2
	s_add_u32 s90, s16, s2
	v_cmp_eq_u32_e32 vcc, 0, v204
	s_addc_u32 s91, s17, s3
	s_waitcnt vmcnt(4)
; DI u32x4 pack8(const float* v) { u32x4 w; w.x = pk2(v[0], v[1]); w.y = pk2(v[2], v[3]); w.z = pk2(v[4], v[5]); w.w = pk2(v[6], v[7]); return w; }
; #define xor16_32(s) xor16_32_l((s), fr + 16 * fq)
;     DI void operator()(AccRef acc, const Unit& u, int wr, int wc, int fr, int fq) const {
;     ...
;             for (int m = 0; m < 4; ++m) {
;                 const int row = rb + 16 * m;
;                 const float* xi = row < MP ? xin_p + (size_t)row * 1024 : xin_s + (size_t)(row - MP) * 1024;
;                 float s = 0.f;
; #pragma unroll
;                 for (int bj = 0; bj < 2; ++bj) {
;                     const int c = u.pn * 256 + bj * 128 + cl;
;                     float v[8];
; #pragma unroll
;                     for (int n = 0; n < 2; ++n) {
;                         const f32x4 x = *(const f32x4*)(xi + c + 4 * n);
;                         const f32x4 y = x + gt[bj][n] * acc[ai][bj][m][n];
;                         *(f32x4*)(xout + (size_t)row * 1024 + c + 4 * n) = y;
; #pragma unroll
;                         for (int j = 0; j < 4; ++j) { s += y[j] * y[j]; v[4 * n + j] = ap ? y[j] * gs[bj][n][j] : 0.f; }
;                     }
;                     if (ap) *(u32x4*)(ap + (size_t)row * 1024 + c) = pack8(v);
;                 }
;                 s = xor16_32(s);
;                 if (fq == 0) ssq[(size_t)row * 16 + u.pn * 4 + wc] = s;
	v_permlane32_swap_b32_e32 v228, v232
	v_permlane32_swap_b32_e32 v229, v233
	v_permlane32_swap_b32_e32 v230, v234
	v_permlane32_swap_b32_e32 v231, v235
	v_permlane32_swap_b32_e32 v236, v240
	v_permlane32_swap_b32_e32 v237, v241
	v_permlane32_swap_b32_e32 v238, v242
	v_permlane32_swap_b32_e32 v239, v243
	v_permlane16_swap_b32_e32 v228, v232
	v_permlane16_swap_b32_e32 v229, v233
	v_permlane16_swap_b32_e32 v230, v234
	v_permlane16_swap_b32_e32 v231, v235
	v_permlane16_swap_b32_e32 v236, v240
	v_permlane16_swap_b32_e32 v237, v241
	v_permlane16_swap_b32_e32 v238, v242
	v_permlane16_swap_b32_e32 v239, v243
	v_pk_fma_f32 v[140:141], v[140:141], v[116:117], v[228:229]
	v_pk_fma_f32 v[142:143], v[142:143], v[118:119], v[230:231]
	v_mul_f32_e32 v210, v141, v141
	v_fmac_f32_e32 v210, v140, v140
	v_fmac_f32_e32 v210, v142, v142
	v_fmac_f32_e32 v210, v143, v143
	v_pk_mul_f32 v[228:229], v[164:165], v[140:141]
	v_pk_mul_f32 v[230:231], v[166:167], v[142:143]
	v_pk_fma_f32 v[136:137], v[136:137], v[108:109], v[232:233]
	v_pk_fma_f32 v[138:139], v[138:139], v[110:111], v[234:235]
	v_fmac_f32_e32 v210, v136, v136
	v_fmac_f32_e32 v210, v137, v137
	v_fmac_f32_e32 v210, v138, v138
	v_fmac_f32_e32 v210, v139, v139
	v_pk_mul_f32 v[232:233], v[162:163], v[136:137]
	v_pk_mul_f32 v[234:235], v[160:161], v[138:139]
	v_cvt_pk_bf16_f32 v228, v228, v229
	v_cvt_pk_bf16_f32 v229, v230, v231
	v_cvt_pk_bf16_f32 v230, v232, v233
	v_cvt_pk_bf16_f32 v231, v234, v235
	global_store_dwordx4 v208, v[228:231], s[64:65]
	v_pk_fma_f32 v[132:133], v[132:133], v[104:105], v[236:237]
	v_pk_fma_f32 v[134:135], v[134:135], v[106:107], v[238:239]
	v_fmac_f32_e32 v210, v132, v132
	v_fmac_f32_e32 v210, v133, v133
	v_fmac_f32_e32 v210, v134, v134
	v_fmac_f32_e32 v210, v135, v135
	v_pk_mul_f32 v[236:237], v[150:151], v[132:133]
	v_pk_mul_f32 v[238:239], v[148:149], v[134:135]
	v_pk_fma_f32 v[128:129], v[128:129], v[100:101], v[240:241]
	v_pk_fma_f32 v[130:131], v[130:131], v[102:103], v[242:243]
	v_fmac_f32_e32 v210, v128, v128
	v_fmac_f32_e32 v210, v129, v129
	v_fmac_f32_e32 v210, v130, v130
	v_fmac_f32_e32 v210, v131, v131
	v_pk_mul_f32 v[240:241], v[144:145], v[128:129]
	v_pk_mul_f32 v[242:243], v[146:147], v[130:131]
	v_cvt_pk_bf16_f32 v236, v236, v237
	v_cvt_pk_bf16_f32 v237, v238, v239
	v_cvt_pk_bf16_f32 v238, v240, v241
	v_cvt_pk_bf16_f32 v239, v242, v243
	global_store_dwordx4 v208, v[236:239], s[64:65] offset:256
	ds_bpermute_b32 v211, v203, v210
	v_permlane16_swap_b32_e32 v140, v136
	v_permlane16_swap_b32_e32 v141, v137
	v_permlane16_swap_b32_e32 v142, v138
	v_permlane16_swap_b32_e32 v143, v139
	v_permlane16_swap_b32_e32 v132, v128
	v_permlane16_swap_b32_e32 v133, v129
	v_permlane16_swap_b32_e32 v134, v130
	v_permlane16_swap_b32_e32 v135, v131
	v_permlane32_swap_b32_e32 v140, v136
	v_permlane32_swap_b32_e32 v141, v137
	v_permlane32_swap_b32_e32 v142, v138
	v_permlane32_swap_b32_e32 v143, v139
	v_permlane32_swap_b32_e32 v132, v128
	v_permlane32_swap_b32_e32 v133, v129
	v_permlane32_swap_b32_e32 v134, v130
	v_permlane32_swap_b32_e32 v135, v131
	s_nop 1
	v_mov_b32_dpp v232, v136 row_ror:8 row_mask:0xf bank_mask:0xf
	v_mov_b32_dpp v233, v137 row_ror:8 row_mask:0xf bank_mask:0xf
	v_mov_b32_dpp v234, v138 row_ror:8 row_mask:0xf bank_mask:0xf
	v_mov_b32_dpp v235, v139 row_ror:8 row_mask:0xf bank_mask:0xf
	v_mov_b32_dpp v240, v128 row_ror:8 row_mask:0xf bank_mask:0xf
	v_mov_b32_dpp v241, v129 row_ror:8 row_mask:0xf bank_mask:0xf
	v_mov_b32_dpp v242, v130 row_ror:8 row_mask:0xf bank_mask:0xf
	v_mov_b32_dpp v243, v131 row_ror:8 row_mask:0xf bank_mask:0xf
	s_mov_b32 vcc_lo, 0xff00ff
	s_mov_b32 vcc_hi, 0xff00ff
	v_mov_b32_e32 v205, 0xffff8040
	v_mov_b32_e32 v214, 0x8040
	v_cndmask_b32_e64 v205, v205, 0, vcc
	v_cndmask_b32_e64 v214, 0, v214, vcc
	v_add_u32_e32 v205, v205, v207
	v_add_u32_e32 v214, v214, v207
	v_cndmask_b32_e32 v228, v232, v140, vcc
	v_cndmask_b32_e32 v229, v233, v141, vcc
	v_cndmask_b32_e32 v230, v234, v142, vcc
	v_cndmask_b32_e32 v231, v235, v143, vcc
	v_cndmask_b32_e32 v236, v240, v132, vcc
	v_cndmask_b32_e32 v237, v241, v133, vcc
	v_cndmask_b32_e32 v238, v242, v134, vcc
	v_cndmask_b32_e32 v239, v243, v135, vcc
	v_cndmask_b32_e32 v140, v140, v232, vcc
	v_cndmask_b32_e32 v141, v141, v233, vcc
	v_cndmask_b32_e32 v142, v142, v234, vcc
	v_cndmask_b32_e32 v143, v143, v235, vcc
	v_cndmask_b32_e32 v132, v132, v240, vcc
	v_cndmask_b32_e32 v133, v133, v241, vcc
	v_cndmask_b32_e32 v134, v134, v242, vcc
	v_cndmask_b32_e32 v135, v135, v243, vcc
	global_store_dwordx4 v205, v[228:231], s[92:93]
	global_store_dwordx4 v205, v[236:239], s[92:93] offset:512
	global_store_dwordx4 v214, v[140:143], s[92:93]
	global_store_dwordx4 v214, v[132:135], s[92:93] offset:512
	v_add_u32_e32 v207, 0x10000, v207
	global_load_dwordx4 v[232:235], v206, s[82:83] offset:64
	global_load_dwordx4 v[240:243], v206, s[82:83] offset:576
	global_load_dwordx4 v[228:231], v206, s[82:83]
	global_load_dwordx4 v[236:239], v206, s[82:83] offset:512
	s_waitcnt lgkmcnt(0)
	v_add_f32_e32 v211, v210, v211
	ds_bpermute_b32 v212, v202, v211
	v_add_u32_e32 v208, 0x8000, v208
	s_waitcnt lgkmcnt(0)
	v_add_f32_e32 v211, v211, v212
	s_mov_b64 exec, 0xffff
	global_store_dword v209, v211, s[90:91]
	s_mov_b64 exec, -1
	v_add_u32_e32 v209, 0x400, v209
	s_waitcnt vmcnt(11)
; DI u32x4 pack8(const float* v) { u32x4 w; w.x = pk2(v[0], v[1]); w.y = pk2(v[2], v[3]); w.z = pk2(v[4], v[5]); w.w = pk2(v[6], v[7]); return w; }
; #define xor16_32(s) xor16_32_l((s), fr + 16 * fq)
;     DI void operator()(AccRef acc, const Unit& u, int wr, int wc, int fr, int fq) const {
;     ...
;             for (int m = 0; m < 4; ++m) {
;                 const int row = rb + 16 * m;
;                 const float* xi = row < MP ? xin_p + (size_t)row * 1024 : xin_s + (size_t)(row - MP) * 1024;
;                 float s = 0.f;
; #pragma unroll
;                 for (int bj = 0; bj < 2; ++bj) {
;                     const int c = u.pn * 256 + bj * 128 + cl;
;                     float v[8];
; #pragma unroll
;                     for (int n = 0; n < 2; ++n) {
;                         const f32x4 x = *(const f32x4*)(xi + c + 4 * n);
;                         const f32x4 y = x + gt[bj][n] * acc[ai][bj][m][n];
;                         *(f32x4*)(xout + (size_t)row * 1024 + c + 4 * n) = y;
; #pragma unroll
;                         for (int j = 0; j < 4; ++j) { s += y[j] * y[j]; v[4 * n + j] = ap ? y[j] * gs[bj][n][j] : 0.f; }
;                     }
;                     if (ap) *(u32x4*)(ap + (size_t)row * 1024 + c) = pack8(v);
;                 }
;                 s = xor16_32(s);
;                 if (fq == 0) ssq[(size_t)row * 16 + u.pn * 4 + wc] = s;
	v_permlane32_swap_b32_e32 v244, v248
	v_permlane32_swap_b32_e32 v245, v249
	v_permlane32_swap_b32_e32 v246, v250
	v_permlane32_swap_b32_e32 v247, v251
	v_permlane32_swap_b32_e32 v216, v220
	v_permlane32_swap_b32_e32 v217, v221
	v_permlane32_swap_b32_e32 v218, v222
	v_permlane32_swap_b32_e32 v219, v223
	v_permlane16_swap_b32_e32 v244, v248
	v_permlane16_swap_b32_e32 v245, v249
	v_permlane16_swap_b32_e32 v246, v250
	v_permlane16_swap_b32_e32 v247, v251
	v_permlane16_swap_b32_e32 v216, v220
	v_permlane16_swap_b32_e32 v217, v221
	v_permlane16_swap_b32_e32 v218, v222
	v_permlane16_swap_b32_e32 v219, v223
	v_pk_fma_f32 v[124:125], v[124:125], v[116:117], v[244:245]
	v_pk_fma_f32 v[126:127], v[126:127], v[118:119], v[246:247]
	v_mul_f32_e32 v210, v125, v125
	v_fmac_f32_e32 v210, v124, v124
	v_fmac_f32_e32 v210, v126, v126
	v_fmac_f32_e32 v210, v127, v127
	v_pk_mul_f32 v[244:245], v[164:165], v[124:125]
	v_pk_mul_f32 v[246:247], v[166:167], v[126:127]
	v_pk_fma_f32 v[120:121], v[120:121], v[108:109], v[248:249]
	v_pk_fma_f32 v[122:123], v[122:123], v[110:111], v[250:251]
	v_fmac_f32_e32 v210, v120, v120
	v_fmac_f32_e32 v210, v121, v121
	v_fmac_f32_e32 v210, v122, v122
	v_fmac_f32_e32 v210, v123, v123
	v_pk_mul_f32 v[248:249], v[162:163], v[120:121]
	v_pk_mul_f32 v[250:251], v[160:161], v[122:123]
	v_cvt_pk_bf16_f32 v244, v244, v245
	v_cvt_pk_bf16_f32 v245, v246, v247
	v_cvt_pk_bf16_f32 v246, v248, v249
	v_cvt_pk_bf16_f32 v247, v250, v251
	global_store_dwordx4 v208, v[244:247], s[64:65]
	v_pk_fma_f32 v[112:113], v[112:113], v[104:105], v[216:217]
	v_pk_fma_f32 v[114:115], v[114:115], v[106:107], v[218:219]
	v_fmac_f32_e32 v210, v112, v112
	v_fmac_f32_e32 v210, v113, v113
	v_fmac_f32_e32 v210, v114, v114
	v_fmac_f32_e32 v210, v115, v115
	v_pk_mul_f32 v[216:217], v[150:151], v[112:113]
	v_pk_mul_f32 v[218:219], v[148:149], v[114:115]
	v_pk_fma_f32 v[96:97], v[96:97], v[100:101], v[220:221]
	v_pk_fma_f32 v[98:99], v[98:99], v[102:103], v[222:223]
	v_fmac_f32_e32 v210, v96, v96
	v_fmac_f32_e32 v210, v97, v97
	v_fmac_f32_e32 v210, v98, v98
	v_fmac_f32_e32 v210, v99, v99
	v_pk_mul_f32 v[220:221], v[144:145], v[96:97]
	v_pk_mul_f32 v[222:223], v[146:147], v[98:99]
	v_cvt_pk_bf16_f32 v216, v216, v217
	v_cvt_pk_bf16_f32 v217, v218, v219
	v_cvt_pk_bf16_f32 v218, v220, v221
	v_cvt_pk_bf16_f32 v219, v222, v223
	global_store_dwordx4 v208, v[216:219], s[64:65] offset:256
	ds_bpermute_b32 v211, v203, v210
	v_permlane16_swap_b32_e32 v124, v120
	v_permlane16_swap_b32_e32 v125, v121
	v_permlane16_swap_b32_e32 v126, v122
	v_permlane16_swap_b32_e32 v127, v123
	v_permlane16_swap_b32_e32 v112, v96
	v_permlane16_swap_b32_e32 v113, v97
	v_permlane16_swap_b32_e32 v114, v98
	v_permlane16_swap_b32_e32 v115, v99
	v_permlane32_swap_b32_e32 v124, v120
	v_permlane32_swap_b32_e32 v125, v121
	v_permlane32_swap_b32_e32 v126, v122
	v_permlane32_swap_b32_e32 v127, v123
	v_permlane32_swap_b32_e32 v112, v96
	v_permlane32_swap_b32_e32 v113, v97
	v_permlane32_swap_b32_e32 v114, v98
	v_permlane32_swap_b32_e32 v115, v99
	s_nop 1
	v_mov_b32_dpp v248, v120 row_ror:8 row_mask:0xf bank_mask:0xf
	v_mov_b32_dpp v249, v121 row_ror:8 row_mask:0xf bank_mask:0xf
	v_mov_b32_dpp v250, v122 row_ror:8 row_mask:0xf bank_mask:0xf
	v_mov_b32_dpp v251, v123 row_ror:8 row_mask:0xf bank_mask:0xf
	v_mov_b32_dpp v220, v96 row_ror:8 row_mask:0xf bank_mask:0xf
	v_mov_b32_dpp v221, v97 row_ror:8 row_mask:0xf bank_mask:0xf
	v_mov_b32_dpp v222, v98 row_ror:8 row_mask:0xf bank_mask:0xf
	v_mov_b32_dpp v223, v99 row_ror:8 row_mask:0xf bank_mask:0xf
	s_mov_b32 vcc_lo, 0xff00ff
	s_mov_b32 vcc_hi, 0xff00ff
	v_mov_b32_e32 v205, 0xffff8040
	v_mov_b32_e32 v214, 0x8040
	v_cndmask_b32_e64 v205, v205, 0, vcc
	v_cndmask_b32_e64 v214, 0, v214, vcc
	v_add_u32_e32 v205, v205, v207
	v_add_u32_e32 v214, v214, v207
	v_cndmask_b32_e32 v244, v248, v124, vcc
	v_cndmask_b32_e32 v245, v249, v125, vcc
	v_cndmask_b32_e32 v246, v250, v126, vcc
	v_cndmask_b32_e32 v247, v251, v127, vcc
	v_cndmask_b32_e32 v216, v220, v112, vcc
	v_cndmask_b32_e32 v217, v221, v113, vcc
	v_cndmask_b32_e32 v218, v222, v114, vcc
	v_cndmask_b32_e32 v219, v223, v115, vcc
	v_cndmask_b32_e32 v124, v124, v248, vcc
	v_cndmask_b32_e32 v125, v125, v249, vcc
	v_cndmask_b32_e32 v126, v126, v250, vcc
	v_cndmask_b32_e32 v127, v127, v251, vcc
	v_cndmask_b32_e32 v112, v112, v220, vcc
	v_cndmask_b32_e32 v113, v113, v221, vcc
	v_cndmask_b32_e32 v114, v114, v222, vcc
	v_cndmask_b32_e32 v115, v115, v223, vcc
	global_store_dwordx4 v205, v[244:247], s[92:93]
	global_store_dwordx4 v205, v[216:219], s[92:93] offset:512
	global_store_dwordx4 v214, v[124:127], s[92:93]
	global_store_dwordx4 v214, v[112:115], s[92:93] offset:512
	v_add_u32_e32 v207, 0x10000, v207
	v_add_u32_e32 v206, 0x10000, v206
	global_load_dwordx4 v[248:251], v206, s[82:83] offset:64
	global_load_dwordx4 v[220:223], v206, s[82:83] offset:576
	global_load_dwordx4 v[244:247], v206, s[82:83]
	global_load_dwordx4 v[216:219], v206, s[82:83] offset:512
	s_waitcnt lgkmcnt(0)
	v_add_f32_e32 v211, v210, v211
	ds_bpermute_b32 v212, v202, v211
	v_add_u32_e32 v208, 0x8000, v208
	s_waitcnt lgkmcnt(0)
	v_add_f32_e32 v211, v211, v212
	s_mov_b64 exec, 0xffff
	global_store_dword v209, v211, s[90:91]
	s_mov_b64 exec, -1
	v_add_u32_e32 v209, 0x400, v209
	s_waitcnt vmcnt(12)
; DI u32x4 pack8(const float* v) { u32x4 w; w.x = pk2(v[0], v[1]); w.y = pk2(v[2], v[3]); w.z = pk2(v[4], v[5]); w.w = pk2(v[6], v[7]); return w; }
; #define xor16_32(s) xor16_32_l((s), fr + 16 * fq)
;     DI void operator()(AccRef acc, const Unit& u, int wr, int wc, int fr, int fq) const {
;     ...
;             for (int m = 0; m < 4; ++m) {
;                 const int row = rb + 16 * m;
;                 const float* xi = row < MP ? xin_p + (size_t)row * 1024 : xin_s + (size_t)(row - MP) * 1024;
;                 float s = 0.f;
; #pragma unroll
;                 for (int bj = 0; bj < 2; ++bj) {
;                     const int c = u.pn * 256 + bj * 128 + cl;
;                     float v[8];
; #pragma unroll
;                     for (int n = 0; n < 2; ++n) {
;                         const f32x4 x = *(const f32x4*)(xi + c + 4 * n);
;                         const f32x4 y = x + gt[bj][n] * acc[ai][bj][m][n];
;                         *(f32x4*)(xout + (size_t)row * 1024 + c + 4 * n) = y;
; #pragma unroll
;                         for (int j = 0; j < 4; ++j) { s += y[j] * y[j]; v[4 * n + j] = ap ? y[j] * gs[bj][n][j] : 0.f; }
;                     }
;                     if (ap) *(u32x4*)(ap + (size_t)row * 1024 + c) = pack8(v);
;                 }
;                 s = xor16_32(s);
;                 if (fq == 0) ssq[(size_t)row * 16 + u.pn * 4 + wc] = s;
	v_permlane32_swap_b32_e32 v228, v232
	v_permlane32_swap_b32_e32 v229, v233
	v_permlane32_swap_b32_e32 v230, v234
	v_permlane32_swap_b32_e32 v231, v235
	v_permlane32_swap_b32_e32 v236, v240
	v_permlane32_swap_b32_e32 v237, v241
	v_permlane32_swap_b32_e32 v238, v242
	v_permlane32_swap_b32_e32 v239, v243
	v_permlane16_swap_b32_e32 v228, v232
	v_permlane16_swap_b32_e32 v229, v233
	v_permlane16_swap_b32_e32 v230, v234
	v_permlane16_swap_b32_e32 v231, v235
	v_permlane16_swap_b32_e32 v236, v240
	v_permlane16_swap_b32_e32 v237, v241
	v_permlane16_swap_b32_e32 v238, v242
	v_permlane16_swap_b32_e32 v239, v243
	v_pk_fma_f32 v[92:93], v[92:93], v[116:117], v[228:229]
	v_pk_fma_f32 v[94:95], v[94:95], v[118:119], v[230:231]
	v_mul_f32_e32 v210, v93, v93
	v_fmac_f32_e32 v210, v92, v92
	v_fmac_f32_e32 v210, v94, v94
	v_fmac_f32_e32 v210, v95, v95
	v_pk_mul_f32 v[228:229], v[164:165], v[92:93]
	v_pk_mul_f32 v[230:231], v[166:167], v[94:95]
	v_pk_fma_f32 v[88:89], v[88:89], v[108:109], v[232:233]
	v_pk_fma_f32 v[90:91], v[90:91], v[110:111], v[234:235]
	v_fmac_f32_e32 v210, v88, v88
	v_fmac_f32_e32 v210, v89, v89
	v_fmac_f32_e32 v210, v90, v90
	v_fmac_f32_e32 v210, v91, v91
	v_pk_mul_f32 v[232:233], v[162:163], v[88:89]
	v_pk_mul_f32 v[234:235], v[160:161], v[90:91]
	v_cvt_pk_bf16_f32 v228, v228, v229
	v_cvt_pk_bf16_f32 v229, v230, v231
	v_cvt_pk_bf16_f32 v230, v232, v233
	v_cvt_pk_bf16_f32 v231, v234, v235
	global_store_dwordx4 v208, v[228:231], s[64:65]
	v_pk_fma_f32 v[84:85], v[84:85], v[104:105], v[236:237]
	v_pk_fma_f32 v[86:87], v[86:87], v[106:107], v[238:239]
	v_fmac_f32_e32 v210, v84, v84
	v_fmac_f32_e32 v210, v85, v85
	v_fmac_f32_e32 v210, v86, v86
	v_fmac_f32_e32 v210, v87, v87
	v_pk_mul_f32 v[236:237], v[150:151], v[84:85]
	v_pk_mul_f32 v[238:239], v[148:149], v[86:87]
	v_pk_fma_f32 v[80:81], v[80:81], v[100:101], v[240:241]
	v_pk_fma_f32 v[82:83], v[82:83], v[102:103], v[242:243]
	v_fmac_f32_e32 v210, v80, v80
	v_fmac_f32_e32 v210, v81, v81
	v_fmac_f32_e32 v210, v82, v82
	v_fmac_f32_e32 v210, v83, v83
	v_pk_mul_f32 v[240:241], v[144:145], v[80:81]
	v_pk_mul_f32 v[242:243], v[146:147], v[82:83]
	v_cvt_pk_bf16_f32 v236, v236, v237
	v_cvt_pk_bf16_f32 v237, v238, v239
	v_cvt_pk_bf16_f32 v238, v240, v241
	v_cvt_pk_bf16_f32 v239, v242, v243
	global_store_dwordx4 v208, v[236:239], s[64:65] offset:256
	ds_bpermute_b32 v211, v203, v210
	v_permlane16_swap_b32_e32 v92, v88
	v_permlane16_swap_b32_e32 v93, v89
	v_permlane16_swap_b32_e32 v94, v90
	v_permlane16_swap_b32_e32 v95, v91
	v_permlane16_swap_b32_e32 v84, v80
	v_permlane16_swap_b32_e32 v85, v81
	v_permlane16_swap_b32_e32 v86, v82
	v_permlane16_swap_b32_e32 v87, v83
	v_permlane32_swap_b32_e32 v92, v88
	v_permlane32_swap_b32_e32 v93, v89
	v_permlane32_swap_b32_e32 v94, v90
	v_permlane32_swap_b32_e32 v95, v91
	v_permlane32_swap_b32_e32 v84, v80
	v_permlane32_swap_b32_e32 v85, v81
	v_permlane32_swap_b32_e32 v86, v82
	v_permlane32_swap_b32_e32 v87, v83
	s_nop 1
	v_mov_b32_dpp v232, v88 row_ror:8 row_mask:0xf bank_mask:0xf
	v_mov_b32_dpp v233, v89 row_ror:8 row_mask:0xf bank_mask:0xf
	v_mov_b32_dpp v234, v90 row_ror:8 row_mask:0xf bank_mask:0xf
	v_mov_b32_dpp v235, v91 row_ror:8 row_mask:0xf bank_mask:0xf
	v_mov_b32_dpp v240, v80 row_ror:8 row_mask:0xf bank_mask:0xf
	v_mov_b32_dpp v241, v81 row_ror:8 row_mask:0xf bank_mask:0xf
	v_mov_b32_dpp v242, v82 row_ror:8 row_mask:0xf bank_mask:0xf
	v_mov_b32_dpp v243, v83 row_ror:8 row_mask:0xf bank_mask:0xf
	s_mov_b32 vcc_lo, 0xff00ff
	s_mov_b32 vcc_hi, 0xff00ff
	v_mov_b32_e32 v205, 0xffff8040
	v_mov_b32_e32 v214, 0x8040
	v_cndmask_b32_e64 v205, v205, 0, vcc
	v_cndmask_b32_e64 v214, 0, v214, vcc
	v_add_u32_e32 v205, v205, v207
	v_add_u32_e32 v214, v214, v207
	v_cndmask_b32_e32 v228, v232, v92, vcc
	v_cndmask_b32_e32 v229, v233, v93, vcc
	v_cndmask_b32_e32 v230, v234, v94, vcc
	v_cndmask_b32_e32 v231, v235, v95, vcc
	v_cndmask_b32_e32 v236, v240, v84, vcc
	v_cndmask_b32_e32 v237, v241, v85, vcc
	v_cndmask_b32_e32 v238, v242, v86, vcc
	v_cndmask_b32_e32 v239, v243, v87, vcc
	v_cndmask_b32_e32 v92, v92, v232, vcc
	v_cndmask_b32_e32 v93, v93, v233, vcc
	v_cndmask_b32_e32 v94, v94, v234, vcc
	v_cndmask_b32_e32 v95, v95, v235, vcc
	v_cndmask_b32_e32 v84, v84, v240, vcc
	v_cndmask_b32_e32 v85, v85, v241, vcc
	v_cndmask_b32_e32 v86, v86, v242, vcc
	v_cndmask_b32_e32 v87, v87, v243, vcc
	global_store_dwordx4 v205, v[228:231], s[92:93]
	global_store_dwordx4 v205, v[236:239], s[92:93] offset:512
	global_store_dwordx4 v214, v[92:95], s[92:93]
	global_store_dwordx4 v214, v[84:87], s[92:93] offset:512
	v_add_u32_e32 v207, 0x10000, v207
	v_add_u32_e32 v206, 0x50000, v206
	global_load_dwordx4 v[232:235], v206, s[82:83] offset:64
	global_load_dwordx4 v[240:243], v206, s[82:83] offset:576
	global_load_dwordx4 v[228:231], v206, s[82:83]
	global_load_dwordx4 v[236:239], v206, s[82:83] offset:512
	s_waitcnt lgkmcnt(0)
	v_add_f32_e32 v211, v210, v211
	ds_bpermute_b32 v212, v202, v211
	v_add_u32_e32 v208, 0x8000, v208
	s_waitcnt lgkmcnt(0)
	v_add_f32_e32 v211, v211, v212
	s_mov_b64 exec, 0xffff
	global_store_dword v209, v211, s[90:91]
	s_mov_b64 exec, -1
	v_add_u32_e32 v209, 0x400, v209
	s_waitcnt vmcnt(12)
; DI u32x4 pack8(const float* v) { u32x4 w; w.x = pk2(v[0], v[1]); w.y = pk2(v[2], v[3]); w.z = pk2(v[4], v[5]); w.w = pk2(v[6], v[7]); return w; }
; #define xor16_32(s) xor16_32_l((s), fr + 16 * fq)
;     DI void operator()(AccRef acc, const Unit& u, int wr, int wc, int fr, int fq) const {
;     ...
;             for (int m = 0; m < 4; ++m) {
;                 const int row = rb + 16 * m;
;                 const float* xi = row < MP ? xin_p + (size_t)row * 1024 : xin_s + (size_t)(row - MP) * 1024;
;                 float s = 0.f;
; #pragma unroll
;                 for (int bj = 0; bj < 2; ++bj) {
;                     const int c = u.pn * 256 + bj * 128 + cl;
;                     float v[8];
; #pragma unroll
;                     for (int n = 0; n < 2; ++n) {
;                         const f32x4 x = *(const f32x4*)(xi + c + 4 * n);
;                         const f32x4 y = x + gt[bj][n] * acc[ai][bj][m][n];
;                         *(f32x4*)(xout + (size_t)row * 1024 + c + 4 * n) = y;
; #pragma unroll
;                         for (int j = 0; j < 4; ++j) { s += y[j] * y[j]; v[4 * n + j] = ap ? y[j] * gs[bj][n][j] : 0.f; }
;                     }
;                     if (ap) *(u32x4*)(ap + (size_t)row * 1024 + c) = pack8(v);
;                 }
;                 s = xor16_32(s);
;                 if (fq == 0) ssq[(size_t)row * 16 + u.pn * 4 + wc] = s;
	v_permlane32_swap_b32_e32 v244, v248
	v_permlane32_swap_b32_e32 v245, v249
	v_permlane32_swap_b32_e32 v246, v250
	v_permlane32_swap_b32_e32 v247, v251
	v_permlane32_swap_b32_e32 v216, v220
	v_permlane32_swap_b32_e32 v217, v221
	v_permlane32_swap_b32_e32 v218, v222
	v_permlane32_swap_b32_e32 v219, v223
	v_permlane16_swap_b32_e32 v244, v248
	v_permlane16_swap_b32_e32 v245, v249
	v_permlane16_swap_b32_e32 v246, v250
	v_permlane16_swap_b32_e32 v247, v251
	v_permlane16_swap_b32_e32 v216, v220
	v_permlane16_swap_b32_e32 v217, v221
	v_permlane16_swap_b32_e32 v218, v222
	v_permlane16_swap_b32_e32 v219, v223
	v_pk_fma_f32 v[76:77], v[76:77], v[116:117], v[244:245]
	v_pk_fma_f32 v[78:79], v[78:79], v[118:119], v[246:247]
	v_mul_f32_e32 v210, v77, v77
	v_fmac_f32_e32 v210, v76, v76
	v_fmac_f32_e32 v210, v78, v78
	v_fmac_f32_e32 v210, v79, v79
	v_pk_mul_f32 v[244:245], v[164:165], v[76:77]
	v_pk_mul_f32 v[246:247], v[166:167], v[78:79]
	v_pk_fma_f32 v[72:73], v[72:73], v[108:109], v[248:249]
	v_pk_fma_f32 v[74:75], v[74:75], v[110:111], v[250:251]
	v_fmac_f32_e32 v210, v72, v72
	v_fmac_f32_e32 v210, v73, v73
	v_fmac_f32_e32 v210, v74, v74
	v_fmac_f32_e32 v210, v75, v75
	v_pk_mul_f32 v[248:249], v[162:163], v[72:73]
	v_pk_mul_f32 v[250:251], v[160:161], v[74:75]
	v_cvt_pk_bf16_f32 v244, v244, v245
	v_cvt_pk_bf16_f32 v245, v246, v247
	v_cvt_pk_bf16_f32 v246, v248, v249
	v_cvt_pk_bf16_f32 v247, v250, v251
	global_store_dwordx4 v208, v[244:247], s[64:65]
	v_pk_fma_f32 v[68:69], v[68:69], v[104:105], v[216:217]
	v_pk_fma_f32 v[70:71], v[70:71], v[106:107], v[218:219]
	v_fmac_f32_e32 v210, v68, v68
	v_fmac_f32_e32 v210, v69, v69
	v_fmac_f32_e32 v210, v70, v70
	v_fmac_f32_e32 v210, v71, v71
	v_pk_mul_f32 v[216:217], v[150:151], v[68:69]
	v_pk_mul_f32 v[218:219], v[148:149], v[70:71]
	v_pk_fma_f32 v[64:65], v[64:65], v[100:101], v[220:221]
	v_pk_fma_f32 v[66:67], v[66:67], v[102:103], v[222:223]
	v_fmac_f32_e32 v210, v64, v64
	v_fmac_f32_e32 v210, v65, v65
	v_fmac_f32_e32 v210, v66, v66
	v_fmac_f32_e32 v210, v67, v67
	v_pk_mul_f32 v[220:221], v[144:145], v[64:65]
	v_pk_mul_f32 v[222:223], v[146:147], v[66:67]
	v_cvt_pk_bf16_f32 v216, v216, v217
	v_cvt_pk_bf16_f32 v217, v218, v219
	v_cvt_pk_bf16_f32 v218, v220, v221
	v_cvt_pk_bf16_f32 v219, v222, v223
	global_store_dwordx4 v208, v[216:219], s[64:65] offset:256
	ds_bpermute_b32 v211, v203, v210
	v_permlane16_swap_b32_e32 v76, v72
	v_permlane16_swap_b32_e32 v77, v73
	v_permlane16_swap_b32_e32 v78, v74
	v_permlane16_swap_b32_e32 v79, v75
	v_permlane16_swap_b32_e32 v68, v64
	v_permlane16_swap_b32_e32 v69, v65
	v_permlane16_swap_b32_e32 v70, v66
	v_permlane16_swap_b32_e32 v71, v67
	v_permlane32_swap_b32_e32 v76, v72
	v_permlane32_swap_b32_e32 v77, v73
	v_permlane32_swap_b32_e32 v78, v74
	v_permlane32_swap_b32_e32 v79, v75
	v_permlane32_swap_b32_e32 v68, v64
	v_permlane32_swap_b32_e32 v69, v65
	v_permlane32_swap_b32_e32 v70, v66
	v_permlane32_swap_b32_e32 v71, v67
	s_nop 1
	v_mov_b32_dpp v248, v72 row_ror:8 row_mask:0xf bank_mask:0xf
	v_mov_b32_dpp v249, v73 row_ror:8 row_mask:0xf bank_mask:0xf
	v_mov_b32_dpp v250, v74 row_ror:8 row_mask:0xf bank_mask:0xf
	v_mov_b32_dpp v251, v75 row_ror:8 row_mask:0xf bank_mask:0xf
	v_mov_b32_dpp v220, v64 row_ror:8 row_mask:0xf bank_mask:0xf
	v_mov_b32_dpp v221, v65 row_ror:8 row_mask:0xf bank_mask:0xf
	v_mov_b32_dpp v222, v66 row_ror:8 row_mask:0xf bank_mask:0xf
	v_mov_b32_dpp v223, v67 row_ror:8 row_mask:0xf bank_mask:0xf
	s_mov_b32 vcc_lo, 0xff00ff
	s_mov_b32 vcc_hi, 0xff00ff
	v_mov_b32_e32 v205, 0xffff8040
	v_mov_b32_e32 v214, 0x8040
	v_cndmask_b32_e64 v205, v205, 0, vcc
	v_cndmask_b32_e64 v214, 0, v214, vcc
	v_add_u32_e32 v205, v205, v207
	v_add_u32_e32 v214, v214, v207
	v_cndmask_b32_e32 v244, v248, v76, vcc
	v_cndmask_b32_e32 v245, v249, v77, vcc
	v_cndmask_b32_e32 v246, v250, v78, vcc
	v_cndmask_b32_e32 v247, v251, v79, vcc
	v_cndmask_b32_e32 v216, v220, v68, vcc
	v_cndmask_b32_e32 v217, v221, v69, vcc
	v_cndmask_b32_e32 v218, v222, v70, vcc
	v_cndmask_b32_e32 v219, v223, v71, vcc
	v_cndmask_b32_e32 v76, v76, v248, vcc
	v_cndmask_b32_e32 v77, v77, v249, vcc
	v_cndmask_b32_e32 v78, v78, v250, vcc
	v_cndmask_b32_e32 v79, v79, v251, vcc
	v_cndmask_b32_e32 v68, v68, v220, vcc
	v_cndmask_b32_e32 v69, v69, v221, vcc
	v_cndmask_b32_e32 v70, v70, v222, vcc
	v_cndmask_b32_e32 v71, v71, v223, vcc
	global_store_dwordx4 v205, v[244:247], s[92:93]
	global_store_dwordx4 v205, v[216:219], s[92:93] offset:512
	global_store_dwordx4 v214, v[76:79], s[92:93]
	global_store_dwordx4 v214, v[68:71], s[92:93] offset:512
	v_add_u32_e32 v207, 0x50000, v207
	v_add_u32_e32 v206, 0x10000, v206
	global_load_dwordx4 v[248:251], v206, s[82:83] offset:64
	global_load_dwordx4 v[220:223], v206, s[82:83] offset:576
	global_load_dwordx4 v[244:247], v206, s[82:83]
	global_load_dwordx4 v[216:219], v206, s[82:83] offset:512
	s_waitcnt lgkmcnt(0)
	v_add_f32_e32 v211, v210, v211
	ds_bpermute_b32 v212, v202, v211
	v_add_u32_e32 v208, 0x28000, v208
	s_waitcnt lgkmcnt(0)
	v_add_f32_e32 v211, v211, v212
	s_mov_b64 exec, 0xffff
	global_store_dword v209, v211, s[90:91]
	s_mov_b64 exec, -1
	v_add_u32_e32 v209, 0x1400, v209
	v_add_u32_e32 v224, 0xffffc080, v192
	v_add_u32_e32 v112, 0x80, v192
	s_waitcnt lgkmcnt(0)
; DI u32x4 pack8(const float* v) { u32x4 w; w.x = pk2(v[0], v[1]); w.y = pk2(v[2], v[3]); w.z = pk2(v[4], v[5]); w.w = pk2(v[6], v[7]); return w; }
; #define xor16_32(s) xor16_32_l((s), fr + 16 * fq)
;     DI void operator()(AccRef acc, const Unit& u, int wr, int wc, int fr, int fq) const {
;     ...
;         for (int ai = 0; ai < 2; ++ai) {
;             const int rb = u.pm * 256 + ai * 128 + wr * 64 + fr;
;             int mb, pos0, kv0; row_info(rb, mb, pos0, kv0);
;             f32x4 gt[2][2], gs[2][2];
; #pragma unroll
;             for (int bj = 0; bj < 2; ++bj)
; #pragma unroll
;                 for (int n = 0; n < 2; ++n) {
;                     const int c = u.pn * 256 + bj * 128 + cl + 4 * n;
;                     gt[bj][n] = *(const f32x4*)(gate + (size_t)mb * 6144 + c);
;                     if (ap) { const f32x4 g = *(const f32x4*)(gn + c), s = *(const f32x4*)(scn + (size_t)mb * 6144 + c); gs[bj][n] = g * (s + 1.f); }
;                 }
; #pragma unroll
;             for (int m = 0; m < 4; ++m) {
;                 const int row = rb + 16 * m;
;                 const float* xi = row < MP ? xin_p + (size_t)row * 1024 : xin_s + (size_t)(row - MP) * 1024;
;                 float s = 0.f;
; #pragma unroll
;                 for (int bj = 0; bj < 2; ++bj) {
;                     const int c = u.pn * 256 + bj * 128 + cl;
;                     float v[8];
; #pragma unroll
;                     for (int n = 0; n < 2; ++n) {
;                         const f32x4 x = *(const f32x4*)(xi + c + 4 * n);
;                         const f32x4 y = x + gt[bj][n] * acc[ai][bj][m][n];
;                         *(f32x4*)(xout + (size_t)row * 1024 + c + 4 * n) = y;
; #pragma unroll
;                         for (int j = 0; j < 4; ++j) { s += y[j] * y[j]; v[4 * n + j] = ap ? y[j] * gs[bj][n][j] : 0.f; }
;                     }
;                     if (ap) *(u32x4*)(ap + (size_t)row * 1024 + c) = pack8(v);
;                 }
;                 s = xor16_32(s);
;                 if (fq == 0) ssq[(size_t)row * 16 + u.pn * 4 + wc] = s;
	v_lshrrev_b32_e32 v65, 6, v224
	v_ashrrev_i32_e32 v64, 11, v112
	v_add_u32_e32 v65, 8, v65
	v_cmp_gt_i32_e64 s[2:3], s94, v112
	v_mov_b64_e32 v[66:67], s[60:61]
	s_nop 0
	v_cndmask_b32_e64 v68, v65, v64, s[2:3]
	v_mov_b64_e32 v[64:65], s[8:9]
	v_mad_i64_i32 v[64:65], s[2:3], v68, s75, v[64:65]
	v_mad_i64_i32 v[66:67], s[2:3], v68, s75, v[66:67]
	v_lshl_add_u64 v[68:69], v[64:65], 0, v[190:191]
	v_lshl_add_u64 v[104:105], v[66:67], 0, v[190:191]
	global_load_dwordx4 v[72:75], v[68:69], off offset:16
	global_load_dwordx4 v[76:79], v[68:69], off
	global_load_dwordx4 v[84:87], v[194:195], off offset:16
	global_load_dwordx4 v[100:103], v[194:195], off
	global_load_dwordx4 v[96:99], v[104:105], off offset:16
	global_load_dwordx4 v[108:111], v[104:105], off
	global_load_dwordx4 v[64:67], v[68:69], off offset:528
	s_nop 0
	global_load_dwordx4 v[68:71], v[68:69], off offset:512
	s_nop 0
	global_load_dwordx4 v[80:83], v[194:195], off offset:528
	global_load_dwordx4 v[92:95], v[194:195], off offset:512
	global_load_dwordx4 v[88:91], v[104:105], off offset:528
	s_nop 0
	global_load_dwordx4 v[104:107], v[104:105], off offset:512
	s_movk_i32 s2, 0x3fff
	v_cmp_lt_i32_e64 s[2:3], s2, v112
	s_and_saveexec_b64 s[12:13], s[2:3]
	s_xor_b64 s[2:3], exec, s[12:13]
	v_lshlrev_b64 v[114:115], 12, v[224:225]
	v_mov_b32_e32 v113, v225
	v_lshl_add_u64 v[116:117], s[20:21], 0, v[114:115]
	v_lshlrev_b64 v[114:115], 12, v[112:113]
	s_andn2_saveexec_b64 s[2:3], s[2:3]
	v_ashrrev_i32_e32 v113, 31, v112
	v_lshlrev_b64 v[114:115], 12, v[112:113]
	v_lshl_add_u64 v[116:117], s[42:43], 0, v[114:115]
	s_or_b64 exec, exec, s[2:3]
	s_waitcnt vmcnt(6)
	v_pk_add_f32 v[108:109], v[108:109], 1.0 op_sel_hi:[1,0]
	s_waitcnt vmcnt(1)
	v_pk_add_f32 v[90:91], v[90:91], 1.0 op_sel_hi:[1,0]
	v_pk_mul_f32 v[100:101], v[100:101], v[108:109]
	v_pk_add_f32 v[108:109], v[96:97], 1.0 op_sel_hi:[1,0]
	v_pk_add_f32 v[96:97], v[98:99], 1.0 op_sel_hi:[1,0]
	v_pk_mul_f32 v[98:99], v[84:85], v[108:109]
	v_pk_mul_f32 v[96:97], v[86:87], v[96:97]
	s_waitcnt vmcnt(0)
	v_pk_add_f32 v[84:85], v[106:107], 1.0 op_sel_hi:[1,0]
	v_pk_add_f32 v[86:87], v[104:105], 1.0 op_sel_hi:[1,0]
	v_pk_mul_f32 v[82:83], v[82:83], v[90:91]
	v_lshl_add_u64 v[90:91], v[116:117], 0, v[190:191]
	v_pk_mul_f32 v[84:85], v[94:95], v[84:85]
	v_pk_mul_f32 v[86:87], v[92:93], v[86:87]
	v_pk_add_f32 v[110:111], v[110:111], 1.0 op_sel_hi:[1,0]
	v_pk_add_f32 v[88:89], v[88:89], 1.0 op_sel_hi:[1,0]
	v_pk_mul_f32 v[102:103], v[102:103], v[110:111]
	v_pk_mul_f32 v[80:81], v[80:81], v[88:89]
	v_lshlrev_b64 v[88:89], 11, v[112:113]
	v_lshl_add_u64 v[88:89], s[64:65], 0, v[88:89]
	v_permlane32_swap_b32_e32 v228, v232
	v_permlane32_swap_b32_e32 v229, v233
	v_permlane32_swap_b32_e32 v230, v234
	v_permlane32_swap_b32_e32 v231, v235
	v_permlane32_swap_b32_e32 v236, v240
	v_permlane32_swap_b32_e32 v237, v241
	v_permlane32_swap_b32_e32 v238, v242
	v_permlane32_swap_b32_e32 v239, v243
	v_permlane16_swap_b32_e32 v228, v232
	v_permlane16_swap_b32_e32 v229, v233
	v_permlane16_swap_b32_e32 v230, v234
	v_permlane16_swap_b32_e32 v231, v235
	v_permlane16_swap_b32_e32 v236, v240
	v_permlane16_swap_b32_e32 v237, v241
	v_permlane16_swap_b32_e32 v238, v242
	v_permlane16_swap_b32_e32 v239, v243
	v_pk_fma_f32 v[60:61], v[60:61], v[76:77], v[228:229]
	v_pk_fma_f32 v[62:63], v[62:63], v[78:79], v[230:231]
	v_mul_f32_e32 v210, v61, v61
	v_fmac_f32_e32 v210, v60, v60
	v_fmac_f32_e32 v210, v62, v62
	v_fmac_f32_e32 v210, v63, v63
	v_pk_mul_f32 v[228:229], v[100:101], v[60:61]
	v_pk_mul_f32 v[230:231], v[102:103], v[62:63]
	v_pk_fma_f32 v[56:57], v[56:57], v[72:73], v[232:233]
	v_pk_fma_f32 v[58:59], v[58:59], v[74:75], v[234:235]
	v_fmac_f32_e32 v210, v56, v56
	v_fmac_f32_e32 v210, v57, v57
	v_fmac_f32_e32 v210, v58, v58
	v_fmac_f32_e32 v210, v59, v59
	v_pk_mul_f32 v[232:233], v[98:99], v[56:57]
	v_pk_mul_f32 v[234:235], v[96:97], v[58:59]
	v_cvt_pk_bf16_f32 v228, v228, v229
	v_cvt_pk_bf16_f32 v229, v230, v231
	v_cvt_pk_bf16_f32 v230, v232, v233
	v_cvt_pk_bf16_f32 v231, v234, v235
	global_store_dwordx4 v208, v[228:231], s[64:65]
	v_pk_fma_f32 v[52:53], v[52:53], v[68:69], v[236:237]
	v_pk_fma_f32 v[54:55], v[54:55], v[70:71], v[238:239]
	v_fmac_f32_e32 v210, v52, v52
	v_fmac_f32_e32 v210, v53, v53
	v_fmac_f32_e32 v210, v54, v54
	v_fmac_f32_e32 v210, v55, v55
	v_pk_mul_f32 v[236:237], v[86:87], v[52:53]
	v_pk_mul_f32 v[238:239], v[84:85], v[54:55]
	v_pk_fma_f32 v[48:49], v[48:49], v[64:65], v[240:241]
	v_pk_fma_f32 v[50:51], v[50:51], v[66:67], v[242:243]
	v_fmac_f32_e32 v210, v48, v48
	v_fmac_f32_e32 v210, v49, v49
	v_fmac_f32_e32 v210, v50, v50
	v_fmac_f32_e32 v210, v51, v51
	v_pk_mul_f32 v[240:241], v[80:81], v[48:49]
	v_pk_mul_f32 v[242:243], v[82:83], v[50:51]
	v_cvt_pk_bf16_f32 v236, v236, v237
	v_cvt_pk_bf16_f32 v237, v238, v239
	v_cvt_pk_bf16_f32 v238, v240, v241
	v_cvt_pk_bf16_f32 v239, v242, v243
	global_store_dwordx4 v208, v[236:239], s[64:65] offset:256
	ds_bpermute_b32 v211, v203, v210
	v_permlane16_swap_b32_e32 v60, v56
	v_permlane16_swap_b32_e32 v61, v57
	v_permlane16_swap_b32_e32 v62, v58
	v_permlane16_swap_b32_e32 v63, v59
	v_permlane16_swap_b32_e32 v52, v48
	v_permlane16_swap_b32_e32 v53, v49
	v_permlane16_swap_b32_e32 v54, v50
	v_permlane16_swap_b32_e32 v55, v51
	v_permlane32_swap_b32_e32 v60, v56
	v_permlane32_swap_b32_e32 v61, v57
	v_permlane32_swap_b32_e32 v62, v58
	v_permlane32_swap_b32_e32 v63, v59
	v_permlane32_swap_b32_e32 v52, v48
	v_permlane32_swap_b32_e32 v53, v49
	v_permlane32_swap_b32_e32 v54, v50
	v_permlane32_swap_b32_e32 v55, v51
	s_nop 1
	v_mov_b32_dpp v232, v56 row_ror:8 row_mask:0xf bank_mask:0xf
; DI u32x4 pack8(const float* v) { u32x4 w; w.x = pk2(v[0], v[1]); w.y = pk2(v[2], v[3]); w.z = pk2(v[4], v[5]); w.w = pk2(v[6], v[7]); return w; }
; #define xor16_32(s) xor16_32_l((s), fr + 16 * fq)
;     DI void operator()(AccRef acc, const Unit& u, int wr, int wc, int fr, int fq) const {
;     ...
;             for (int m = 0; m < 4; ++m) {
;                 const int row = rb + 16 * m;
;                 const float* xi = row < MP ? xin_p + (size_t)row * 1024 : xin_s + (size_t)(row - MP) * 1024;
;                 float s = 0.f;
; #pragma unroll
;                 for (int bj = 0; bj < 2; ++bj) {
;                     const int c = u.pn * 256 + bj * 128 + cl;
;                     float v[8];
; #pragma unroll
;                     for (int n = 0; n < 2; ++n) {
;                         const f32x4 x = *(const f32x4*)(xi + c + 4 * n);
;                         const f32x4 y = x + gt[bj][n] * acc[ai][bj][m][n];
;                         *(f32x4*)(xout + (size_t)row * 1024 + c + 4 * n) = y;
; #pragma unroll
;                         for (int j = 0; j < 4; ++j) { s += y[j] * y[j]; v[4 * n + j] = ap ? y[j] * gs[bj][n][j] : 0.f; }
;                     }
;                     if (ap) *(u32x4*)(ap + (size_t)row * 1024 + c) = pack8(v);
;                 }
;                 s = xor16_32(s);
;                 if (fq == 0) ssq[(size_t)row * 16 + u.pn * 4 + wc] = s;
	v_mov_b32_dpp v233, v57 row_ror:8 row_mask:0xf bank_mask:0xf
	v_mov_b32_dpp v234, v58 row_ror:8 row_mask:0xf bank_mask:0xf
	v_mov_b32_dpp v235, v59 row_ror:8 row_mask:0xf bank_mask:0xf
	v_mov_b32_dpp v240, v48 row_ror:8 row_mask:0xf bank_mask:0xf
	v_mov_b32_dpp v241, v49 row_ror:8 row_mask:0xf bank_mask:0xf
	v_mov_b32_dpp v242, v50 row_ror:8 row_mask:0xf bank_mask:0xf
	v_mov_b32_dpp v243, v51 row_ror:8 row_mask:0xf bank_mask:0xf
	s_mov_b32 vcc_lo, 0xff00ff
	s_mov_b32 vcc_hi, 0xff00ff
	v_mov_b32_e32 v205, 0xffff8040
	v_mov_b32_e32 v214, 0x8040
	v_cndmask_b32_e64 v205, v205, 0, vcc
	v_cndmask_b32_e64 v214, 0, v214, vcc
	v_add_u32_e32 v205, v205, v207
	v_add_u32_e32 v214, v214, v207
	v_cndmask_b32_e32 v228, v232, v60, vcc
	v_cndmask_b32_e32 v229, v233, v61, vcc
	v_cndmask_b32_e32 v230, v234, v62, vcc
	v_cndmask_b32_e32 v231, v235, v63, vcc
	v_cndmask_b32_e32 v236, v240, v52, vcc
	v_cndmask_b32_e32 v237, v241, v53, vcc
	v_cndmask_b32_e32 v238, v242, v54, vcc
	v_cndmask_b32_e32 v239, v243, v55, vcc
	v_cndmask_b32_e32 v60, v60, v232, vcc
	v_cndmask_b32_e32 v61, v61, v233, vcc
	v_cndmask_b32_e32 v62, v62, v234, vcc
	v_cndmask_b32_e32 v63, v63, v235, vcc
	v_cndmask_b32_e32 v52, v52, v240, vcc
	v_cndmask_b32_e32 v53, v53, v241, vcc
	v_cndmask_b32_e32 v54, v54, v242, vcc
	v_cndmask_b32_e32 v55, v55, v243, vcc
	global_store_dwordx4 v205, v[228:231], s[92:93]
	global_store_dwordx4 v205, v[236:239], s[92:93] offset:512
	global_store_dwordx4 v214, v[60:63], s[92:93]
	global_store_dwordx4 v214, v[52:55], s[92:93] offset:512
	v_add_u32_e32 v207, 0x10000, v207
	v_add_u32_e32 v206, 0x10000, v206
	global_load_dwordx4 v[232:235], v206, s[82:83] offset:64
	global_load_dwordx4 v[240:243], v206, s[82:83] offset:576
	global_load_dwordx4 v[228:231], v206, s[82:83]
	global_load_dwordx4 v[236:239], v206, s[82:83] offset:512
	s_waitcnt lgkmcnt(0)
	v_add_f32_e32 v211, v210, v211
	ds_bpermute_b32 v212, v202, v211
	v_add_u32_e32 v208, 0x8000, v208
	s_waitcnt lgkmcnt(0)
	v_add_f32_e32 v211, v211, v212
	s_mov_b64 exec, 0xffff
	global_store_dword v209, v211, s[90:91]
	s_mov_b64 exec, -1
	v_add_u32_e32 v209, 0x400, v209
	v_permlane32_swap_b32_e32 v244, v248
	v_permlane32_swap_b32_e32 v245, v249
	v_permlane32_swap_b32_e32 v246, v250
	v_permlane32_swap_b32_e32 v247, v251
	v_permlane32_swap_b32_e32 v216, v220
	v_permlane32_swap_b32_e32 v217, v221
	v_permlane32_swap_b32_e32 v218, v222
	v_permlane32_swap_b32_e32 v219, v223
	v_permlane16_swap_b32_e32 v244, v248
	v_permlane16_swap_b32_e32 v245, v249
	v_permlane16_swap_b32_e32 v246, v250
	v_permlane16_swap_b32_e32 v247, v251
	v_permlane16_swap_b32_e32 v216, v220
	v_permlane16_swap_b32_e32 v217, v221
	v_permlane16_swap_b32_e32 v218, v222
	v_permlane16_swap_b32_e32 v219, v223
	v_pk_fma_f32 v[44:45], v[44:45], v[76:77], v[244:245]
	v_pk_fma_f32 v[46:47], v[46:47], v[78:79], v[246:247]
	v_mul_f32_e32 v210, v45, v45
	v_fmac_f32_e32 v210, v44, v44
	v_fmac_f32_e32 v210, v46, v46
	v_fmac_f32_e32 v210, v47, v47
	v_pk_mul_f32 v[244:245], v[100:101], v[44:45]
	v_pk_mul_f32 v[246:247], v[102:103], v[46:47]
	v_pk_fma_f32 v[40:41], v[40:41], v[72:73], v[248:249]
	v_pk_fma_f32 v[42:43], v[42:43], v[74:75], v[250:251]
	v_fmac_f32_e32 v210, v40, v40
	v_fmac_f32_e32 v210, v41, v41
	v_fmac_f32_e32 v210, v42, v42
	v_fmac_f32_e32 v210, v43, v43
	v_pk_mul_f32 v[248:249], v[98:99], v[40:41]
	v_pk_mul_f32 v[250:251], v[96:97], v[42:43]
	v_cvt_pk_bf16_f32 v244, v244, v245
	v_cvt_pk_bf16_f32 v245, v246, v247
	v_cvt_pk_bf16_f32 v246, v248, v249
	v_cvt_pk_bf16_f32 v247, v250, v251
	global_store_dwordx4 v208, v[244:247], s[64:65]
	v_pk_fma_f32 v[36:37], v[36:37], v[68:69], v[216:217]
	v_pk_fma_f32 v[38:39], v[38:39], v[70:71], v[218:219]
	v_fmac_f32_e32 v210, v36, v36
	v_fmac_f32_e32 v210, v37, v37
	v_fmac_f32_e32 v210, v38, v38
	v_fmac_f32_e32 v210, v39, v39
	v_pk_mul_f32 v[216:217], v[86:87], v[36:37]
	v_pk_mul_f32 v[218:219], v[84:85], v[38:39]
	v_pk_fma_f32 v[32:33], v[32:33], v[64:65], v[220:221]
	v_pk_fma_f32 v[34:35], v[34:35], v[66:67], v[222:223]
	v_fmac_f32_e32 v210, v32, v32
	v_fmac_f32_e32 v210, v33, v33
	v_fmac_f32_e32 v210, v34, v34
	v_fmac_f32_e32 v210, v35, v35
	v_pk_mul_f32 v[220:221], v[80:81], v[32:33]
	v_pk_mul_f32 v[222:223], v[82:83], v[34:35]
	v_cvt_pk_bf16_f32 v216, v216, v217
	v_cvt_pk_bf16_f32 v217, v218, v219
	v_cvt_pk_bf16_f32 v218, v220, v221
	v_cvt_pk_bf16_f32 v219, v222, v223
	global_store_dwordx4 v208, v[216:219], s[64:65] offset:256
	ds_bpermute_b32 v211, v203, v210
	v_permlane16_swap_b32_e32 v44, v40
	v_permlane16_swap_b32_e32 v45, v41
	v_permlane16_swap_b32_e32 v46, v42
	v_permlane16_swap_b32_e32 v47, v43
	v_permlane16_swap_b32_e32 v36, v32
	v_permlane16_swap_b32_e32 v37, v33
	v_permlane16_swap_b32_e32 v38, v34
	v_permlane16_swap_b32_e32 v39, v35
	v_permlane32_swap_b32_e32 v44, v40
	v_permlane32_swap_b32_e32 v45, v41
	v_permlane32_swap_b32_e32 v46, v42
	v_permlane32_swap_b32_e32 v47, v43
	v_permlane32_swap_b32_e32 v36, v32
	v_permlane32_swap_b32_e32 v37, v33
	v_permlane32_swap_b32_e32 v38, v34
	v_permlane32_swap_b32_e32 v39, v35
	s_nop 1
	v_mov_b32_dpp v248, v40 row_ror:8 row_mask:0xf bank_mask:0xf
	v_mov_b32_dpp v249, v41 row_ror:8 row_mask:0xf bank_mask:0xf
	v_mov_b32_dpp v250, v42 row_ror:8 row_mask:0xf bank_mask:0xf
	v_mov_b32_dpp v251, v43 row_ror:8 row_mask:0xf bank_mask:0xf
	v_mov_b32_dpp v220, v32 row_ror:8 row_mask:0xf bank_mask:0xf
	v_mov_b32_dpp v221, v33 row_ror:8 row_mask:0xf bank_mask:0xf
	v_mov_b32_dpp v222, v34 row_ror:8 row_mask:0xf bank_mask:0xf
	v_mov_b32_dpp v223, v35 row_ror:8 row_mask:0xf bank_mask:0xf
	s_mov_b32 vcc_lo, 0xff00ff
	s_mov_b32 vcc_hi, 0xff00ff
	v_mov_b32_e32 v205, 0xffff8040
	v_mov_b32_e32 v214, 0x8040
	v_cndmask_b32_e64 v205, v205, 0, vcc
	v_cndmask_b32_e64 v214, 0, v214, vcc
	v_add_u32_e32 v205, v205, v207
	v_add_u32_e32 v214, v214, v207
	v_cndmask_b32_e32 v244, v248, v44, vcc
	v_cndmask_b32_e32 v245, v249, v45, vcc
	v_cndmask_b32_e32 v246, v250, v46, vcc
	v_cndmask_b32_e32 v247, v251, v47, vcc
	v_cndmask_b32_e32 v216, v220, v36, vcc
	v_cndmask_b32_e32 v217, v221, v37, vcc
	v_cndmask_b32_e32 v218, v222, v38, vcc
	v_cndmask_b32_e32 v219, v223, v39, vcc
	v_cndmask_b32_e32 v44, v44, v248, vcc
	v_cndmask_b32_e32 v45, v45, v249, vcc
	v_cndmask_b32_e32 v46, v46, v250, vcc
	v_cndmask_b32_e32 v47, v47, v251, vcc
	v_cndmask_b32_e32 v36, v36, v220, vcc
	v_cndmask_b32_e32 v37, v37, v221, vcc
	v_cndmask_b32_e32 v38, v38, v222, vcc
	v_cndmask_b32_e32 v39, v39, v223, vcc
	global_store_dwordx4 v205, v[244:247], s[92:93]
	global_store_dwordx4 v205, v[216:219], s[92:93] offset:512
	global_store_dwordx4 v214, v[44:47], s[92:93]
	global_store_dwordx4 v214, v[36:39], s[92:93] offset:512
	v_add_u32_e32 v207, 0x10000, v207
	v_add_u32_e32 v206, 0x10000, v206
	global_load_dwordx4 v[248:251], v206, s[82:83] offset:64
	global_load_dwordx4 v[220:223], v206, s[82:83] offset:576
	global_load_dwordx4 v[244:247], v206, s[82:83]
	global_load_dwordx4 v[216:219], v206, s[82:83] offset:512
	s_waitcnt lgkmcnt(0)
; DI u32x4 pack8(const float* v) { u32x4 w; w.x = pk2(v[0], v[1]); w.y = pk2(v[2], v[3]); w.z = pk2(v[4], v[5]); w.w = pk2(v[6], v[7]); return w; }
; #define xor16_32(s) xor16_32_l((s), fr + 16 * fq)
;     DI void operator()(AccRef acc, const Unit& u, int wr, int wc, int fr, int fq) const {
;     ...
;             for (int m = 0; m < 4; ++m) {
;                 const int row = rb + 16 * m;
;                 const float* xi = row < MP ? xin_p + (size_t)row * 1024 : xin_s + (size_t)(row - MP) * 1024;
;                 float s = 0.f;
; #pragma unroll
;                 for (int bj = 0; bj < 2; ++bj) {
;                     const int c = u.pn * 256 + bj * 128 + cl;
;                     float v[8];
; #pragma unroll
;                     for (int n = 0; n < 2; ++n) {
;                         const f32x4 x = *(const f32x4*)(xi + c + 4 * n);
;                         const f32x4 y = x + gt[bj][n] * acc[ai][bj][m][n];
;                         *(f32x4*)(xout + (size_t)row * 1024 + c + 4 * n) = y;
; #pragma unroll
;                         for (int j = 0; j < 4; ++j) { s += y[j] * y[j]; v[4 * n + j] = ap ? y[j] * gs[bj][n][j] : 0.f; }
;                     }
;                     if (ap) *(u32x4*)(ap + (size_t)row * 1024 + c) = pack8(v);
;                 }
;                 s = xor16_32(s);
;                 if (fq == 0) ssq[(size_t)row * 16 + u.pn * 4 + wc] = s;
	v_add_f32_e32 v211, v210, v211
	ds_bpermute_b32 v212, v202, v211
	v_add_u32_e32 v208, 0x8000, v208
	s_waitcnt lgkmcnt(0)
	v_add_f32_e32 v211, v211, v212
	s_mov_b64 exec, 0xffff
	global_store_dword v209, v211, s[90:91]
	s_mov_b64 exec, -1
	v_add_u32_e32 v209, 0x400, v209
	s_waitcnt vmcnt(12)
	v_permlane32_swap_b32_e32 v228, v232
	v_permlane32_swap_b32_e32 v229, v233
	v_permlane32_swap_b32_e32 v230, v234
	v_permlane32_swap_b32_e32 v231, v235
	v_permlane32_swap_b32_e32 v236, v240
	v_permlane32_swap_b32_e32 v237, v241
	v_permlane32_swap_b32_e32 v238, v242
	v_permlane32_swap_b32_e32 v239, v243
	v_permlane16_swap_b32_e32 v228, v232
	v_permlane16_swap_b32_e32 v229, v233
	v_permlane16_swap_b32_e32 v230, v234
	v_permlane16_swap_b32_e32 v231, v235
	v_permlane16_swap_b32_e32 v236, v240
	v_permlane16_swap_b32_e32 v237, v241
	v_permlane16_swap_b32_e32 v238, v242
	v_permlane16_swap_b32_e32 v239, v243
	v_pk_fma_f32 v[28:29], v[28:29], v[76:77], v[228:229]
	v_pk_fma_f32 v[30:31], v[30:31], v[78:79], v[230:231]
	v_mul_f32_e32 v210, v29, v29
	v_fmac_f32_e32 v210, v28, v28
	v_fmac_f32_e32 v210, v30, v30
	v_fmac_f32_e32 v210, v31, v31
	v_pk_mul_f32 v[228:229], v[100:101], v[28:29]
	v_pk_mul_f32 v[230:231], v[102:103], v[30:31]
	v_pk_fma_f32 v[24:25], v[24:25], v[72:73], v[232:233]
	v_pk_fma_f32 v[26:27], v[26:27], v[74:75], v[234:235]
	v_fmac_f32_e32 v210, v24, v24
	v_fmac_f32_e32 v210, v25, v25
	v_fmac_f32_e32 v210, v26, v26
	v_fmac_f32_e32 v210, v27, v27
	v_pk_mul_f32 v[232:233], v[98:99], v[24:25]
	v_pk_mul_f32 v[234:235], v[96:97], v[26:27]
	v_cvt_pk_bf16_f32 v228, v228, v229
	v_cvt_pk_bf16_f32 v229, v230, v231
	v_cvt_pk_bf16_f32 v230, v232, v233
	v_cvt_pk_bf16_f32 v231, v234, v235
	global_store_dwordx4 v208, v[228:231], s[64:65]
	v_pk_fma_f32 v[20:21], v[20:21], v[68:69], v[236:237]
	v_pk_fma_f32 v[22:23], v[22:23], v[70:71], v[238:239]
	v_fmac_f32_e32 v210, v20, v20
	v_fmac_f32_e32 v210, v21, v21
	v_fmac_f32_e32 v210, v22, v22
	v_fmac_f32_e32 v210, v23, v23
	v_pk_mul_f32 v[236:237], v[86:87], v[20:21]
	v_pk_mul_f32 v[238:239], v[84:85], v[22:23]
	v_pk_fma_f32 v[16:17], v[16:17], v[64:65], v[240:241]
	v_pk_fma_f32 v[18:19], v[18:19], v[66:67], v[242:243]
	v_fmac_f32_e32 v210, v16, v16
	v_fmac_f32_e32 v210, v17, v17
	v_fmac_f32_e32 v210, v18, v18
	v_fmac_f32_e32 v210, v19, v19
	v_pk_mul_f32 v[240:241], v[80:81], v[16:17]
	v_pk_mul_f32 v[242:243], v[82:83], v[18:19]
	v_cvt_pk_bf16_f32 v236, v236, v237
	v_cvt_pk_bf16_f32 v237, v238, v239
	v_cvt_pk_bf16_f32 v238, v240, v241
	v_cvt_pk_bf16_f32 v239, v242, v243
	global_store_dwordx4 v208, v[236:239], s[64:65] offset:256
	ds_bpermute_b32 v211, v203, v210
	v_permlane16_swap_b32_e32 v28, v24
	v_permlane16_swap_b32_e32 v29, v25
	v_permlane16_swap_b32_e32 v30, v26
	v_permlane16_swap_b32_e32 v31, v27
	v_permlane16_swap_b32_e32 v20, v16
	v_permlane16_swap_b32_e32 v21, v17
	v_permlane16_swap_b32_e32 v22, v18
	v_permlane16_swap_b32_e32 v23, v19
	v_permlane32_swap_b32_e32 v28, v24
	v_permlane32_swap_b32_e32 v29, v25
	v_permlane32_swap_b32_e32 v30, v26
	v_permlane32_swap_b32_e32 v31, v27
	v_permlane32_swap_b32_e32 v20, v16
	v_permlane32_swap_b32_e32 v21, v17
	v_permlane32_swap_b32_e32 v22, v18
	v_permlane32_swap_b32_e32 v23, v19
	s_nop 1
	v_mov_b32_dpp v232, v24 row_ror:8 row_mask:0xf bank_mask:0xf
	v_mov_b32_dpp v233, v25 row_ror:8 row_mask:0xf bank_mask:0xf
	v_mov_b32_dpp v234, v26 row_ror:8 row_mask:0xf bank_mask:0xf
	v_mov_b32_dpp v235, v27 row_ror:8 row_mask:0xf bank_mask:0xf
	v_mov_b32_dpp v240, v16 row_ror:8 row_mask:0xf bank_mask:0xf
	v_mov_b32_dpp v241, v17 row_ror:8 row_mask:0xf bank_mask:0xf
	v_mov_b32_dpp v242, v18 row_ror:8 row_mask:0xf bank_mask:0xf
	v_mov_b32_dpp v243, v19 row_ror:8 row_mask:0xf bank_mask:0xf
	s_mov_b32 vcc_lo, 0xff00ff
	s_mov_b32 vcc_hi, 0xff00ff
	v_mov_b32_e32 v205, 0xffff8040
	v_mov_b32_e32 v214, 0x8040
	v_cndmask_b32_e64 v205, v205, 0, vcc
	v_cndmask_b32_e64 v214, 0, v214, vcc
	v_add_u32_e32 v205, v205, v207
	v_add_u32_e32 v214, v214, v207
	v_cndmask_b32_e32 v228, v232, v28, vcc
	v_cndmask_b32_e32 v229, v233, v29, vcc
	v_cndmask_b32_e32 v230, v234, v30, vcc
	v_cndmask_b32_e32 v231, v235, v31, vcc
	v_cndmask_b32_e32 v236, v240, v20, vcc
	v_cndmask_b32_e32 v237, v241, v21, vcc
	v_cndmask_b32_e32 v238, v242, v22, vcc
	v_cndmask_b32_e32 v239, v243, v23, vcc
	v_cndmask_b32_e32 v28, v28, v232, vcc
	v_cndmask_b32_e32 v29, v29, v233, vcc
	v_cndmask_b32_e32 v30, v30, v234, vcc
	v_cndmask_b32_e32 v31, v31, v235, vcc
	v_cndmask_b32_e32 v20, v20, v240, vcc
	v_cndmask_b32_e32 v21, v21, v241, vcc
	v_cndmask_b32_e32 v22, v22, v242, vcc
	v_cndmask_b32_e32 v23, v23, v243, vcc
	global_store_dwordx4 v205, v[228:231], s[92:93]
	global_store_dwordx4 v205, v[236:239], s[92:93] offset:512
	global_store_dwordx4 v214, v[28:31], s[92:93]
	global_store_dwordx4 v214, v[20:23], s[92:93] offset:512
	v_add_u32_e32 v207, 0x10000, v207
	s_waitcnt lgkmcnt(0)
	v_add_f32_e32 v211, v210, v211
	ds_bpermute_b32 v212, v202, v211
	v_add_u32_e32 v208, 0x8000, v208
	s_waitcnt lgkmcnt(0)
; DI u32x4 pack8(const float* v) { u32x4 w; w.x = pk2(v[0], v[1]); w.y = pk2(v[2], v[3]); w.z = pk2(v[4], v[5]); w.w = pk2(v[6], v[7]); return w; }
; #define xor16_32(s) xor16_32_l((s), fr + 16 * fq)
; #define otid() otid_w(g_wave)
; #define PG8_BAR __builtin_amdgcn_s_barrier()
; template <class Epi, bool ALIGN_EPI, bool SP2>
; DI void gemm_phase(int g_wave, LAS unsigned char* lds, const Gemm g, const StaticOrder& S, const Epi& E) {
;     ...
;         if constexpr (ALIGN_EPI) { if (wr == 0) PG8_BAR; }
;         { const int t2_ = otid(); int fr_ = t2_ & 15, fq_ = (t2_ >> 4) & 3, wr_ = wr, wc_ = wc; asm volatile("" : "+v"(fr_), "+v"(fq_), "+s"(wr_), "+s"(wc_)); E(acc, cur, wr_, wc_, fr_, fq_); }
;         if (!has_next) break;
; #pragma unroll
;         for (int a = 0; a < 2; ++a)
; #pragma unroll
;             for (int b = 0; b < 2; ++b)
; #pragma unroll
;                 for (int m = 0; m < 4; ++m)
; #pragma unroll
;                     for (int n = 0; n < 2; ++n) acc[a][b][m][n] = (f32x4){0.f, 0.f, 0.f, 0.f};
;         cur = nxt; cA = nA; cB = nB; ++ui;
;         if constexpr (ALIGN_EPI) { if (wr == 1) PG8_BAR; }
;     }
;     DI void operator()(AccRef acc, const Unit& u, int wr, int wc, int fr, int fq) const {
;     ...
;             for (int m = 0; m < 4; ++m) {
;                 const int row = rb + 16 * m;
;                 const float* xi = row < MP ? xin_p + (size_t)row * 1024 : xin_s + (size_t)(row - MP) * 1024;
;                 float s = 0.f;
; #pragma unroll
;                 for (int bj = 0; bj < 2; ++bj) {
;                     const int c = u.pn * 256 + bj * 128 + cl;
;                     float v[8];
; #pragma unroll
;                     for (int n = 0; n < 2; ++n) {
;                         const f32x4 x = *(const f32x4*)(xi + c + 4 * n);
;                         const f32x4 y = x + gt[bj][n] * acc[ai][bj][m][n];
;                         *(f32x4*)(xout + (size_t)row * 1024 + c + 4 * n) = y;
; #pragma unroll
;                         for (int j = 0; j < 4; ++j) { s += y[j] * y[j]; v[4 * n + j] = ap ? y[j] * gs[bj][n][j] : 0.f; }
;                     }
;                     if (ap) *(u32x4*)(ap + (size_t)row * 1024 + c) = pack8(v);
;                 }
;                 s = xor16_32(s);
;                 if (fq == 0) ssq[(size_t)row * 16 + u.pn * 4 + wc] = s;
	v_add_f32_e32 v211, v211, v212
	s_mov_b64 exec, 0xffff
	global_store_dword v209, v211, s[90:91]
	s_mov_b64 exec, -1
	v_add_u32_e32 v209, 0x400, v209
	s_waitcnt vmcnt(8)
	v_permlane32_swap_b32_e32 v244, v248
	v_permlane32_swap_b32_e32 v245, v249
	v_permlane32_swap_b32_e32 v246, v250
	v_permlane32_swap_b32_e32 v247, v251
	v_permlane32_swap_b32_e32 v216, v220
	v_permlane32_swap_b32_e32 v217, v221
	v_permlane32_swap_b32_e32 v218, v222
	v_permlane32_swap_b32_e32 v219, v223
	v_permlane16_swap_b32_e32 v244, v248
	v_permlane16_swap_b32_e32 v245, v249
	v_permlane16_swap_b32_e32 v246, v250
	v_permlane16_swap_b32_e32 v247, v251
	v_permlane16_swap_b32_e32 v216, v220
	v_permlane16_swap_b32_e32 v217, v221
	v_permlane16_swap_b32_e32 v218, v222
	v_permlane16_swap_b32_e32 v219, v223
	v_pk_fma_f32 v[12:13], v[12:13], v[76:77], v[244:245]
	v_pk_fma_f32 v[14:15], v[14:15], v[78:79], v[246:247]
	v_mul_f32_e32 v210, v13, v13
	v_fmac_f32_e32 v210, v12, v12
	v_fmac_f32_e32 v210, v14, v14
	v_fmac_f32_e32 v210, v15, v15
	v_pk_mul_f32 v[244:245], v[100:101], v[12:13]
	v_pk_mul_f32 v[246:247], v[102:103], v[14:15]
	v_pk_fma_f32 v[8:9], v[8:9], v[72:73], v[248:249]
	v_pk_fma_f32 v[10:11], v[10:11], v[74:75], v[250:251]
	v_fmac_f32_e32 v210, v8, v8
	v_fmac_f32_e32 v210, v9, v9
	v_fmac_f32_e32 v210, v10, v10
	v_fmac_f32_e32 v210, v11, v11
	v_pk_mul_f32 v[248:249], v[98:99], v[8:9]
	v_pk_mul_f32 v[250:251], v[96:97], v[10:11]
	v_cvt_pk_bf16_f32 v244, v244, v245
	v_cvt_pk_bf16_f32 v245, v246, v247
	v_cvt_pk_bf16_f32 v246, v248, v249
	v_cvt_pk_bf16_f32 v247, v250, v251
	global_store_dwordx4 v208, v[244:247], s[64:65]
	v_pk_fma_f32 v[4:5], v[4:5], v[68:69], v[216:217]
	v_pk_fma_f32 v[6:7], v[6:7], v[70:71], v[218:219]
	v_fmac_f32_e32 v210, v4, v4
	v_fmac_f32_e32 v210, v5, v5
	v_fmac_f32_e32 v210, v6, v6
	v_fmac_f32_e32 v210, v7, v7
	v_pk_mul_f32 v[216:217], v[86:87], v[4:5]
	v_pk_mul_f32 v[218:219], v[84:85], v[6:7]
	v_pk_fma_f32 v[0:1], v[0:1], v[64:65], v[220:221]
	v_pk_fma_f32 v[2:3], v[2:3], v[66:67], v[222:223]
	v_fmac_f32_e32 v210, v0, v0
	v_fmac_f32_e32 v210, v1, v1
	v_fmac_f32_e32 v210, v2, v2
	v_fmac_f32_e32 v210, v3, v3
	v_pk_mul_f32 v[220:221], v[80:81], v[0:1]
	v_pk_mul_f32 v[222:223], v[82:83], v[2:3]
	v_cvt_pk_bf16_f32 v216, v216, v217
	v_cvt_pk_bf16_f32 v217, v218, v219
	v_cvt_pk_bf16_f32 v218, v220, v221
	v_cvt_pk_bf16_f32 v219, v222, v223
	global_store_dwordx4 v208, v[216:219], s[64:65] offset:256
	ds_bpermute_b32 v211, v203, v210
	v_permlane16_swap_b32_e32 v12, v8
	v_permlane16_swap_b32_e32 v13, v9
	v_permlane16_swap_b32_e32 v14, v10
	v_permlane16_swap_b32_e32 v15, v11
	v_permlane16_swap_b32_e32 v4, v0
	v_permlane16_swap_b32_e32 v5, v1
	v_permlane16_swap_b32_e32 v6, v2
	v_permlane16_swap_b32_e32 v7, v3
	v_permlane32_swap_b32_e32 v12, v8
	v_permlane32_swap_b32_e32 v13, v9
	v_permlane32_swap_b32_e32 v14, v10
	v_permlane32_swap_b32_e32 v15, v11
	v_permlane32_swap_b32_e32 v4, v0
	v_permlane32_swap_b32_e32 v5, v1
	v_permlane32_swap_b32_e32 v6, v2
	v_permlane32_swap_b32_e32 v7, v3
	s_nop 1
	v_mov_b32_dpp v248, v8 row_ror:8 row_mask:0xf bank_mask:0xf
	v_mov_b32_dpp v249, v9 row_ror:8 row_mask:0xf bank_mask:0xf
	v_mov_b32_dpp v250, v10 row_ror:8 row_mask:0xf bank_mask:0xf
	v_mov_b32_dpp v251, v11 row_ror:8 row_mask:0xf bank_mask:0xf
	v_mov_b32_dpp v220, v0 row_ror:8 row_mask:0xf bank_mask:0xf
	v_mov_b32_dpp v221, v1 row_ror:8 row_mask:0xf bank_mask:0xf
	v_mov_b32_dpp v222, v2 row_ror:8 row_mask:0xf bank_mask:0xf
	v_mov_b32_dpp v223, v3 row_ror:8 row_mask:0xf bank_mask:0xf
	s_mov_b32 vcc_lo, 0xff00ff
	s_mov_b32 vcc_hi, 0xff00ff
	v_mov_b32_e32 v205, 0xffff8040
	v_mov_b32_e32 v214, 0x8040
	v_cndmask_b32_e64 v205, v205, 0, vcc
	v_cndmask_b32_e64 v214, 0, v214, vcc
	v_add_u32_e32 v205, v205, v207
	v_add_u32_e32 v214, v214, v207
	v_cndmask_b32_e32 v244, v248, v12, vcc
	v_cndmask_b32_e32 v245, v249, v13, vcc
	v_cndmask_b32_e32 v246, v250, v14, vcc
	v_cndmask_b32_e32 v247, v251, v15, vcc
	v_cndmask_b32_e32 v216, v220, v4, vcc
	v_cndmask_b32_e32 v217, v221, v5, vcc
	v_cndmask_b32_e32 v218, v222, v6, vcc
	v_cndmask_b32_e32 v219, v223, v7, vcc
	v_cndmask_b32_e32 v12, v12, v248, vcc
	v_cndmask_b32_e32 v13, v13, v249, vcc
	v_cndmask_b32_e32 v14, v14, v250, vcc
	v_cndmask_b32_e32 v15, v15, v251, vcc
	v_cndmask_b32_e32 v4, v4, v220, vcc
	v_cndmask_b32_e32 v5, v5, v221, vcc
	v_cndmask_b32_e32 v6, v6, v222, vcc
	v_cndmask_b32_e32 v7, v7, v223, vcc
	global_store_dwordx4 v205, v[244:247], s[92:93]
	global_store_dwordx4 v205, v[216:219], s[92:93] offset:512
	global_store_dwordx4 v214, v[12:15], s[92:93]
	global_store_dwordx4 v214, v[4:7], s[92:93] offset:512
	s_waitcnt lgkmcnt(0)
	v_add_f32_e32 v211, v210, v211
	ds_bpermute_b32 v212, v202, v211
	s_waitcnt lgkmcnt(0)
	v_add_f32_e32 v211, v211, v212
	s_mov_b64 exec, 0xffff
	global_store_dword v209, v211, s[90:91]
	s_mov_b64 exec, -1
	s_andn2_b64 vcc, exec, s[0:1]
	s_mov_b64 s[0:1], -1
	s_cbranch_vccnz .LBB0_1083
	s_andn2_b64 vcc, exec, s[4:5]
	s_cbranch_vccnz .LBB0_1082
	s_barrier
	s_branch .LBB0_1082

;     DI void operator()(AccRef acc, const Unit& u, int wr, int wc, int fr, int fq) const {
;     ...
; #pragma unroll
;         for (int ai = 0; ai < 2; ++ai) {
;             const int rb = u.pm * 256 + ai * 128 + wr * 64 + fr;
;             int mb, pos0, kv0; row_info(rb, mb, pos0, kv0);
;             f32x4 gt[2][2], gs[2][2];
; #pragma unroll
;             for (int bj = 0; bj < 2; ++bj)
; #pragma unroll
;                 for (int n = 0; n < 2; ++n) {
;                     const int c = u.pn * 256 + bj * 128 + cl + 4 * n;
;                     gt[bj][n] = *(const f32x4*)(gate + (size_t)mb * 6144 + c);
;                     if (ap) { const f32x4 g = *(const f32x4*)(gn + c), s = *(const f32x4*)(scn + (size_t)mb * 6144 + c); gs[bj][n] = g * (s + 1.f); }
;                 }
; #pragma unroll
;             for (int m = 0; m < 4; ++m) {
;                 const int row = rb + 16 * m;
;                 const float* xi = row < MP ? xin_p + (size_t)row * 1024 : xin_s + (size_t)(row - MP) * 1024;
;                 float s = 0.f;
; #pragma unroll
;                 for (int bj = 0; bj < 2; ++bj) {
;                     const int c = u.pn * 256 + bj * 128 + cl;
;                     float v[8];
; #pragma unroll
;                     for (int n = 0; n < 2; ++n) {
;                         const f32x4 x = *(const f32x4*)(xi + c + 4 * n);
;                         const f32x4 y = x + gt[bj][n] * acc[ai][bj][m][n];
.LBB0_1303:
	v_readlane_b32 s1, v253, 32
	v_mbcnt_lo_u32_b32 v100, -1, 0
	v_mbcnt_hi_u32_b32 v100, -1, v100
	s_mov_b32 s1, s28
	v_and_b32_e32 v202, 15, v100
	v_bfe_u32 v204, v100, 4, 2
	s_mov_b32 s12, s34
	s_lshl_b32 s16, s16, 8
	s_lshl_b32 s1, s1, 6
	s_add_i32 s1, s1, s16
	v_add_u32_e32 v192, s1, v202
	s_lshl_b32 s13, s12, 5
	s_lshl_b32 s1, s0, 8
	v_add_u32_e32 v224, 0xffffc000, v192
	s_add_i32 s13, s13, s1
	v_lshrrev_b32_e32 v101, 6, v224
	v_lshl_add_u32 v188, v204, 3, s13
	v_ashrrev_i32_e32 v100, 11, v192
	v_add_u32_e32 v101, 8, v101
	v_cmp_gt_i32_e32 vcc, s94, v192
	v_mov_b64_e32 v[102:103], s[56:57]
	v_ashrrev_i32_e32 v189, 31, v188
	v_cndmask_b32_e32 v104, v101, v100, vcc
	v_mov_b64_e32 v[100:101], s[6:7]
	v_mad_i64_i32 v[100:101], s[16:17], v104, s75, v[100:101]
	v_mad_i64_i32 v[102:103], s[16:17], v104, s75, v[102:103]
	v_lshlrev_b64 v[190:191], 2, v[188:189]
	v_lshl_add_u64 v[104:105], v[100:101], 0, v[190:191]
	v_lshl_add_u64 v[194:195], s[72:73], 0, v[190:191]
	v_lshl_add_u64 v[168:169], v[102:103], 0, v[190:191]
	global_load_dwordx4 v[108:111], v[104:105], off offset:16
	global_load_dwordx4 v[116:119], v[104:105], off
	global_load_dwordx4 v[148:151], v[194:195], off offset:16
	global_load_dwordx4 v[164:167], v[194:195], off
	global_load_dwordx4 v[160:163], v[168:169], off offset:16
	global_load_dwordx4 v[172:175], v[168:169], off
	global_load_dwordx4 v[100:103], v[104:105], off offset:528
	s_nop 0
	global_load_dwordx4 v[104:107], v[104:105], off offset:512
	s_nop 0
	global_load_dwordx4 v[144:147], v[194:195], off offset:528
	global_load_dwordx4 v[156:159], v[194:195], off offset:512
	global_load_dwordx4 v[152:155], v[168:169], off offset:528
	s_nop 0
	global_load_dwordx4 v[168:171], v[168:169], off offset:512
	s_movk_i32 s1, 0x3fff
	v_cmp_lt_i32_e32 vcc, s1, v192
	s_and_saveexec_b64 s[16:17], vcc
	s_xor_b64 s[16:17], exec, s[16:17]
	v_lshlrev_b64 v[196:197], 12, v[224:225]
	v_mov_b32_e32 v193, v225
	v_lshl_add_u64 v[198:199], s[20:21], 0, v[196:197]
	v_lshlrev_b64 v[196:197], 12, v[192:193]
	s_andn2_saveexec_b64 s[16:17], s[16:17]
	v_ashrrev_i32_e32 v193, 31, v192
	v_lshlrev_b64 v[196:197], 12, v[192:193]
	v_lshl_add_u64 v[198:199], s[42:43], 0, v[196:197]
	s_or_b64 exec, exec, s[16:17]
	s_sub_u32 s82, s20, 0x4000000
	s_subb_u32 s83, s21, 0
	s_cmp_ge_u32 s16, 0x4000
	s_cselect_b32 s82, s82, s42
	s_cselect_b32 s83, s83, s43
	v_lshl_add_u32 v206, v192, 12, v190
	v_lshlrev_b32_e32 v213, 4, v204
	v_sub_u32_e32 v206, v206, v213
	v_lshlrev_b32_e32 v213, 11, v192
	v_lshlrev_b32_e32 v209, 6, v192
	v_mov_b32_e32 v207, v206
	v_lshl_add_u32 v208, v188, 1, v213
	global_load_dwordx4 v[232:235], v206, s[82:83] offset:64
	global_load_dwordx4 v[240:243], v206, s[82:83] offset:576
	global_load_dwordx4 v[228:231], v206, s[82:83]
	global_load_dwordx4 v[236:239], v206, s[82:83] offset:512
	v_add_u32_e32 v206, 0x10000, v206
	global_load_dwordx4 v[248:251], v206, s[82:83] offset:64
	global_load_dwordx4 v[220:223], v206, s[82:83] offset:576
	global_load_dwordx4 v[244:247], v206, s[82:83]
	global_load_dwordx4 v[216:219], v206, s[82:83] offset:512
	v_add_u32_e32 v206, 0x10000, v206
	s_waitcnt vmcnt(8)
	v_pk_add_f32 v[172:173], v[172:173], 1.0 op_sel_hi:[1,0]
	v_pk_add_f32 v[154:155], v[154:155], 1.0 op_sel_hi:[1,0]
	v_pk_mul_f32 v[164:165], v[164:165], v[172:173]
	v_pk_add_f32 v[172:173], v[160:161], 1.0 op_sel_hi:[1,0]
	v_pk_add_f32 v[160:161], v[162:163], 1.0 op_sel_hi:[1,0]
	v_pk_mul_f32 v[162:163], v[148:149], v[172:173]
	v_pk_mul_f32 v[160:161], v[150:151], v[160:161]
	v_pk_add_f32 v[148:149], v[170:171], 1.0 op_sel_hi:[1,0]
	v_pk_add_f32 v[150:151], v[168:169], 1.0 op_sel_hi:[1,0]
	v_pk_mul_f32 v[146:147], v[146:147], v[154:155]
	v_lshl_add_u64 v[154:155], v[198:199], 0, v[190:191]
	v_pk_mul_f32 v[148:149], v[158:159], v[148:149]
	v_pk_mul_f32 v[150:151], v[156:157], v[150:151]
	v_pk_add_f32 v[174:175], v[174:175], 1.0 op_sel_hi:[1,0]
	v_pk_add_f32 v[152:153], v[152:153], 1.0 op_sel_hi:[1,0]
	v_pk_mul_f32 v[166:167], v[166:167], v[174:175]
	v_pk_mul_f32 v[144:145], v[144:145], v[152:153]
	v_lshlrev_b64 v[152:153], 11, v[192:193]
	v_lshl_add_u64 v[152:153], s[58:59], 0, v[152:153]
	v_lshlrev_b32_e32 v202, 2, v202
	v_lshl_add_u32 v202, v204, 6, v202
	v_xor_b32_e32 v203, 64, v202
	s_lshl_b32 s0, s0, 2
	v_xor_b32_e32 v202, 0x80, v202
	s_ashr_i32 s1, s0, 31
	s_ashr_i32 s13, s12, 31
	s_lshl_b64 s[0:1], s[0:1], 2
	s_add_u32 s16, s37, s0
	s_addc_u32 s17, s38, s1
	s_lshl_b64 s[0:1], s[12:13], 2
	s_add_u32 s90, s16, s0
	v_cmp_eq_u32_e32 vcc, 0, v204
	s_addc_u32 s91, s17, s1
	s_waitcnt vmcnt(4)
; DI u32x4 pack8(const float* v) { u32x4 w; w.x = pk2(v[0], v[1]); w.y = pk2(v[2], v[3]); w.z = pk2(v[4], v[5]); w.w = pk2(v[6], v[7]); return w; }
; #define xor16_32(s) xor16_32_l((s), fr + 16 * fq)
;     DI void operator()(AccRef acc, const Unit& u, int wr, int wc, int fr, int fq) const {
;     ...
;             for (int m = 0; m < 4; ++m) {
;                 const int row = rb + 16 * m;
;                 const float* xi = row < MP ? xin_p + (size_t)row * 1024 : xin_s + (size_t)(row - MP) * 1024;
;                 float s = 0.f;
; #pragma unroll
;                 for (int bj = 0; bj < 2; ++bj) {
;                     const int c = u.pn * 256 + bj * 128 + cl;
;                     float v[8];
; #pragma unroll
;                     for (int n = 0; n < 2; ++n) {
;                         const f32x4 x = *(const f32x4*)(xi + c + 4 * n);
;                         const f32x4 y = x + gt[bj][n] * acc[ai][bj][m][n];
;                         *(f32x4*)(xout + (size_t)row * 1024 + c + 4 * n) = y;
; #pragma unroll
;                         for (int j = 0; j < 4; ++j) { s += y[j] * y[j]; v[4 * n + j] = ap ? y[j] * gs[bj][n][j] : 0.f; }
;                     }
;                     if (ap) *(u32x4*)(ap + (size_t)row * 1024 + c) = pack8(v);
;                 }
;                 s = xor16_32(s);
;                 if (fq == 0) ssq[(size_t)row * 16 + u.pn * 4 + wc] = s;
	v_permlane32_swap_b32_e32 v228, v232
	v_permlane32_swap_b32_e32 v229, v233
	v_permlane32_swap_b32_e32 v230, v234
	v_permlane32_swap_b32_e32 v231, v235
	v_permlane32_swap_b32_e32 v236, v240
	v_permlane32_swap_b32_e32 v237, v241
	v_permlane32_swap_b32_e32 v238, v242
	v_permlane32_swap_b32_e32 v239, v243
	v_permlane16_swap_b32_e32 v228, v232
	v_permlane16_swap_b32_e32 v229, v233
	v_permlane16_swap_b32_e32 v230, v234
	v_permlane16_swap_b32_e32 v231, v235
	v_permlane16_swap_b32_e32 v236, v240
	v_permlane16_swap_b32_e32 v237, v241
	v_permlane16_swap_b32_e32 v238, v242
	v_permlane16_swap_b32_e32 v239, v243
	v_pk_fma_f32 v[140:141], v[140:141], v[116:117], v[228:229]
	v_pk_fma_f32 v[142:143], v[142:143], v[118:119], v[230:231]
	v_mul_f32_e32 v210, v141, v141
	v_fmac_f32_e32 v210, v140, v140
	v_fmac_f32_e32 v210, v142, v142
	v_fmac_f32_e32 v210, v143, v143
	v_pk_mul_f32 v[228:229], v[164:165], v[140:141]
	v_pk_mul_f32 v[230:231], v[166:167], v[142:143]
	v_pk_fma_f32 v[136:137], v[136:137], v[108:109], v[232:233]
	v_pk_fma_f32 v[138:139], v[138:139], v[110:111], v[234:235]
	v_fmac_f32_e32 v210, v136, v136
	v_fmac_f32_e32 v210, v137, v137
	v_fmac_f32_e32 v210, v138, v138
	v_fmac_f32_e32 v210, v139, v139
	v_pk_mul_f32 v[232:233], v[162:163], v[136:137]
	v_pk_mul_f32 v[234:235], v[160:161], v[138:139]
	v_cvt_pk_bf16_f32 v228, v228, v229
	v_cvt_pk_bf16_f32 v229, v230, v231
	v_cvt_pk_bf16_f32 v230, v232, v233
	v_cvt_pk_bf16_f32 v231, v234, v235
	global_store_dwordx4 v208, v[228:231], s[58:59]
	v_pk_fma_f32 v[132:133], v[132:133], v[104:105], v[236:237]
	v_pk_fma_f32 v[134:135], v[134:135], v[106:107], v[238:239]
	v_fmac_f32_e32 v210, v132, v132
	v_fmac_f32_e32 v210, v133, v133
	v_fmac_f32_e32 v210, v134, v134
	v_fmac_f32_e32 v210, v135, v135
	v_pk_mul_f32 v[236:237], v[150:151], v[132:133]
	v_pk_mul_f32 v[238:239], v[148:149], v[134:135]
	v_pk_fma_f32 v[128:129], v[128:129], v[100:101], v[240:241]
	v_pk_fma_f32 v[130:131], v[130:131], v[102:103], v[242:243]
	v_fmac_f32_e32 v210, v128, v128
	v_fmac_f32_e32 v210, v129, v129
	v_fmac_f32_e32 v210, v130, v130
	v_fmac_f32_e32 v210, v131, v131
	v_pk_mul_f32 v[240:241], v[144:145], v[128:129]
	v_pk_mul_f32 v[242:243], v[146:147], v[130:131]
	v_cvt_pk_bf16_f32 v236, v236, v237
	v_cvt_pk_bf16_f32 v237, v238, v239
	v_cvt_pk_bf16_f32 v238, v240, v241
	v_cvt_pk_bf16_f32 v239, v242, v243
	global_store_dwordx4 v208, v[236:239], s[58:59] offset:256
	ds_bpermute_b32 v211, v203, v210
	v_permlane16_swap_b32_e32 v140, v136
	v_permlane16_swap_b32_e32 v141, v137
	v_permlane16_swap_b32_e32 v142, v138
	v_permlane16_swap_b32_e32 v143, v139
	v_permlane16_swap_b32_e32 v132, v128
	v_permlane16_swap_b32_e32 v133, v129
	v_permlane16_swap_b32_e32 v134, v130
	v_permlane16_swap_b32_e32 v135, v131
	v_permlane32_swap_b32_e32 v140, v136
	v_permlane32_swap_b32_e32 v141, v137
	v_permlane32_swap_b32_e32 v142, v138
	v_permlane32_swap_b32_e32 v143, v139
	v_permlane32_swap_b32_e32 v132, v128
	v_permlane32_swap_b32_e32 v133, v129
	v_permlane32_swap_b32_e32 v134, v130
	v_permlane32_swap_b32_e32 v135, v131
	s_nop 1
	v_mov_b32_dpp v232, v136 row_ror:8 row_mask:0xf bank_mask:0xf
	v_mov_b32_dpp v233, v137 row_ror:8 row_mask:0xf bank_mask:0xf
	v_mov_b32_dpp v234, v138 row_ror:8 row_mask:0xf bank_mask:0xf
	v_mov_b32_dpp v235, v139 row_ror:8 row_mask:0xf bank_mask:0xf
	v_mov_b32_dpp v240, v128 row_ror:8 row_mask:0xf bank_mask:0xf
	v_mov_b32_dpp v241, v129 row_ror:8 row_mask:0xf bank_mask:0xf
	v_mov_b32_dpp v242, v130 row_ror:8 row_mask:0xf bank_mask:0xf
	v_mov_b32_dpp v243, v131 row_ror:8 row_mask:0xf bank_mask:0xf
	s_mov_b32 vcc_lo, 0xff00ff
	s_mov_b32 vcc_hi, 0xff00ff
	v_mov_b32_e32 v205, 0xffff8040
	v_mov_b32_e32 v214, 0x8040
	v_cndmask_b32_e64 v205, v205, 0, vcc
	v_cndmask_b32_e64 v214, 0, v214, vcc
	v_add_u32_e32 v205, v205, v207
	v_add_u32_e32 v214, v214, v207
	v_cndmask_b32_e32 v228, v232, v140, vcc
	v_cndmask_b32_e32 v229, v233, v141, vcc
	v_cndmask_b32_e32 v230, v234, v142, vcc
	v_cndmask_b32_e32 v231, v235, v143, vcc
	v_cndmask_b32_e32 v236, v240, v132, vcc
	v_cndmask_b32_e32 v237, v241, v133, vcc
	v_cndmask_b32_e32 v238, v242, v134, vcc
	v_cndmask_b32_e32 v239, v243, v135, vcc
	v_cndmask_b32_e32 v140, v140, v232, vcc
	v_cndmask_b32_e32 v141, v141, v233, vcc
	v_cndmask_b32_e32 v142, v142, v234, vcc
	v_cndmask_b32_e32 v143, v143, v235, vcc
	v_cndmask_b32_e32 v132, v132, v240, vcc
	v_cndmask_b32_e32 v133, v133, v241, vcc
	v_cndmask_b32_e32 v134, v134, v242, vcc
	v_cndmask_b32_e32 v135, v135, v243, vcc
	global_store_dwordx4 v205, v[228:231], s[92:93]
	global_store_dwordx4 v205, v[236:239], s[92:93] offset:512
	global_store_dwordx4 v214, v[140:143], s[92:93]
	global_store_dwordx4 v214, v[132:135], s[92:93] offset:512
	v_add_u32_e32 v207, 0x10000, v207
	global_load_dwordx4 v[232:235], v206, s[82:83] offset:64
	global_load_dwordx4 v[240:243], v206, s[82:83] offset:576
	global_load_dwordx4 v[228:231], v206, s[82:83]
	global_load_dwordx4 v[236:239], v206, s[82:83] offset:512
	s_waitcnt lgkmcnt(0)
	v_add_f32_e32 v211, v210, v211
	ds_bpermute_b32 v212, v202, v211
	v_add_u32_e32 v208, 0x8000, v208
	s_waitcnt lgkmcnt(0)
	v_add_f32_e32 v211, v211, v212
	s_mov_b64 exec, 0xffff
	global_store_dword v209, v211, s[90:91]
	s_mov_b64 exec, -1
	v_add_u32_e32 v209, 0x400, v209
	s_waitcnt vmcnt(11)
; DI u32x4 pack8(const float* v) { u32x4 w; w.x = pk2(v[0], v[1]); w.y = pk2(v[2], v[3]); w.z = pk2(v[4], v[5]); w.w = pk2(v[6], v[7]); return w; }
; #define xor16_32(s) xor16_32_l((s), fr + 16 * fq)
;     DI void operator()(AccRef acc, const Unit& u, int wr, int wc, int fr, int fq) const {
;     ...
;             for (int m = 0; m < 4; ++m) {
;                 const int row = rb + 16 * m;
;                 const float* xi = row < MP ? xin_p + (size_t)row * 1024 : xin_s + (size_t)(row - MP) * 1024;
;                 float s = 0.f;
; #pragma unroll
;                 for (int bj = 0; bj < 2; ++bj) {
;                     const int c = u.pn * 256 + bj * 128 + cl;
;                     float v[8];
; #pragma unroll
;                     for (int n = 0; n < 2; ++n) {
;                         const f32x4 x = *(const f32x4*)(xi + c + 4 * n);
;                         const f32x4 y = x + gt[bj][n] * acc[ai][bj][m][n];
;                         *(f32x4*)(xout + (size_t)row * 1024 + c + 4 * n) = y;
; #pragma unroll
;                         for (int j = 0; j < 4; ++j) { s += y[j] * y[j]; v[4 * n + j] = ap ? y[j] * gs[bj][n][j] : 0.f; }
;                     }
;                     if (ap) *(u32x4*)(ap + (size_t)row * 1024 + c) = pack8(v);
;                 }
;                 s = xor16_32(s);
;                 if (fq == 0) ssq[(size_t)row * 16 + u.pn * 4 + wc] = s;
	v_permlane32_swap_b32_e32 v244, v248
	v_permlane32_swap_b32_e32 v245, v249
	v_permlane32_swap_b32_e32 v246, v250
	v_permlane32_swap_b32_e32 v247, v251
	v_permlane32_swap_b32_e32 v216, v220
	v_permlane32_swap_b32_e32 v217, v221
	v_permlane32_swap_b32_e32 v218, v222
	v_permlane32_swap_b32_e32 v219, v223
	v_permlane16_swap_b32_e32 v244, v248
	v_permlane16_swap_b32_e32 v245, v249
	v_permlane16_swap_b32_e32 v246, v250
	v_permlane16_swap_b32_e32 v247, v251
	v_permlane16_swap_b32_e32 v216, v220
	v_permlane16_swap_b32_e32 v217, v221
	v_permlane16_swap_b32_e32 v218, v222
	v_permlane16_swap_b32_e32 v219, v223
	v_pk_fma_f32 v[124:125], v[124:125], v[116:117], v[244:245]
	v_pk_fma_f32 v[126:127], v[126:127], v[118:119], v[246:247]
	v_mul_f32_e32 v210, v125, v125
	v_fmac_f32_e32 v210, v124, v124
	v_fmac_f32_e32 v210, v126, v126
	v_fmac_f32_e32 v210, v127, v127
	v_pk_mul_f32 v[244:245], v[164:165], v[124:125]
	v_pk_mul_f32 v[246:247], v[166:167], v[126:127]
	v_pk_fma_f32 v[120:121], v[120:121], v[108:109], v[248:249]
	v_pk_fma_f32 v[122:123], v[122:123], v[110:111], v[250:251]
	v_fmac_f32_e32 v210, v120, v120
	v_fmac_f32_e32 v210, v121, v121
	v_fmac_f32_e32 v210, v122, v122
	v_fmac_f32_e32 v210, v123, v123
	v_pk_mul_f32 v[248:249], v[162:163], v[120:121]
	v_pk_mul_f32 v[250:251], v[160:161], v[122:123]
	v_cvt_pk_bf16_f32 v244, v244, v245
	v_cvt_pk_bf16_f32 v245, v246, v247
	v_cvt_pk_bf16_f32 v246, v248, v249
	v_cvt_pk_bf16_f32 v247, v250, v251
	global_store_dwordx4 v208, v[244:247], s[58:59]
	v_pk_fma_f32 v[112:113], v[112:113], v[104:105], v[216:217]
	v_pk_fma_f32 v[114:115], v[114:115], v[106:107], v[218:219]
	v_fmac_f32_e32 v210, v112, v112
	v_fmac_f32_e32 v210, v113, v113
	v_fmac_f32_e32 v210, v114, v114
	v_fmac_f32_e32 v210, v115, v115
	v_pk_mul_f32 v[216:217], v[150:151], v[112:113]
	v_pk_mul_f32 v[218:219], v[148:149], v[114:115]
	v_pk_fma_f32 v[96:97], v[96:97], v[100:101], v[220:221]
	v_pk_fma_f32 v[98:99], v[98:99], v[102:103], v[222:223]
	v_fmac_f32_e32 v210, v96, v96
	v_fmac_f32_e32 v210, v97, v97
	v_fmac_f32_e32 v210, v98, v98
	v_fmac_f32_e32 v210, v99, v99
	v_pk_mul_f32 v[220:221], v[144:145], v[96:97]
	v_pk_mul_f32 v[222:223], v[146:147], v[98:99]
	v_cvt_pk_bf16_f32 v216, v216, v217
	v_cvt_pk_bf16_f32 v217, v218, v219
	v_cvt_pk_bf16_f32 v218, v220, v221
	v_cvt_pk_bf16_f32 v219, v222, v223
	global_store_dwordx4 v208, v[216:219], s[58:59] offset:256
	ds_bpermute_b32 v211, v203, v210
	v_permlane16_swap_b32_e32 v124, v120
	v_permlane16_swap_b32_e32 v125, v121
	v_permlane16_swap_b32_e32 v126, v122
	v_permlane16_swap_b32_e32 v127, v123
	v_permlane16_swap_b32_e32 v112, v96
	v_permlane16_swap_b32_e32 v113, v97
	v_permlane16_swap_b32_e32 v114, v98
	v_permlane16_swap_b32_e32 v115, v99
	v_permlane32_swap_b32_e32 v124, v120
	v_permlane32_swap_b32_e32 v125, v121
	v_permlane32_swap_b32_e32 v126, v122
	v_permlane32_swap_b32_e32 v127, v123
	v_permlane32_swap_b32_e32 v112, v96
	v_permlane32_swap_b32_e32 v113, v97
	v_permlane32_swap_b32_e32 v114, v98
	v_permlane32_swap_b32_e32 v115, v99
	s_nop 1
	v_mov_b32_dpp v248, v120 row_ror:8 row_mask:0xf bank_mask:0xf
	v_mov_b32_dpp v249, v121 row_ror:8 row_mask:0xf bank_mask:0xf
	v_mov_b32_dpp v250, v122 row_ror:8 row_mask:0xf bank_mask:0xf
	v_mov_b32_dpp v251, v123 row_ror:8 row_mask:0xf bank_mask:0xf
	v_mov_b32_dpp v220, v96 row_ror:8 row_mask:0xf bank_mask:0xf
	v_mov_b32_dpp v221, v97 row_ror:8 row_mask:0xf bank_mask:0xf
	v_mov_b32_dpp v222, v98 row_ror:8 row_mask:0xf bank_mask:0xf
	v_mov_b32_dpp v223, v99 row_ror:8 row_mask:0xf bank_mask:0xf
	s_mov_b32 vcc_lo, 0xff00ff
	s_mov_b32 vcc_hi, 0xff00ff
	v_mov_b32_e32 v205, 0xffff8040
	v_mov_b32_e32 v214, 0x8040
	v_cndmask_b32_e64 v205, v205, 0, vcc
	v_cndmask_b32_e64 v214, 0, v214, vcc
	v_add_u32_e32 v205, v205, v207
	v_add_u32_e32 v214, v214, v207
	v_cndmask_b32_e32 v244, v248, v124, vcc
	v_cndmask_b32_e32 v245, v249, v125, vcc
	v_cndmask_b32_e32 v246, v250, v126, vcc
	v_cndmask_b32_e32 v247, v251, v127, vcc
	v_cndmask_b32_e32 v216, v220, v112, vcc
	v_cndmask_b32_e32 v217, v221, v113, vcc
	v_cndmask_b32_e32 v218, v222, v114, vcc
	v_cndmask_b32_e32 v219, v223, v115, vcc
	v_cndmask_b32_e32 v124, v124, v248, vcc
	v_cndmask_b32_e32 v125, v125, v249, vcc
	v_cndmask_b32_e32 v126, v126, v250, vcc
	v_cndmask_b32_e32 v127, v127, v251, vcc
	v_cndmask_b32_e32 v112, v112, v220, vcc
	v_cndmask_b32_e32 v113, v113, v221, vcc
	v_cndmask_b32_e32 v114, v114, v222, vcc
	v_cndmask_b32_e32 v115, v115, v223, vcc
	global_store_dwordx4 v205, v[244:247], s[92:93]
	global_store_dwordx4 v205, v[216:219], s[92:93] offset:512
	global_store_dwordx4 v214, v[124:127], s[92:93]
	global_store_dwordx4 v214, v[112:115], s[92:93] offset:512
	v_add_u32_e32 v207, 0x10000, v207
	v_add_u32_e32 v206, 0x10000, v206
	global_load_dwordx4 v[248:251], v206, s[82:83] offset:64
	global_load_dwordx4 v[220:223], v206, s[82:83] offset:576
	global_load_dwordx4 v[244:247], v206, s[82:83]
	global_load_dwordx4 v[216:219], v206, s[82:83] offset:512
	s_waitcnt lgkmcnt(0)
	v_add_f32_e32 v211, v210, v211
	ds_bpermute_b32 v212, v202, v211
	v_add_u32_e32 v208, 0x8000, v208
	s_waitcnt lgkmcnt(0)
	v_add_f32_e32 v211, v211, v212
	s_mov_b64 exec, 0xffff
	global_store_dword v209, v211, s[90:91]
	s_mov_b64 exec, -1
	v_add_u32_e32 v209, 0x400, v209
	s_waitcnt vmcnt(12)
; DI u32x4 pack8(const float* v) { u32x4 w; w.x = pk2(v[0], v[1]); w.y = pk2(v[2], v[3]); w.z = pk2(v[4], v[5]); w.w = pk2(v[6], v[7]); return w; }
; #define xor16_32(s) xor16_32_l((s), fr + 16 * fq)
;     DI void operator()(AccRef acc, const Unit& u, int wr, int wc, int fr, int fq) const {
;     ...
;             for (int m = 0; m < 4; ++m) {
;                 const int row = rb + 16 * m;
;                 const float* xi = row < MP ? xin_p + (size_t)row * 1024 : xin_s + (size_t)(row - MP) * 1024;
;                 float s = 0.f;
; #pragma unroll
;                 for (int bj = 0; bj < 2; ++bj) {
;                     const int c = u.pn * 256 + bj * 128 + cl;
;                     float v[8];
; #pragma unroll
;                     for (int n = 0; n < 2; ++n) {
;                         const f32x4 x = *(const f32x4*)(xi + c + 4 * n);
;                         const f32x4 y = x + gt[bj][n] * acc[ai][bj][m][n];
;                         *(f32x4*)(xout + (size_t)row * 1024 + c + 4 * n) = y;
; #pragma unroll
;                         for (int j = 0; j < 4; ++j) { s += y[j] * y[j]; v[4 * n + j] = ap ? y[j] * gs[bj][n][j] : 0.f; }
;                     }
;                     if (ap) *(u32x4*)(ap + (size_t)row * 1024 + c) = pack8(v);
;                 }
;                 s = xor16_32(s);
;                 if (fq == 0) ssq[(size_t)row * 16 + u.pn * 4 + wc] = s;
	v_permlane32_swap_b32_e32 v228, v232
	v_permlane32_swap_b32_e32 v229, v233
	v_permlane32_swap_b32_e32 v230, v234
	v_permlane32_swap_b32_e32 v231, v235
	v_permlane32_swap_b32_e32 v236, v240
	v_permlane32_swap_b32_e32 v237, v241
	v_permlane32_swap_b32_e32 v238, v242
	v_permlane32_swap_b32_e32 v239, v243
	v_permlane16_swap_b32_e32 v228, v232
	v_permlane16_swap_b32_e32 v229, v233
	v_permlane16_swap_b32_e32 v230, v234
	v_permlane16_swap_b32_e32 v231, v235
	v_permlane16_swap_b32_e32 v236, v240
	v_permlane16_swap_b32_e32 v237, v241
	v_permlane16_swap_b32_e32 v238, v242
	v_permlane16_swap_b32_e32 v239, v243
	v_pk_fma_f32 v[92:93], v[92:93], v[116:117], v[228:229]
	v_pk_fma_f32 v[94:95], v[94:95], v[118:119], v[230:231]
	v_mul_f32_e32 v210, v93, v93
	v_fmac_f32_e32 v210, v92, v92
	v_fmac_f32_e32 v210, v94, v94
	v_fmac_f32_e32 v210, v95, v95
	v_pk_mul_f32 v[228:229], v[164:165], v[92:93]
	v_pk_mul_f32 v[230:231], v[166:167], v[94:95]
	v_pk_fma_f32 v[88:89], v[88:89], v[108:109], v[232:233]
	v_pk_fma_f32 v[90:91], v[90:91], v[110:111], v[234:235]
	v_fmac_f32_e32 v210, v88, v88
	v_fmac_f32_e32 v210, v89, v89
	v_fmac_f32_e32 v210, v90, v90
	v_fmac_f32_e32 v210, v91, v91
	v_pk_mul_f32 v[232:233], v[162:163], v[88:89]
	v_pk_mul_f32 v[234:235], v[160:161], v[90:91]
	v_cvt_pk_bf16_f32 v228, v228, v229
	v_cvt_pk_bf16_f32 v229, v230, v231
	v_cvt_pk_bf16_f32 v230, v232, v233
	v_cvt_pk_bf16_f32 v231, v234, v235
	global_store_dwordx4 v208, v[228:231], s[58:59]
	v_pk_fma_f32 v[84:85], v[84:85], v[104:105], v[236:237]
	v_pk_fma_f32 v[86:87], v[86:87], v[106:107], v[238:239]
	v_fmac_f32_e32 v210, v84, v84
	v_fmac_f32_e32 v210, v85, v85
	v_fmac_f32_e32 v210, v86, v86
	v_fmac_f32_e32 v210, v87, v87
	v_pk_mul_f32 v[236:237], v[150:151], v[84:85]
	v_pk_mul_f32 v[238:239], v[148:149], v[86:87]
	v_pk_fma_f32 v[80:81], v[80:81], v[100:101], v[240:241]
	v_pk_fma_f32 v[82:83], v[82:83], v[102:103], v[242:243]
	v_fmac_f32_e32 v210, v80, v80
	v_fmac_f32_e32 v210, v81, v81
	v_fmac_f32_e32 v210, v82, v82
	v_fmac_f32_e32 v210, v83, v83
	v_pk_mul_f32 v[240:241], v[144:145], v[80:81]
	v_pk_mul_f32 v[242:243], v[146:147], v[82:83]
	v_cvt_pk_bf16_f32 v236, v236, v237
	v_cvt_pk_bf16_f32 v237, v238, v239
	v_cvt_pk_bf16_f32 v238, v240, v241
	v_cvt_pk_bf16_f32 v239, v242, v243
	global_store_dwordx4 v208, v[236:239], s[58:59] offset:256
	ds_bpermute_b32 v211, v203, v210
	v_permlane16_swap_b32_e32 v92, v88
	v_permlane16_swap_b32_e32 v93, v89
	v_permlane16_swap_b32_e32 v94, v90
	v_permlane16_swap_b32_e32 v95, v91
	v_permlane16_swap_b32_e32 v84, v80
	v_permlane16_swap_b32_e32 v85, v81
	v_permlane16_swap_b32_e32 v86, v82
	v_permlane16_swap_b32_e32 v87, v83
	v_permlane32_swap_b32_e32 v92, v88
	v_permlane32_swap_b32_e32 v93, v89
	v_permlane32_swap_b32_e32 v94, v90
	v_permlane32_swap_b32_e32 v95, v91
	v_permlane32_swap_b32_e32 v84, v80
	v_permlane32_swap_b32_e32 v85, v81
	v_permlane32_swap_b32_e32 v86, v82
	v_permlane32_swap_b32_e32 v87, v83
	s_nop 1
	v_mov_b32_dpp v232, v88 row_ror:8 row_mask:0xf bank_mask:0xf
	v_mov_b32_dpp v233, v89 row_ror:8 row_mask:0xf bank_mask:0xf
	v_mov_b32_dpp v234, v90 row_ror:8 row_mask:0xf bank_mask:0xf
	v_mov_b32_dpp v235, v91 row_ror:8 row_mask:0xf bank_mask:0xf
	v_mov_b32_dpp v240, v80 row_ror:8 row_mask:0xf bank_mask:0xf
	v_mov_b32_dpp v241, v81 row_ror:8 row_mask:0xf bank_mask:0xf
	v_mov_b32_dpp v242, v82 row_ror:8 row_mask:0xf bank_mask:0xf
	v_mov_b32_dpp v243, v83 row_ror:8 row_mask:0xf bank_mask:0xf
	s_mov_b32 vcc_lo, 0xff00ff
	s_mov_b32 vcc_hi, 0xff00ff
	v_mov_b32_e32 v205, 0xffff8040
	v_mov_b32_e32 v214, 0x8040
	v_cndmask_b32_e64 v205, v205, 0, vcc
	v_cndmask_b32_e64 v214, 0, v214, vcc
	v_add_u32_e32 v205, v205, v207
	v_add_u32_e32 v214, v214, v207
	v_cndmask_b32_e32 v228, v232, v92, vcc
	v_cndmask_b32_e32 v229, v233, v93, vcc
	v_cndmask_b32_e32 v230, v234, v94, vcc
	v_cndmask_b32_e32 v231, v235, v95, vcc
	v_cndmask_b32_e32 v236, v240, v84, vcc
	v_cndmask_b32_e32 v237, v241, v85, vcc
	v_cndmask_b32_e32 v238, v242, v86, vcc
	v_cndmask_b32_e32 v239, v243, v87, vcc
	v_cndmask_b32_e32 v92, v92, v232, vcc
	v_cndmask_b32_e32 v93, v93, v233, vcc
	v_cndmask_b32_e32 v94, v94, v234, vcc
	v_cndmask_b32_e32 v95, v95, v235, vcc
	v_cndmask_b32_e32 v84, v84, v240, vcc
	v_cndmask_b32_e32 v85, v85, v241, vcc
	v_cndmask_b32_e32 v86, v86, v242, vcc
	v_cndmask_b32_e32 v87, v87, v243, vcc
	global_store_dwordx4 v205, v[228:231], s[92:93]
	global_store_dwordx4 v205, v[236:239], s[92:93] offset:512
	global_store_dwordx4 v214, v[92:95], s[92:93]
	global_store_dwordx4 v214, v[84:87], s[92:93] offset:512
	v_add_u32_e32 v207, 0x10000, v207
	v_add_u32_e32 v206, 0x50000, v206
	global_load_dwordx4 v[232:235], v206, s[82:83] offset:64
	global_load_dwordx4 v[240:243], v206, s[82:83] offset:576
	global_load_dwordx4 v[228:231], v206, s[82:83]
	global_load_dwordx4 v[236:239], v206, s[82:83] offset:512
	s_waitcnt lgkmcnt(0)
	v_add_f32_e32 v211, v210, v211
	ds_bpermute_b32 v212, v202, v211
	v_add_u32_e32 v208, 0x8000, v208
	s_waitcnt lgkmcnt(0)
	v_add_f32_e32 v211, v211, v212
	s_mov_b64 exec, 0xffff
	global_store_dword v209, v211, s[90:91]
	s_mov_b64 exec, -1
	v_add_u32_e32 v209, 0x400, v209
	s_waitcnt vmcnt(12)
; DI u32x4 pack8(const float* v) { u32x4 w; w.x = pk2(v[0], v[1]); w.y = pk2(v[2], v[3]); w.z = pk2(v[4], v[5]); w.w = pk2(v[6], v[7]); return w; }
; #define xor16_32(s) xor16_32_l((s), fr + 16 * fq)
;     DI void operator()(AccRef acc, const Unit& u, int wr, int wc, int fr, int fq) const {
;     ...
;             for (int m = 0; m < 4; ++m) {
;                 const int row = rb + 16 * m;
;                 const float* xi = row < MP ? xin_p + (size_t)row * 1024 : xin_s + (size_t)(row - MP) * 1024;
;                 float s = 0.f;
; #pragma unroll
;                 for (int bj = 0; bj < 2; ++bj) {
;                     const int c = u.pn * 256 + bj * 128 + cl;
;                     float v[8];
; #pragma unroll
;                     for (int n = 0; n < 2; ++n) {
;                         const f32x4 x = *(const f32x4*)(xi + c + 4 * n);
;                         const f32x4 y = x + gt[bj][n] * acc[ai][bj][m][n];
;                         *(f32x4*)(xout + (size_t)row * 1024 + c + 4 * n) = y;
; #pragma unroll
;                         for (int j = 0; j < 4; ++j) { s += y[j] * y[j]; v[4 * n + j] = ap ? y[j] * gs[bj][n][j] : 0.f; }
;                     }
;                     if (ap) *(u32x4*)(ap + (size_t)row * 1024 + c) = pack8(v);
;                 }
;                 s = xor16_32(s);
;                 if (fq == 0) ssq[(size_t)row * 16 + u.pn * 4 + wc] = s;
	v_permlane32_swap_b32_e32 v244, v248
	v_permlane32_swap_b32_e32 v245, v249
	v_permlane32_swap_b32_e32 v246, v250
	v_permlane32_swap_b32_e32 v247, v251
	v_permlane32_swap_b32_e32 v216, v220
	v_permlane32_swap_b32_e32 v217, v221
	v_permlane32_swap_b32_e32 v218, v222
	v_permlane32_swap_b32_e32 v219, v223
	v_permlane16_swap_b32_e32 v244, v248
	v_permlane16_swap_b32_e32 v245, v249
	v_permlane16_swap_b32_e32 v246, v250
	v_permlane16_swap_b32_e32 v247, v251
	v_permlane16_swap_b32_e32 v216, v220
	v_permlane16_swap_b32_e32 v217, v221
	v_permlane16_swap_b32_e32 v218, v222
	v_permlane16_swap_b32_e32 v219, v223
	v_pk_fma_f32 v[76:77], v[76:77], v[116:117], v[244:245]
	v_pk_fma_f32 v[78:79], v[78:79], v[118:119], v[246:247]
	v_mul_f32_e32 v210, v77, v77
	v_fmac_f32_e32 v210, v76, v76
	v_fmac_f32_e32 v210, v78, v78
	v_fmac_f32_e32 v210, v79, v79
	v_pk_mul_f32 v[244:245], v[164:165], v[76:77]
	v_pk_mul_f32 v[246:247], v[166:167], v[78:79]
	v_pk_fma_f32 v[72:73], v[72:73], v[108:109], v[248:249]
	v_pk_fma_f32 v[74:75], v[74:75], v[110:111], v[250:251]
	v_fmac_f32_e32 v210, v72, v72
	v_fmac_f32_e32 v210, v73, v73
	v_fmac_f32_e32 v210, v74, v74
	v_fmac_f32_e32 v210, v75, v75
	v_pk_mul_f32 v[248:249], v[162:163], v[72:73]
	v_pk_mul_f32 v[250:251], v[160:161], v[74:75]
	v_cvt_pk_bf16_f32 v244, v244, v245
	v_cvt_pk_bf16_f32 v245, v246, v247
	v_cvt_pk_bf16_f32 v246, v248, v249
	v_cvt_pk_bf16_f32 v247, v250, v251
	global_store_dwordx4 v208, v[244:247], s[58:59]
	v_pk_fma_f32 v[68:69], v[68:69], v[104:105], v[216:217]
	v_pk_fma_f32 v[70:71], v[70:71], v[106:107], v[218:219]
	v_fmac_f32_e32 v210, v68, v68
	v_fmac_f32_e32 v210, v69, v69
	v_fmac_f32_e32 v210, v70, v70
	v_fmac_f32_e32 v210, v71, v71
	v_pk_mul_f32 v[216:217], v[150:151], v[68:69]
	v_pk_mul_f32 v[218:219], v[148:149], v[70:71]
	v_pk_fma_f32 v[64:65], v[64:65], v[100:101], v[220:221]
	v_pk_fma_f32 v[66:67], v[66:67], v[102:103], v[222:223]
	v_fmac_f32_e32 v210, v64, v64
	v_fmac_f32_e32 v210, v65, v65
	v_fmac_f32_e32 v210, v66, v66
	v_fmac_f32_e32 v210, v67, v67
	v_pk_mul_f32 v[220:221], v[144:145], v[64:65]
	v_pk_mul_f32 v[222:223], v[146:147], v[66:67]
	v_cvt_pk_bf16_f32 v216, v216, v217
	v_cvt_pk_bf16_f32 v217, v218, v219
	v_cvt_pk_bf16_f32 v218, v220, v221
	v_cvt_pk_bf16_f32 v219, v222, v223
	global_store_dwordx4 v208, v[216:219], s[58:59] offset:256
	ds_bpermute_b32 v211, v203, v210
	v_permlane16_swap_b32_e32 v76, v72
	v_permlane16_swap_b32_e32 v77, v73
	v_permlane16_swap_b32_e32 v78, v74
	v_permlane16_swap_b32_e32 v79, v75
	v_permlane16_swap_b32_e32 v68, v64
	v_permlane16_swap_b32_e32 v69, v65
	v_permlane16_swap_b32_e32 v70, v66
	v_permlane16_swap_b32_e32 v71, v67
	v_permlane32_swap_b32_e32 v76, v72
	v_permlane32_swap_b32_e32 v77, v73
	v_permlane32_swap_b32_e32 v78, v74
	v_permlane32_swap_b32_e32 v79, v75
	v_permlane32_swap_b32_e32 v68, v64
	v_permlane32_swap_b32_e32 v69, v65
	v_permlane32_swap_b32_e32 v70, v66
	v_permlane32_swap_b32_e32 v71, v67
	s_nop 1
	v_mov_b32_dpp v248, v72 row_ror:8 row_mask:0xf bank_mask:0xf
	v_mov_b32_dpp v249, v73 row_ror:8 row_mask:0xf bank_mask:0xf
	v_mov_b32_dpp v250, v74 row_ror:8 row_mask:0xf bank_mask:0xf
	v_mov_b32_dpp v251, v75 row_ror:8 row_mask:0xf bank_mask:0xf
	v_mov_b32_dpp v220, v64 row_ror:8 row_mask:0xf bank_mask:0xf
	v_mov_b32_dpp v221, v65 row_ror:8 row_mask:0xf bank_mask:0xf
	v_mov_b32_dpp v222, v66 row_ror:8 row_mask:0xf bank_mask:0xf
	v_mov_b32_dpp v223, v67 row_ror:8 row_mask:0xf bank_mask:0xf
	s_mov_b32 vcc_lo, 0xff00ff
	s_mov_b32 vcc_hi, 0xff00ff
	v_mov_b32_e32 v205, 0xffff8040
	v_mov_b32_e32 v214, 0x8040
	v_cndmask_b32_e64 v205, v205, 0, vcc
	v_cndmask_b32_e64 v214, 0, v214, vcc
	v_add_u32_e32 v205, v205, v207
	v_add_u32_e32 v214, v214, v207
	v_cndmask_b32_e32 v244, v248, v76, vcc
	v_cndmask_b32_e32 v245, v249, v77, vcc
	v_cndmask_b32_e32 v246, v250, v78, vcc
	v_cndmask_b32_e32 v247, v251, v79, vcc
	v_cndmask_b32_e32 v216, v220, v68, vcc
	v_cndmask_b32_e32 v217, v221, v69, vcc
	v_cndmask_b32_e32 v218, v222, v70, vcc
	v_cndmask_b32_e32 v219, v223, v71, vcc
	v_cndmask_b32_e32 v76, v76, v248, vcc
	v_cndmask_b32_e32 v77, v77, v249, vcc
	v_cndmask_b32_e32 v78, v78, v250, vcc
	v_cndmask_b32_e32 v79, v79, v251, vcc
	v_cndmask_b32_e32 v68, v68, v220, vcc
	v_cndmask_b32_e32 v69, v69, v221, vcc
	v_cndmask_b32_e32 v70, v70, v222, vcc
	v_cndmask_b32_e32 v71, v71, v223, vcc
	global_store_dwordx4 v205, v[244:247], s[92:93]
	global_store_dwordx4 v205, v[216:219], s[92:93] offset:512
	global_store_dwordx4 v214, v[76:79], s[92:93]
	global_store_dwordx4 v214, v[68:71], s[92:93] offset:512
	v_add_u32_e32 v207, 0x50000, v207
	v_add_u32_e32 v206, 0x10000, v206
	global_load_dwordx4 v[248:251], v206, s[82:83] offset:64
	global_load_dwordx4 v[220:223], v206, s[82:83] offset:576
	global_load_dwordx4 v[244:247], v206, s[82:83]
	global_load_dwordx4 v[216:219], v206, s[82:83] offset:512
	s_waitcnt lgkmcnt(0)
	v_add_f32_e32 v211, v210, v211
	ds_bpermute_b32 v212, v202, v211
	v_add_u32_e32 v208, 0x28000, v208
	s_waitcnt lgkmcnt(0)
	v_add_f32_e32 v211, v211, v212
	s_mov_b64 exec, 0xffff
	global_store_dword v209, v211, s[90:91]
	s_mov_b64 exec, -1
	v_add_u32_e32 v209, 0x1400, v209
	v_add_u32_e32 v224, 0xffffc080, v192
	v_add_u32_e32 v112, 0x80, v192
	s_waitcnt lgkmcnt(0)
; DI u32x4 pack8(const float* v) { u32x4 w; w.x = pk2(v[0], v[1]); w.y = pk2(v[2], v[3]); w.z = pk2(v[4], v[5]); w.w = pk2(v[6], v[7]); return w; }
; #define xor16_32(s) xor16_32_l((s), fr + 16 * fq)
;     DI void operator()(AccRef acc, const Unit& u, int wr, int wc, int fr, int fq) const {
;     ...
;             const int rb = u.pm * 256 + ai * 128 + wr * 64 + fr;
;             int mb, pos0, kv0; row_info(rb, mb, pos0, kv0);
;             f32x4 gt[2][2], gs[2][2];
; #pragma unroll
;             for (int bj = 0; bj < 2; ++bj)
; #pragma unroll
;                 for (int n = 0; n < 2; ++n) {
;                     const int c = u.pn * 256 + bj * 128 + cl + 4 * n;
;                     gt[bj][n] = *(const f32x4*)(gate + (size_t)mb * 6144 + c);
;                     if (ap) { const f32x4 g = *(const f32x4*)(gn + c), s = *(const f32x4*)(scn + (size_t)mb * 6144 + c); gs[bj][n] = g * (s + 1.f); }
;                 }
; #pragma unroll
;             for (int m = 0; m < 4; ++m) {
;                 const int row = rb + 16 * m;
;                 const float* xi = row < MP ? xin_p + (size_t)row * 1024 : xin_s + (size_t)(row - MP) * 1024;
;                 float s = 0.f;
; #pragma unroll
;                 for (int bj = 0; bj < 2; ++bj) {
;                     const int c = u.pn * 256 + bj * 128 + cl;
;                     float v[8];
; #pragma unroll
;                     for (int n = 0; n < 2; ++n) {
;                         const f32x4 x = *(const f32x4*)(xi + c + 4 * n);
;                         const f32x4 y = x + gt[bj][n] * acc[ai][bj][m][n];
;                         *(f32x4*)(xout + (size_t)row * 1024 + c + 4 * n) = y;
; #pragma unroll
;                         for (int j = 0; j < 4; ++j) { s += y[j] * y[j]; v[4 * n + j] = ap ? y[j] * gs[bj][n][j] : 0.f; }
;                     }
;                     if (ap) *(u32x4*)(ap + (size_t)row * 1024 + c) = pack8(v);
;                 }
;                 s = xor16_32(s);
;                 if (fq == 0) ssq[(size_t)row * 16 + u.pn * 4 + wc] = s;
	v_lshrrev_b32_e32 v65, 6, v224
	v_ashrrev_i32_e32 v64, 11, v112
	v_add_u32_e32 v65, 8, v65
	v_cmp_gt_i32_e64 s[0:1], s94, v112
	v_mov_b64_e32 v[66:67], s[56:57]
	s_nop 0
	v_cndmask_b32_e64 v68, v65, v64, s[0:1]
	v_mov_b64_e32 v[64:65], s[6:7]
	v_mad_i64_i32 v[64:65], s[0:1], v68, s75, v[64:65]
	v_mad_i64_i32 v[66:67], s[0:1], v68, s75, v[66:67]
	v_lshl_add_u64 v[68:69], v[64:65], 0, v[190:191]
	v_lshl_add_u64 v[104:105], v[66:67], 0, v[190:191]
	global_load_dwordx4 v[72:75], v[68:69], off offset:16
	global_load_dwordx4 v[76:79], v[68:69], off
	global_load_dwordx4 v[84:87], v[194:195], off offset:16
	global_load_dwordx4 v[100:103], v[194:195], off
	global_load_dwordx4 v[96:99], v[104:105], off offset:16
	global_load_dwordx4 v[108:111], v[104:105], off
	global_load_dwordx4 v[64:67], v[68:69], off offset:528
	s_nop 0
	global_load_dwordx4 v[68:71], v[68:69], off offset:512
	s_nop 0
	global_load_dwordx4 v[80:83], v[194:195], off offset:528
	global_load_dwordx4 v[92:95], v[194:195], off offset:512
	global_load_dwordx4 v[88:91], v[104:105], off offset:528
	s_nop 0
	global_load_dwordx4 v[104:107], v[104:105], off offset:512
	s_movk_i32 s0, 0x3fff
	v_cmp_lt_i32_e64 s[0:1], s0, v112
	s_and_saveexec_b64 s[12:13], s[0:1]
	s_xor_b64 s[0:1], exec, s[12:13]
	v_lshlrev_b64 v[114:115], 12, v[224:225]
	v_mov_b32_e32 v113, v225
	v_lshl_add_u64 v[116:117], s[20:21], 0, v[114:115]
	v_lshlrev_b64 v[114:115], 12, v[112:113]
	s_andn2_saveexec_b64 s[0:1], s[0:1]
	v_ashrrev_i32_e32 v113, 31, v112
	v_lshlrev_b64 v[114:115], 12, v[112:113]
	v_lshl_add_u64 v[116:117], s[42:43], 0, v[114:115]
	s_or_b64 exec, exec, s[0:1]
	s_waitcnt vmcnt(6)
	v_pk_add_f32 v[108:109], v[108:109], 1.0 op_sel_hi:[1,0]
	s_waitcnt vmcnt(1)
	v_pk_add_f32 v[90:91], v[90:91], 1.0 op_sel_hi:[1,0]
	v_pk_mul_f32 v[100:101], v[100:101], v[108:109]
	v_pk_add_f32 v[108:109], v[96:97], 1.0 op_sel_hi:[1,0]
	v_pk_add_f32 v[96:97], v[98:99], 1.0 op_sel_hi:[1,0]
	v_pk_mul_f32 v[98:99], v[84:85], v[108:109]
	v_pk_mul_f32 v[96:97], v[86:87], v[96:97]
	s_waitcnt vmcnt(0)
	v_pk_add_f32 v[84:85], v[106:107], 1.0 op_sel_hi:[1,0]
	v_pk_add_f32 v[86:87], v[104:105], 1.0 op_sel_hi:[1,0]
	v_pk_mul_f32 v[82:83], v[82:83], v[90:91]
	v_lshl_add_u64 v[90:91], v[116:117], 0, v[190:191]
	v_pk_mul_f32 v[84:85], v[94:95], v[84:85]
	v_pk_mul_f32 v[86:87], v[92:93], v[86:87]
	v_pk_add_f32 v[110:111], v[110:111], 1.0 op_sel_hi:[1,0]
	v_pk_add_f32 v[88:89], v[88:89], 1.0 op_sel_hi:[1,0]
	v_pk_mul_f32 v[102:103], v[102:103], v[110:111]
	v_pk_mul_f32 v[80:81], v[80:81], v[88:89]
	v_lshlrev_b64 v[88:89], 11, v[112:113]
	v_lshl_add_u64 v[88:89], s[58:59], 0, v[88:89]
	v_permlane32_swap_b32_e32 v228, v232
	v_permlane32_swap_b32_e32 v229, v233
	v_permlane32_swap_b32_e32 v230, v234
	v_permlane32_swap_b32_e32 v231, v235
	v_permlane32_swap_b32_e32 v236, v240
	v_permlane32_swap_b32_e32 v237, v241
	v_permlane32_swap_b32_e32 v238, v242
	v_permlane32_swap_b32_e32 v239, v243
	v_permlane16_swap_b32_e32 v228, v232
	v_permlane16_swap_b32_e32 v229, v233
	v_permlane16_swap_b32_e32 v230, v234
	v_permlane16_swap_b32_e32 v231, v235
	v_permlane16_swap_b32_e32 v236, v240
	v_permlane16_swap_b32_e32 v237, v241
	v_permlane16_swap_b32_e32 v238, v242
	v_permlane16_swap_b32_e32 v239, v243
	v_pk_fma_f32 v[60:61], v[60:61], v[76:77], v[228:229]
	v_pk_fma_f32 v[62:63], v[62:63], v[78:79], v[230:231]
	v_mul_f32_e32 v210, v61, v61
	v_fmac_f32_e32 v210, v60, v60
	v_fmac_f32_e32 v210, v62, v62
	v_fmac_f32_e32 v210, v63, v63
	v_pk_mul_f32 v[228:229], v[100:101], v[60:61]
	v_pk_mul_f32 v[230:231], v[102:103], v[62:63]
	v_pk_fma_f32 v[56:57], v[56:57], v[72:73], v[232:233]
	v_pk_fma_f32 v[58:59], v[58:59], v[74:75], v[234:235]
	v_fmac_f32_e32 v210, v56, v56
	v_fmac_f32_e32 v210, v57, v57
	v_fmac_f32_e32 v210, v58, v58
	v_fmac_f32_e32 v210, v59, v59
	v_pk_mul_f32 v[232:233], v[98:99], v[56:57]
	v_pk_mul_f32 v[234:235], v[96:97], v[58:59]
	v_cvt_pk_bf16_f32 v228, v228, v229
	v_cvt_pk_bf16_f32 v229, v230, v231
	v_cvt_pk_bf16_f32 v230, v232, v233
	v_cvt_pk_bf16_f32 v231, v234, v235
	global_store_dwordx4 v208, v[228:231], s[58:59]
	v_pk_fma_f32 v[52:53], v[52:53], v[68:69], v[236:237]
	v_pk_fma_f32 v[54:55], v[54:55], v[70:71], v[238:239]
	v_fmac_f32_e32 v210, v52, v52
	v_fmac_f32_e32 v210, v53, v53
	v_fmac_f32_e32 v210, v54, v54
	v_fmac_f32_e32 v210, v55, v55
	v_pk_mul_f32 v[236:237], v[86:87], v[52:53]
	v_pk_mul_f32 v[238:239], v[84:85], v[54:55]
	v_pk_fma_f32 v[48:49], v[48:49], v[64:65], v[240:241]
	v_pk_fma_f32 v[50:51], v[50:51], v[66:67], v[242:243]
	v_fmac_f32_e32 v210, v48, v48
	v_fmac_f32_e32 v210, v49, v49
	v_fmac_f32_e32 v210, v50, v50
	v_fmac_f32_e32 v210, v51, v51
	v_pk_mul_f32 v[240:241], v[80:81], v[48:49]
	v_pk_mul_f32 v[242:243], v[82:83], v[50:51]
	v_cvt_pk_bf16_f32 v236, v236, v237
	v_cvt_pk_bf16_f32 v237, v238, v239
	v_cvt_pk_bf16_f32 v238, v240, v241
	v_cvt_pk_bf16_f32 v239, v242, v243
	global_store_dwordx4 v208, v[236:239], s[58:59] offset:256
	ds_bpermute_b32 v211, v203, v210
	v_permlane16_swap_b32_e32 v60, v56
	v_permlane16_swap_b32_e32 v61, v57
	v_permlane16_swap_b32_e32 v62, v58
	v_permlane16_swap_b32_e32 v63, v59
	v_permlane16_swap_b32_e32 v52, v48
	v_permlane16_swap_b32_e32 v53, v49
	v_permlane16_swap_b32_e32 v54, v50
	v_permlane16_swap_b32_e32 v55, v51
	v_permlane32_swap_b32_e32 v60, v56
	v_permlane32_swap_b32_e32 v61, v57
	v_permlane32_swap_b32_e32 v62, v58
	v_permlane32_swap_b32_e32 v63, v59
	v_permlane32_swap_b32_e32 v52, v48
	v_permlane32_swap_b32_e32 v53, v49
	v_permlane32_swap_b32_e32 v54, v50
	v_permlane32_swap_b32_e32 v55, v51
	s_nop 1
	v_mov_b32_dpp v232, v56 row_ror:8 row_mask:0xf bank_mask:0xf
; DI u32x4 pack8(const float* v) { u32x4 w; w.x = pk2(v[0], v[1]); w.y = pk2(v[2], v[3]); w.z = pk2(v[4], v[5]); w.w = pk2(v[6], v[7]); return w; }
; #define xor16_32(s) xor16_32_l((s), fr + 16 * fq)
;     DI void operator()(AccRef acc, const Unit& u, int wr, int wc, int fr, int fq) const {
;     ...
;             for (int m = 0; m < 4; ++m) {
;                 const int row = rb + 16 * m;
;                 const float* xi = row < MP ? xin_p + (size_t)row * 1024 : xin_s + (size_t)(row - MP) * 1024;
;                 float s = 0.f;
; #pragma unroll
;                 for (int bj = 0; bj < 2; ++bj) {
;                     const int c = u.pn * 256 + bj * 128 + cl;
;                     float v[8];
; #pragma unroll
;                     for (int n = 0; n < 2; ++n) {
;                         const f32x4 x = *(const f32x4*)(xi + c + 4 * n);
;                         const f32x4 y = x + gt[bj][n] * acc[ai][bj][m][n];
;                         *(f32x4*)(xout + (size_t)row * 1024 + c + 4 * n) = y;
; #pragma unroll
;                         for (int j = 0; j < 4; ++j) { s += y[j] * y[j]; v[4 * n + j] = ap ? y[j] * gs[bj][n][j] : 0.f; }
;                     }
;                     if (ap) *(u32x4*)(ap + (size_t)row * 1024 + c) = pack8(v);
;                 }
;                 s = xor16_32(s);
;                 if (fq == 0) ssq[(size_t)row * 16 + u.pn * 4 + wc] = s;
	v_mov_b32_dpp v233, v57 row_ror:8 row_mask:0xf bank_mask:0xf
	v_mov_b32_dpp v234, v58 row_ror:8 row_mask:0xf bank_mask:0xf
	v_mov_b32_dpp v235, v59 row_ror:8 row_mask:0xf bank_mask:0xf
	v_mov_b32_dpp v240, v48 row_ror:8 row_mask:0xf bank_mask:0xf
	v_mov_b32_dpp v241, v49 row_ror:8 row_mask:0xf bank_mask:0xf
	v_mov_b32_dpp v242, v50 row_ror:8 row_mask:0xf bank_mask:0xf
	v_mov_b32_dpp v243, v51 row_ror:8 row_mask:0xf bank_mask:0xf
	s_mov_b32 vcc_lo, 0xff00ff
	s_mov_b32 vcc_hi, 0xff00ff
	v_mov_b32_e32 v205, 0xffff8040
	v_mov_b32_e32 v214, 0x8040
	v_cndmask_b32_e64 v205, v205, 0, vcc
	v_cndmask_b32_e64 v214, 0, v214, vcc
	v_add_u32_e32 v205, v205, v207
	v_add_u32_e32 v214, v214, v207
	v_cndmask_b32_e32 v228, v232, v60, vcc
	v_cndmask_b32_e32 v229, v233, v61, vcc
	v_cndmask_b32_e32 v230, v234, v62, vcc
	v_cndmask_b32_e32 v231, v235, v63, vcc
	v_cndmask_b32_e32 v236, v240, v52, vcc
	v_cndmask_b32_e32 v237, v241, v53, vcc
	v_cndmask_b32_e32 v238, v242, v54, vcc
	v_cndmask_b32_e32 v239, v243, v55, vcc
	v_cndmask_b32_e32 v60, v60, v232, vcc
	v_cndmask_b32_e32 v61, v61, v233, vcc
	v_cndmask_b32_e32 v62, v62, v234, vcc
	v_cndmask_b32_e32 v63, v63, v235, vcc
	v_cndmask_b32_e32 v52, v52, v240, vcc
	v_cndmask_b32_e32 v53, v53, v241, vcc
	v_cndmask_b32_e32 v54, v54, v242, vcc
	v_cndmask_b32_e32 v55, v55, v243, vcc
	global_store_dwordx4 v205, v[228:231], s[92:93]
	global_store_dwordx4 v205, v[236:239], s[92:93] offset:512
	global_store_dwordx4 v214, v[60:63], s[92:93]
	global_store_dwordx4 v214, v[52:55], s[92:93] offset:512
	v_add_u32_e32 v207, 0x10000, v207
	v_add_u32_e32 v206, 0x10000, v206
	global_load_dwordx4 v[232:235], v206, s[82:83] offset:64
	global_load_dwordx4 v[240:243], v206, s[82:83] offset:576
	global_load_dwordx4 v[228:231], v206, s[82:83]
	global_load_dwordx4 v[236:239], v206, s[82:83] offset:512
	s_waitcnt lgkmcnt(0)
	v_add_f32_e32 v211, v210, v211
	ds_bpermute_b32 v212, v202, v211
	v_add_u32_e32 v208, 0x8000, v208
	s_waitcnt lgkmcnt(0)
	v_add_f32_e32 v211, v211, v212
	s_mov_b64 exec, 0xffff
	global_store_dword v209, v211, s[90:91]
	s_mov_b64 exec, -1
	v_add_u32_e32 v209, 0x400, v209
	v_permlane32_swap_b32_e32 v244, v248
	v_permlane32_swap_b32_e32 v245, v249
	v_permlane32_swap_b32_e32 v246, v250
	v_permlane32_swap_b32_e32 v247, v251
	v_permlane32_swap_b32_e32 v216, v220
	v_permlane32_swap_b32_e32 v217, v221
	v_permlane32_swap_b32_e32 v218, v222
	v_permlane32_swap_b32_e32 v219, v223
	v_permlane16_swap_b32_e32 v244, v248
	v_permlane16_swap_b32_e32 v245, v249
	v_permlane16_swap_b32_e32 v246, v250
	v_permlane16_swap_b32_e32 v247, v251
	v_permlane16_swap_b32_e32 v216, v220
	v_permlane16_swap_b32_e32 v217, v221
	v_permlane16_swap_b32_e32 v218, v222
	v_permlane16_swap_b32_e32 v219, v223
	v_pk_fma_f32 v[44:45], v[44:45], v[76:77], v[244:245]
	v_pk_fma_f32 v[46:47], v[46:47], v[78:79], v[246:247]
	v_mul_f32_e32 v210, v45, v45
	v_fmac_f32_e32 v210, v44, v44
	v_fmac_f32_e32 v210, v46, v46
	v_fmac_f32_e32 v210, v47, v47
	v_pk_mul_f32 v[244:245], v[100:101], v[44:45]
	v_pk_mul_f32 v[246:247], v[102:103], v[46:47]
	v_pk_fma_f32 v[40:41], v[40:41], v[72:73], v[248:249]
	v_pk_fma_f32 v[42:43], v[42:43], v[74:75], v[250:251]
	v_fmac_f32_e32 v210, v40, v40
	v_fmac_f32_e32 v210, v41, v41
	v_fmac_f32_e32 v210, v42, v42
	v_fmac_f32_e32 v210, v43, v43
	v_pk_mul_f32 v[248:249], v[98:99], v[40:41]
	v_pk_mul_f32 v[250:251], v[96:97], v[42:43]
	v_cvt_pk_bf16_f32 v244, v244, v245
	v_cvt_pk_bf16_f32 v245, v246, v247
	v_cvt_pk_bf16_f32 v246, v248, v249
	v_cvt_pk_bf16_f32 v247, v250, v251
	global_store_dwordx4 v208, v[244:247], s[58:59]
	v_pk_fma_f32 v[36:37], v[36:37], v[68:69], v[216:217]
	v_pk_fma_f32 v[38:39], v[38:39], v[70:71], v[218:219]
	v_fmac_f32_e32 v210, v36, v36
	v_fmac_f32_e32 v210, v37, v37
	v_fmac_f32_e32 v210, v38, v38
	v_fmac_f32_e32 v210, v39, v39
	v_pk_mul_f32 v[216:217], v[86:87], v[36:37]
	v_pk_mul_f32 v[218:219], v[84:85], v[38:39]
	v_pk_fma_f32 v[32:33], v[32:33], v[64:65], v[220:221]
	v_pk_fma_f32 v[34:35], v[34:35], v[66:67], v[222:223]
	v_fmac_f32_e32 v210, v32, v32
	v_fmac_f32_e32 v210, v33, v33
	v_fmac_f32_e32 v210, v34, v34
	v_fmac_f32_e32 v210, v35, v35
	v_pk_mul_f32 v[220:221], v[80:81], v[32:33]
	v_pk_mul_f32 v[222:223], v[82:83], v[34:35]
	v_cvt_pk_bf16_f32 v216, v216, v217
	v_cvt_pk_bf16_f32 v217, v218, v219
	v_cvt_pk_bf16_f32 v218, v220, v221
	v_cvt_pk_bf16_f32 v219, v222, v223
	global_store_dwordx4 v208, v[216:219], s[58:59] offset:256
	ds_bpermute_b32 v211, v203, v210
	v_permlane16_swap_b32_e32 v44, v40
	v_permlane16_swap_b32_e32 v45, v41
	v_permlane16_swap_b32_e32 v46, v42
	v_permlane16_swap_b32_e32 v47, v43
	v_permlane16_swap_b32_e32 v36, v32
	v_permlane16_swap_b32_e32 v37, v33
	v_permlane16_swap_b32_e32 v38, v34
	v_permlane16_swap_b32_e32 v39, v35
	v_permlane32_swap_b32_e32 v44, v40
	v_permlane32_swap_b32_e32 v45, v41
	v_permlane32_swap_b32_e32 v46, v42
	v_permlane32_swap_b32_e32 v47, v43
	v_permlane32_swap_b32_e32 v36, v32
	v_permlane32_swap_b32_e32 v37, v33
	v_permlane32_swap_b32_e32 v38, v34
	v_permlane32_swap_b32_e32 v39, v35
	s_nop 1
	v_mov_b32_dpp v248, v40 row_ror:8 row_mask:0xf bank_mask:0xf
	v_mov_b32_dpp v249, v41 row_ror:8 row_mask:0xf bank_mask:0xf
	v_mov_b32_dpp v250, v42 row_ror:8 row_mask:0xf bank_mask:0xf
	v_mov_b32_dpp v251, v43 row_ror:8 row_mask:0xf bank_mask:0xf
	v_mov_b32_dpp v220, v32 row_ror:8 row_mask:0xf bank_mask:0xf
	v_mov_b32_dpp v221, v33 row_ror:8 row_mask:0xf bank_mask:0xf
	v_mov_b32_dpp v222, v34 row_ror:8 row_mask:0xf bank_mask:0xf
	v_mov_b32_dpp v223, v35 row_ror:8 row_mask:0xf bank_mask:0xf
	s_mov_b32 vcc_lo, 0xff00ff
	s_mov_b32 vcc_hi, 0xff00ff
	v_mov_b32_e32 v205, 0xffff8040
	v_mov_b32_e32 v214, 0x8040
	v_cndmask_b32_e64 v205, v205, 0, vcc
	v_cndmask_b32_e64 v214, 0, v214, vcc
	v_add_u32_e32 v205, v205, v207
	v_add_u32_e32 v214, v214, v207
	v_cndmask_b32_e32 v244, v248, v44, vcc
	v_cndmask_b32_e32 v245, v249, v45, vcc
	v_cndmask_b32_e32 v246, v250, v46, vcc
	v_cndmask_b32_e32 v247, v251, v47, vcc
	v_cndmask_b32_e32 v216, v220, v36, vcc
	v_cndmask_b32_e32 v217, v221, v37, vcc
	v_cndmask_b32_e32 v218, v222, v38, vcc
	v_cndmask_b32_e32 v219, v223, v39, vcc
	v_cndmask_b32_e32 v44, v44, v248, vcc
	v_cndmask_b32_e32 v45, v45, v249, vcc
	v_cndmask_b32_e32 v46, v46, v250, vcc
	v_cndmask_b32_e32 v47, v47, v251, vcc
	v_cndmask_b32_e32 v36, v36, v220, vcc
	v_cndmask_b32_e32 v37, v37, v221, vcc
	v_cndmask_b32_e32 v38, v38, v222, vcc
	v_cndmask_b32_e32 v39, v39, v223, vcc
	global_store_dwordx4 v205, v[244:247], s[92:93]
	global_store_dwordx4 v205, v[216:219], s[92:93] offset:512
	global_store_dwordx4 v214, v[44:47], s[92:93]
	global_store_dwordx4 v214, v[36:39], s[92:93] offset:512
	v_add_u32_e32 v207, 0x10000, v207
	v_add_u32_e32 v206, 0x10000, v206
	global_load_dwordx4 v[248:251], v206, s[82:83] offset:64
	global_load_dwordx4 v[220:223], v206, s[82:83] offset:576
	global_load_dwordx4 v[244:247], v206, s[82:83]
	global_load_dwordx4 v[216:219], v206, s[82:83] offset:512
	s_waitcnt lgkmcnt(0)
; DI u32x4 pack8(const float* v) { u32x4 w; w.x = pk2(v[0], v[1]); w.y = pk2(v[2], v[3]); w.z = pk2(v[4], v[5]); w.w = pk2(v[6], v[7]); return w; }
; #define xor16_32(s) xor16_32_l((s), fr + 16 * fq)
;     DI void operator()(AccRef acc, const Unit& u, int wr, int wc, int fr, int fq) const {
;     ...
;             for (int m = 0; m < 4; ++m) {
;                 const int row = rb + 16 * m;
;                 const float* xi = row < MP ? xin_p + (size_t)row * 1024 : xin_s + (size_t)(row - MP) * 1024;
;                 float s = 0.f;
; #pragma unroll
;                 for (int bj = 0; bj < 2; ++bj) {
;                     const int c = u.pn * 256 + bj * 128 + cl;
;                     float v[8];
; #pragma unroll
;                     for (int n = 0; n < 2; ++n) {
;                         const f32x4 x = *(const f32x4*)(xi + c + 4 * n);
;                         const f32x4 y = x + gt[bj][n] * acc[ai][bj][m][n];
;                         *(f32x4*)(xout + (size_t)row * 1024 + c + 4 * n) = y;
; #pragma unroll
;                         for (int j = 0; j < 4; ++j) { s += y[j] * y[j]; v[4 * n + j] = ap ? y[j] * gs[bj][n][j] : 0.f; }
;                     }
;                     if (ap) *(u32x4*)(ap + (size_t)row * 1024 + c) = pack8(v);
;                 }
;                 s = xor16_32(s);
;                 if (fq == 0) ssq[(size_t)row * 16 + u.pn * 4 + wc] = s;
	v_add_f32_e32 v211, v210, v211
	ds_bpermute_b32 v212, v202, v211
	v_add_u32_e32 v208, 0x8000, v208
	s_waitcnt lgkmcnt(0)
	v_add_f32_e32 v211, v211, v212
	s_mov_b64 exec, 0xffff
	global_store_dword v209, v211, s[90:91]
	s_mov_b64 exec, -1
	v_add_u32_e32 v209, 0x400, v209
	s_waitcnt vmcnt(12)
	v_permlane32_swap_b32_e32 v228, v232
	v_permlane32_swap_b32_e32 v229, v233
	v_permlane32_swap_b32_e32 v230, v234
	v_permlane32_swap_b32_e32 v231, v235
	v_permlane32_swap_b32_e32 v236, v240
	v_permlane32_swap_b32_e32 v237, v241
	v_permlane32_swap_b32_e32 v238, v242
	v_permlane32_swap_b32_e32 v239, v243
	v_permlane16_swap_b32_e32 v228, v232
	v_permlane16_swap_b32_e32 v229, v233
	v_permlane16_swap_b32_e32 v230, v234
	v_permlane16_swap_b32_e32 v231, v235
	v_permlane16_swap_b32_e32 v236, v240
	v_permlane16_swap_b32_e32 v237, v241
	v_permlane16_swap_b32_e32 v238, v242
	v_permlane16_swap_b32_e32 v239, v243
	v_pk_fma_f32 v[28:29], v[28:29], v[76:77], v[228:229]
	v_pk_fma_f32 v[30:31], v[30:31], v[78:79], v[230:231]
	v_mul_f32_e32 v210, v29, v29
	v_fmac_f32_e32 v210, v28, v28
	v_fmac_f32_e32 v210, v30, v30
	v_fmac_f32_e32 v210, v31, v31
	v_pk_mul_f32 v[228:229], v[100:101], v[28:29]
	v_pk_mul_f32 v[230:231], v[102:103], v[30:31]
	v_pk_fma_f32 v[24:25], v[24:25], v[72:73], v[232:233]
	v_pk_fma_f32 v[26:27], v[26:27], v[74:75], v[234:235]
	v_fmac_f32_e32 v210, v24, v24
	v_fmac_f32_e32 v210, v25, v25
	v_fmac_f32_e32 v210, v26, v26
	v_fmac_f32_e32 v210, v27, v27
	v_pk_mul_f32 v[232:233], v[98:99], v[24:25]
	v_pk_mul_f32 v[234:235], v[96:97], v[26:27]
	v_cvt_pk_bf16_f32 v228, v228, v229
	v_cvt_pk_bf16_f32 v229, v230, v231
	v_cvt_pk_bf16_f32 v230, v232, v233
	v_cvt_pk_bf16_f32 v231, v234, v235
	global_store_dwordx4 v208, v[228:231], s[58:59]
	v_pk_fma_f32 v[20:21], v[20:21], v[68:69], v[236:237]
	v_pk_fma_f32 v[22:23], v[22:23], v[70:71], v[238:239]
	v_fmac_f32_e32 v210, v20, v20
	v_fmac_f32_e32 v210, v21, v21
	v_fmac_f32_e32 v210, v22, v22
	v_fmac_f32_e32 v210, v23, v23
	v_pk_mul_f32 v[236:237], v[86:87], v[20:21]
	v_pk_mul_f32 v[238:239], v[84:85], v[22:23]
	v_pk_fma_f32 v[16:17], v[16:17], v[64:65], v[240:241]
	v_pk_fma_f32 v[18:19], v[18:19], v[66:67], v[242:243]
	v_fmac_f32_e32 v210, v16, v16
	v_fmac_f32_e32 v210, v17, v17
	v_fmac_f32_e32 v210, v18, v18
	v_fmac_f32_e32 v210, v19, v19
	v_pk_mul_f32 v[240:241], v[80:81], v[16:17]
	v_pk_mul_f32 v[242:243], v[82:83], v[18:19]
	v_cvt_pk_bf16_f32 v236, v236, v237
	v_cvt_pk_bf16_f32 v237, v238, v239
	v_cvt_pk_bf16_f32 v238, v240, v241
	v_cvt_pk_bf16_f32 v239, v242, v243
	global_store_dwordx4 v208, v[236:239], s[58:59] offset:256
	ds_bpermute_b32 v211, v203, v210
	v_permlane16_swap_b32_e32 v28, v24
	v_permlane16_swap_b32_e32 v29, v25
	v_permlane16_swap_b32_e32 v30, v26
	v_permlane16_swap_b32_e32 v31, v27
	v_permlane16_swap_b32_e32 v20, v16
	v_permlane16_swap_b32_e32 v21, v17
	v_permlane16_swap_b32_e32 v22, v18
	v_permlane16_swap_b32_e32 v23, v19
	v_permlane32_swap_b32_e32 v28, v24
	v_permlane32_swap_b32_e32 v29, v25
	v_permlane32_swap_b32_e32 v30, v26
	v_permlane32_swap_b32_e32 v31, v27
	v_permlane32_swap_b32_e32 v20, v16
	v_permlane32_swap_b32_e32 v21, v17
	v_permlane32_swap_b32_e32 v22, v18
	v_permlane32_swap_b32_e32 v23, v19
	s_nop 1
	v_mov_b32_dpp v232, v24 row_ror:8 row_mask:0xf bank_mask:0xf
	v_mov_b32_dpp v233, v25 row_ror:8 row_mask:0xf bank_mask:0xf
	v_mov_b32_dpp v234, v26 row_ror:8 row_mask:0xf bank_mask:0xf
	v_mov_b32_dpp v235, v27 row_ror:8 row_mask:0xf bank_mask:0xf
	v_mov_b32_dpp v240, v16 row_ror:8 row_mask:0xf bank_mask:0xf
	v_mov_b32_dpp v241, v17 row_ror:8 row_mask:0xf bank_mask:0xf
	v_mov_b32_dpp v242, v18 row_ror:8 row_mask:0xf bank_mask:0xf
	v_mov_b32_dpp v243, v19 row_ror:8 row_mask:0xf bank_mask:0xf
	s_mov_b32 vcc_lo, 0xff00ff
	s_mov_b32 vcc_hi, 0xff00ff
	v_mov_b32_e32 v205, 0xffff8040
	v_mov_b32_e32 v214, 0x8040
	v_cndmask_b32_e64 v205, v205, 0, vcc
	v_cndmask_b32_e64 v214, 0, v214, vcc
	v_add_u32_e32 v205, v205, v207
	v_add_u32_e32 v214, v214, v207
	v_cndmask_b32_e32 v228, v232, v28, vcc
	v_cndmask_b32_e32 v229, v233, v29, vcc
	v_cndmask_b32_e32 v230, v234, v30, vcc
	v_cndmask_b32_e32 v231, v235, v31, vcc
	v_cndmask_b32_e32 v236, v240, v20, vcc
	v_cndmask_b32_e32 v237, v241, v21, vcc
	v_cndmask_b32_e32 v238, v242, v22, vcc
	v_cndmask_b32_e32 v239, v243, v23, vcc
	v_cndmask_b32_e32 v28, v28, v232, vcc
	v_cndmask_b32_e32 v29, v29, v233, vcc
	v_cndmask_b32_e32 v30, v30, v234, vcc
	v_cndmask_b32_e32 v31, v31, v235, vcc
	v_cndmask_b32_e32 v20, v20, v240, vcc
	v_cndmask_b32_e32 v21, v21, v241, vcc
	v_cndmask_b32_e32 v22, v22, v242, vcc
	v_cndmask_b32_e32 v23, v23, v243, vcc
	global_store_dwordx4 v205, v[228:231], s[92:93]
	global_store_dwordx4 v205, v[236:239], s[92:93] offset:512
	global_store_dwordx4 v214, v[28:31], s[92:93]
	global_store_dwordx4 v214, v[20:23], s[92:93] offset:512
	v_add_u32_e32 v207, 0x10000, v207
	s_waitcnt lgkmcnt(0)
	v_add_f32_e32 v211, v210, v211
	ds_bpermute_b32 v212, v202, v211
	v_add_u32_e32 v208, 0x8000, v208
	s_waitcnt lgkmcnt(0)
; DI u32x4 pack8(const float* v) { u32x4 w; w.x = pk2(v[0], v[1]); w.y = pk2(v[2], v[3]); w.z = pk2(v[4], v[5]); w.w = pk2(v[6], v[7]); return w; }
; #define xor16_32(s) xor16_32_l((s), fr + 16 * fq)
;     DI void operator()(AccRef acc, const Unit& u, int wr, int wc, int fr, int fq) const {
;     ...
;             for (int m = 0; m < 4; ++m) {
;                 const int row = rb + 16 * m;
;                 const float* xi = row < MP ? xin_p + (size_t)row * 1024 : xin_s + (size_t)(row - MP) * 1024;
;                 float s = 0.f;
; #pragma unroll
;                 for (int bj = 0; bj < 2; ++bj) {
;                     const int c = u.pn * 256 + bj * 128 + cl;
;                     float v[8];
; #pragma unroll
;                     for (int n = 0; n < 2; ++n) {
;                         const f32x4 x = *(const f32x4*)(xi + c + 4 * n);
;                         const f32x4 y = x + gt[bj][n] * acc[ai][bj][m][n];
;                         *(f32x4*)(xout + (size_t)row * 1024 + c + 4 * n) = y;
; #pragma unroll
;                         for (int j = 0; j < 4; ++j) { s += y[j] * y[j]; v[4 * n + j] = ap ? y[j] * gs[bj][n][j] : 0.f; }
;                     }
;                     if (ap) *(u32x4*)(ap + (size_t)row * 1024 + c) = pack8(v);
;                 }
;                 s = xor16_32(s);
;                 if (fq == 0) ssq[(size_t)row * 16 + u.pn * 4 + wc] = s;
	v_add_f32_e32 v211, v211, v212
	s_mov_b64 exec, 0xffff
	global_store_dword v209, v211, s[90:91]
	s_mov_b64 exec, -1
	v_add_u32_e32 v209, 0x400, v209
	s_waitcnt vmcnt(8)
	v_permlane32_swap_b32_e32 v244, v248
	v_permlane32_swap_b32_e32 v245, v249
	v_permlane32_swap_b32_e32 v246, v250
	v_permlane32_swap_b32_e32 v247, v251
	v_permlane32_swap_b32_e32 v216, v220
	v_permlane32_swap_b32_e32 v217, v221
	v_permlane32_swap_b32_e32 v218, v222
	v_permlane32_swap_b32_e32 v219, v223
	v_permlane16_swap_b32_e32 v244, v248
	v_permlane16_swap_b32_e32 v245, v249
	v_permlane16_swap_b32_e32 v246, v250
	v_permlane16_swap_b32_e32 v247, v251
	v_permlane16_swap_b32_e32 v216, v220
	v_permlane16_swap_b32_e32 v217, v221
	v_permlane16_swap_b32_e32 v218, v222
	v_permlane16_swap_b32_e32 v219, v223
	v_pk_fma_f32 v[12:13], v[12:13], v[76:77], v[244:245]
	v_pk_fma_f32 v[14:15], v[14:15], v[78:79], v[246:247]
	v_mul_f32_e32 v210, v13, v13
	v_fmac_f32_e32 v210, v12, v12
	v_fmac_f32_e32 v210, v14, v14
	v_fmac_f32_e32 v210, v15, v15
	v_pk_mul_f32 v[244:245], v[100:101], v[12:13]
	v_pk_mul_f32 v[246:247], v[102:103], v[14:15]
	v_pk_fma_f32 v[8:9], v[8:9], v[72:73], v[248:249]
	v_pk_fma_f32 v[10:11], v[10:11], v[74:75], v[250:251]
	v_fmac_f32_e32 v210, v8, v8
	v_fmac_f32_e32 v210, v9, v9
	v_fmac_f32_e32 v210, v10, v10
	v_fmac_f32_e32 v210, v11, v11
	v_pk_mul_f32 v[248:249], v[98:99], v[8:9]
	v_pk_mul_f32 v[250:251], v[96:97], v[10:11]
	v_cvt_pk_bf16_f32 v244, v244, v245
	v_cvt_pk_bf16_f32 v245, v246, v247
	v_cvt_pk_bf16_f32 v246, v248, v249
	v_cvt_pk_bf16_f32 v247, v250, v251
	global_store_dwordx4 v208, v[244:247], s[58:59]
	v_pk_fma_f32 v[4:5], v[4:5], v[68:69], v[216:217]
	v_pk_fma_f32 v[6:7], v[6:7], v[70:71], v[218:219]
	v_fmac_f32_e32 v210, v4, v4
	v_fmac_f32_e32 v210, v5, v5
	v_fmac_f32_e32 v210, v6, v6
	v_fmac_f32_e32 v210, v7, v7
	v_pk_mul_f32 v[216:217], v[86:87], v[4:5]
	v_pk_mul_f32 v[218:219], v[84:85], v[6:7]
	v_pk_fma_f32 v[0:1], v[0:1], v[64:65], v[220:221]
	v_pk_fma_f32 v[2:3], v[2:3], v[66:67], v[222:223]
	v_fmac_f32_e32 v210, v0, v0
	v_fmac_f32_e32 v210, v1, v1
	v_fmac_f32_e32 v210, v2, v2
	v_fmac_f32_e32 v210, v3, v3
	v_pk_mul_f32 v[220:221], v[80:81], v[0:1]
	v_pk_mul_f32 v[222:223], v[82:83], v[2:3]
	v_cvt_pk_bf16_f32 v216, v216, v217
	v_cvt_pk_bf16_f32 v217, v218, v219
	v_cvt_pk_bf16_f32 v218, v220, v221
	v_cvt_pk_bf16_f32 v219, v222, v223
	global_store_dwordx4 v208, v[216:219], s[58:59] offset:256
	ds_bpermute_b32 v211, v203, v210
	v_permlane16_swap_b32_e32 v12, v8
	v_permlane16_swap_b32_e32 v13, v9
	v_permlane16_swap_b32_e32 v14, v10
	v_permlane16_swap_b32_e32 v15, v11
	v_permlane16_swap_b32_e32 v4, v0
	v_permlane16_swap_b32_e32 v5, v1
	v_permlane16_swap_b32_e32 v6, v2
	v_permlane16_swap_b32_e32 v7, v3
	v_permlane32_swap_b32_e32 v12, v8
	v_permlane32_swap_b32_e32 v13, v9
	v_permlane32_swap_b32_e32 v14, v10
	v_permlane32_swap_b32_e32 v15, v11
	v_permlane32_swap_b32_e32 v4, v0
	v_permlane32_swap_b32_e32 v5, v1
	v_permlane32_swap_b32_e32 v6, v2
	v_permlane32_swap_b32_e32 v7, v3
	s_nop 1
	v_mov_b32_dpp v248, v8 row_ror:8 row_mask:0xf bank_mask:0xf
	v_mov_b32_dpp v249, v9 row_ror:8 row_mask:0xf bank_mask:0xf
	v_mov_b32_dpp v250, v10 row_ror:8 row_mask:0xf bank_mask:0xf
	v_mov_b32_dpp v251, v11 row_ror:8 row_mask:0xf bank_mask:0xf
	v_mov_b32_dpp v220, v0 row_ror:8 row_mask:0xf bank_mask:0xf
	v_mov_b32_dpp v221, v1 row_ror:8 row_mask:0xf bank_mask:0xf
	v_mov_b32_dpp v222, v2 row_ror:8 row_mask:0xf bank_mask:0xf
	v_mov_b32_dpp v223, v3 row_ror:8 row_mask:0xf bank_mask:0xf
	s_mov_b32 vcc_lo, 0xff00ff
	s_mov_b32 vcc_hi, 0xff00ff
	v_mov_b32_e32 v205, 0xffff8040
	v_mov_b32_e32 v214, 0x8040
	v_cndmask_b32_e64 v205, v205, 0, vcc
	v_cndmask_b32_e64 v214, 0, v214, vcc
	v_add_u32_e32 v205, v205, v207
	v_add_u32_e32 v214, v214, v207
	v_cndmask_b32_e32 v244, v248, v12, vcc
	v_cndmask_b32_e32 v245, v249, v13, vcc
	v_cndmask_b32_e32 v246, v250, v14, vcc
	v_cndmask_b32_e32 v247, v251, v15, vcc
	v_cndmask_b32_e32 v216, v220, v4, vcc
	v_cndmask_b32_e32 v217, v221, v5, vcc
	v_cndmask_b32_e32 v218, v222, v6, vcc
	v_cndmask_b32_e32 v219, v223, v7, vcc
	v_cndmask_b32_e32 v12, v12, v248, vcc
	v_cndmask_b32_e32 v13, v13, v249, vcc
	v_cndmask_b32_e32 v14, v14, v250, vcc
	v_cndmask_b32_e32 v15, v15, v251, vcc
	v_cndmask_b32_e32 v4, v4, v220, vcc
	v_cndmask_b32_e32 v5, v5, v221, vcc
	v_cndmask_b32_e32 v6, v6, v222, vcc
	v_cndmask_b32_e32 v7, v7, v223, vcc
	global_store_dwordx4 v205, v[244:247], s[92:93]
	global_store_dwordx4 v205, v[216:219], s[92:93] offset:512
	global_store_dwordx4 v214, v[12:15], s[92:93]
	global_store_dwordx4 v214, v[4:7], s[92:93] offset:512
	s_waitcnt lgkmcnt(0)
	v_add_f32_e32 v211, v210, v211
	ds_bpermute_b32 v212, v202, v211
	s_waitcnt lgkmcnt(0)
	v_add_f32_e32 v211, v211, v212
	s_mov_b64 exec, 0xffff
	global_store_dword v209, v211, s[90:91]
	s_mov_b64 exec, -1
	s_andn2_b64 vcc, exec, s[8:9]
	s_mov_b64 s[0:1], -1
	s_cbranch_vccnz .LBB0_1292
	s_andn2_b64 vcc, exec, s[2:3]
	s_cbranch_vccnz .LBB0_1291
	s_barrier
	s_branch .LBB0_1291

; DI u32x4 pack8(const float* v) { u32x4 w; w.x = pk2(v[0], v[1]); w.y = pk2(v[2], v[3]); w.z = pk2(v[4], v[5]); w.w = pk2(v[6], v[7]); return w; }
; #define xor16_32(s) xor16_32_l((s), fr + 16 * fq)
;     DI void operator()(AccRef acc, const Unit& u, int wr, int wc, int fr, int fq) const {
;     ...
;             for (int m = 0; m < 4; ++m) {
;                 const int row = rb + 16 * m;
;                 const float* xi = row < MP ? xin_p + (size_t)row * 1024 : xin_s + (size_t)(row - MP) * 1024;
;                 float s = 0.f;
; #pragma unroll
;                 for (int bj = 0; bj < 2; ++bj) {
;                     const int c = u.pn * 256 + bj * 128 + cl;
;                     float v[8];
; #pragma unroll
;                     for (int n = 0; n < 2; ++n) {
;                         const f32x4 x = *(const f32x4*)(xi + c + 4 * n);
;                         const f32x4 y = x + gt[bj][n] * acc[ai][bj][m][n];
;                         *(f32x4*)(xout + (size_t)row * 1024 + c + 4 * n) = y;
; #pragma unroll
;                         for (int j = 0; j < 4; ++j) { s += y[j] * y[j]; v[4 * n + j] = ap ? y[j] * gs[bj][n][j] : 0.f; }
;                     }
;                     if (ap) *(u32x4*)(ap + (size_t)row * 1024 + c) = pack8(v);
;                 }
;                 s = xor16_32(s);
;                 if (fq == 0) ssq[(size_t)row * 16 + u.pn * 4 + wc] = s;
.Lnoap_C_1:
	ds_bpermute_b32 v211, v214, v210
	v_permlane16_swap_b32_e32 v140, v136
	v_permlane16_swap_b32_e32 v141, v137
	v_permlane16_swap_b32_e32 v142, v138
	v_permlane16_swap_b32_e32 v143, v139
	v_permlane16_swap_b32_e32 v132, v128
	v_permlane16_swap_b32_e32 v133, v129
	v_permlane16_swap_b32_e32 v134, v130
	v_permlane16_swap_b32_e32 v135, v131
	v_permlane32_swap_b32_e32 v140, v136
	v_permlane32_swap_b32_e32 v141, v137
	v_permlane32_swap_b32_e32 v142, v138
	v_permlane32_swap_b32_e32 v143, v139
	v_permlane32_swap_b32_e32 v132, v128
	v_permlane32_swap_b32_e32 v133, v129
	v_permlane32_swap_b32_e32 v134, v130
	v_permlane32_swap_b32_e32 v135, v131
	s_nop 1
	v_mov_b32_dpp v232, v136 row_ror:8 row_mask:0xf bank_mask:0xf
	v_mov_b32_dpp v233, v137 row_ror:8 row_mask:0xf bank_mask:0xf
	v_mov_b32_dpp v234, v138 row_ror:8 row_mask:0xf bank_mask:0xf
	v_mov_b32_dpp v235, v139 row_ror:8 row_mask:0xf bank_mask:0xf
	v_mov_b32_dpp v240, v128 row_ror:8 row_mask:0xf bank_mask:0xf
	v_mov_b32_dpp v241, v129 row_ror:8 row_mask:0xf bank_mask:0xf
	v_mov_b32_dpp v242, v130 row_ror:8 row_mask:0xf bank_mask:0xf
	v_mov_b32_dpp v243, v131 row_ror:8 row_mask:0xf bank_mask:0xf
	s_mov_b32 vcc_lo, 0xff00ff
	s_mov_b32 vcc_hi, 0xff00ff
	v_mov_b32_e32 v204, 0xffff8040
	v_mov_b32_e32 v205, 0x8040
	v_cndmask_b32_e64 v204, v204, 0, vcc
	v_cndmask_b32_e64 v205, 0, v205, vcc
	v_add_u32_e32 v204, v204, v207
	v_add_u32_e32 v205, v205, v207
	v_cndmask_b32_e32 v228, v232, v140, vcc
	v_cndmask_b32_e32 v229, v233, v141, vcc
	v_cndmask_b32_e32 v230, v234, v142, vcc
	v_cndmask_b32_e32 v231, v235, v143, vcc
	v_cndmask_b32_e32 v236, v240, v132, vcc
	v_cndmask_b32_e32 v237, v241, v133, vcc
	v_cndmask_b32_e32 v238, v242, v134, vcc
	v_cndmask_b32_e32 v239, v243, v135, vcc
	v_cndmask_b32_e32 v140, v140, v232, vcc
	v_cndmask_b32_e32 v141, v141, v233, vcc
	v_cndmask_b32_e32 v142, v142, v234, vcc
	v_cndmask_b32_e32 v143, v143, v235, vcc
	v_cndmask_b32_e32 v132, v132, v240, vcc
	v_cndmask_b32_e32 v133, v133, v241, vcc
	v_cndmask_b32_e32 v134, v134, v242, vcc
	v_cndmask_b32_e32 v135, v135, v243, vcc
	global_store_dwordx4 v204, v[228:231], s[8:9]
	global_store_dwordx4 v204, v[236:239], s[8:9] offset:512
	global_store_dwordx4 v205, v[140:143], s[8:9]
	global_store_dwordx4 v205, v[132:135], s[8:9] offset:512
	v_add_u32_e32 v207, 0x10000, v207
	global_load_dwordx4 v[232:235], v206, s[70:71] offset:64
	global_load_dwordx4 v[240:243], v206, s[70:71] offset:576
	global_load_dwordx4 v[228:231], v206, s[70:71]
	global_load_dwordx4 v[236:239], v206, s[70:71] offset:512
	s_waitcnt lgkmcnt(0)
	v_add_f32_e32 v211, v210, v211
	ds_bpermute_b32 v212, v215, v211
	v_add_u32_e32 v208, 0x8000, v208
	s_waitcnt lgkmcnt(0)
	v_add_f32_e32 v211, v211, v212
	s_mov_b64 exec, 0xffff
	global_store_dword v209, v211, s[72:73]
	s_mov_b64 exec, -1
	v_add_u32_e32 v209, 0x400, v209
	s_waitcnt vmcnt(9)
	v_permlane32_swap_b32_e32 v244, v248
	v_permlane32_swap_b32_e32 v245, v249
	v_permlane32_swap_b32_e32 v246, v250
	v_permlane32_swap_b32_e32 v247, v251
	v_permlane32_swap_b32_e32 v216, v220
	v_permlane32_swap_b32_e32 v217, v221
	v_permlane32_swap_b32_e32 v218, v222
	v_permlane32_swap_b32_e32 v219, v223
	v_permlane16_swap_b32_e32 v244, v248
	v_permlane16_swap_b32_e32 v245, v249
	v_permlane16_swap_b32_e32 v246, v250
	v_permlane16_swap_b32_e32 v247, v251
	v_permlane16_swap_b32_e32 v216, v220
	v_permlane16_swap_b32_e32 v217, v221
	v_permlane16_swap_b32_e32 v218, v222
	v_permlane16_swap_b32_e32 v219, v223
	v_pk_fma_f32 v[124:125], v[124:125], v[144:145], v[244:245]
	v_pk_fma_f32 v[126:127], v[126:127], v[146:147], v[246:247]
	v_mul_f32_e32 v210, v125, v125
	v_fmac_f32_e32 v210, v124, v124
	v_fmac_f32_e32 v210, v126, v126
	v_fmac_f32_e32 v210, v127, v127
	v_pk_fma_f32 v[120:121], v[120:121], v[152:153], v[248:249]
	v_pk_fma_f32 v[122:123], v[122:123], v[154:155], v[250:251]
	v_fmac_f32_e32 v210, v120, v120
	v_fmac_f32_e32 v210, v121, v121
	v_fmac_f32_e32 v210, v122, v122
	v_fmac_f32_e32 v210, v123, v123
	v_pk_fma_f32 v[116:117], v[116:117], v[148:149], v[216:217]
	v_pk_fma_f32 v[118:119], v[118:119], v[150:151], v[218:219]
	v_fmac_f32_e32 v210, v116, v116
	v_fmac_f32_e32 v210, v117, v117
	v_fmac_f32_e32 v210, v118, v118
	v_fmac_f32_e32 v210, v119, v119
	v_pk_fma_f32 v[112:113], v[112:113], v[156:157], v[220:221]
	v_pk_fma_f32 v[114:115], v[114:115], v[158:159], v[222:223]
	v_fmac_f32_e32 v210, v112, v112
	v_fmac_f32_e32 v210, v113, v113
	v_fmac_f32_e32 v210, v114, v114
	v_fmac_f32_e32 v210, v115, v115
	s_cmp_lg_u64 s[2:3], 0
	s_cbranch_scc1 .Lnoap_C_2
	v_pk_mul_f32 v[244:245], v[64:65], v[124:125]
	v_pk_mul_f32 v[246:247], v[66:67], v[126:127]
	v_pk_mul_f32 v[248:249], v[72:73], v[120:121]
	v_pk_mul_f32 v[250:251], v[74:75], v[122:123]
	v_pk_mul_f32 v[216:217], v[68:69], v[116:117]
	v_pk_mul_f32 v[218:219], v[70:71], v[118:119]
	v_pk_mul_f32 v[220:221], v[76:77], v[112:113]
	v_pk_mul_f32 v[222:223], v[78:79], v[114:115]
	v_cvt_pk_bf16_f32 v244, v244, v245
	v_cvt_pk_bf16_f32 v245, v246, v247
	v_cvt_pk_bf16_f32 v246, v248, v249
	v_cvt_pk_bf16_f32 v247, v250, v251
	global_store_dwordx4 v208, v[244:247], s[42:43]
	v_cvt_pk_bf16_f32 v216, v216, v217
	v_cvt_pk_bf16_f32 v217, v218, v219
	v_cvt_pk_bf16_f32 v218, v220, v221
	v_cvt_pk_bf16_f32 v219, v222, v223
	global_store_dwordx4 v208, v[216:219], s[42:43] offset:256
; DI u32x4 pack8(const float* v) { u32x4 w; w.x = pk2(v[0], v[1]); w.y = pk2(v[2], v[3]); w.z = pk2(v[4], v[5]); w.w = pk2(v[6], v[7]); return w; }
; #define xor16_32(s) xor16_32_l((s), fr + 16 * fq)
;     DI void operator()(AccRef acc, const Unit& u, int wr, int wc, int fr, int fq) const {
;     ...
;             for (int m = 0; m < 4; ++m) {
;                 const int row = rb + 16 * m;
;                 const float* xi = row < MP ? xin_p + (size_t)row * 1024 : xin_s + (size_t)(row - MP) * 1024;
;                 float s = 0.f;
; #pragma unroll
;                 for (int bj = 0; bj < 2; ++bj) {
;                     const int c = u.pn * 256 + bj * 128 + cl;
;                     float v[8];
; #pragma unroll
;                     for (int n = 0; n < 2; ++n) {
;                         const f32x4 x = *(const f32x4*)(xi + c + 4 * n);
;                         const f32x4 y = x + gt[bj][n] * acc[ai][bj][m][n];
;                         *(f32x4*)(xout + (size_t)row * 1024 + c + 4 * n) = y;
; #pragma unroll
;                         for (int j = 0; j < 4; ++j) { s += y[j] * y[j]; v[4 * n + j] = ap ? y[j] * gs[bj][n][j] : 0.f; }
;                     }
;                     if (ap) *(u32x4*)(ap + (size_t)row * 1024 + c) = pack8(v);
;                 }
;                 s = xor16_32(s);
;                 if (fq == 0) ssq[(size_t)row * 16 + u.pn * 4 + wc] = s;
.Lnoap_C_2:
	ds_bpermute_b32 v211, v214, v210
	v_permlane16_swap_b32_e32 v124, v120
	v_permlane16_swap_b32_e32 v125, v121
	v_permlane16_swap_b32_e32 v126, v122
	v_permlane16_swap_b32_e32 v127, v123
	v_permlane16_swap_b32_e32 v116, v112
	v_permlane16_swap_b32_e32 v117, v113
	v_permlane16_swap_b32_e32 v118, v114
	v_permlane16_swap_b32_e32 v119, v115
	v_permlane32_swap_b32_e32 v124, v120
	v_permlane32_swap_b32_e32 v125, v121
	v_permlane32_swap_b32_e32 v126, v122
	v_permlane32_swap_b32_e32 v127, v123
	v_permlane32_swap_b32_e32 v116, v112
	v_permlane32_swap_b32_e32 v117, v113
	v_permlane32_swap_b32_e32 v118, v114
	v_permlane32_swap_b32_e32 v119, v115
	s_nop 1
	v_mov_b32_dpp v248, v120 row_ror:8 row_mask:0xf bank_mask:0xf
	v_mov_b32_dpp v249, v121 row_ror:8 row_mask:0xf bank_mask:0xf
	v_mov_b32_dpp v250, v122 row_ror:8 row_mask:0xf bank_mask:0xf
	v_mov_b32_dpp v251, v123 row_ror:8 row_mask:0xf bank_mask:0xf
	v_mov_b32_dpp v220, v112 row_ror:8 row_mask:0xf bank_mask:0xf
	v_mov_b32_dpp v221, v113 row_ror:8 row_mask:0xf bank_mask:0xf
	v_mov_b32_dpp v222, v114 row_ror:8 row_mask:0xf bank_mask:0xf
	v_mov_b32_dpp v223, v115 row_ror:8 row_mask:0xf bank_mask:0xf
	s_mov_b32 vcc_lo, 0xff00ff
	s_mov_b32 vcc_hi, 0xff00ff
	v_mov_b32_e32 v204, 0xffff8040
	v_mov_b32_e32 v205, 0x8040
	v_cndmask_b32_e64 v204, v204, 0, vcc
	v_cndmask_b32_e64 v205, 0, v205, vcc
	v_add_u32_e32 v204, v204, v207
	v_add_u32_e32 v205, v205, v207
	v_cndmask_b32_e32 v244, v248, v124, vcc
	v_cndmask_b32_e32 v245, v249, v125, vcc
	v_cndmask_b32_e32 v246, v250, v126, vcc
	v_cndmask_b32_e32 v247, v251, v127, vcc
	v_cndmask_b32_e32 v216, v220, v116, vcc
	v_cndmask_b32_e32 v217, v221, v117, vcc
	v_cndmask_b32_e32 v218, v222, v118, vcc
	v_cndmask_b32_e32 v219, v223, v119, vcc
	v_cndmask_b32_e32 v124, v124, v248, vcc
	v_cndmask_b32_e32 v125, v125, v249, vcc
	v_cndmask_b32_e32 v126, v126, v250, vcc
	v_cndmask_b32_e32 v127, v127, v251, vcc
	v_cndmask_b32_e32 v116, v116, v220, vcc
	v_cndmask_b32_e32 v117, v117, v221, vcc
	v_cndmask_b32_e32 v118, v118, v222, vcc
	v_cndmask_b32_e32 v119, v119, v223, vcc
	global_store_dwordx4 v204, v[244:247], s[8:9]
	global_store_dwordx4 v204, v[216:219], s[8:9] offset:512
	global_store_dwordx4 v205, v[124:127], s[8:9]
	global_store_dwordx4 v205, v[116:119], s[8:9] offset:512
	v_add_u32_e32 v207, 0x10000, v207
	v_add_u32_e32 v206, 0x10000, v206
	global_load_dwordx4 v[248:251], v206, s[70:71] offset:64
	global_load_dwordx4 v[220:223], v206, s[70:71] offset:576
	global_load_dwordx4 v[244:247], v206, s[70:71]
	global_load_dwordx4 v[216:219], v206, s[70:71] offset:512
	s_waitcnt lgkmcnt(0)
	v_add_f32_e32 v211, v210, v211
	ds_bpermute_b32 v212, v215, v211
	v_add_u32_e32 v208, 0x8000, v208
	s_waitcnt lgkmcnt(0)
	v_add_f32_e32 v211, v211, v212
	s_mov_b64 exec, 0xffff
	global_store_dword v209, v211, s[72:73]
	s_mov_b64 exec, -1
	v_add_u32_e32 v209, 0x400, v209
	s_waitcnt vmcnt(10)
	v_permlane32_swap_b32_e32 v228, v232
	v_permlane32_swap_b32_e32 v229, v233
	v_permlane32_swap_b32_e32 v230, v234
	v_permlane32_swap_b32_e32 v231, v235
	v_permlane32_swap_b32_e32 v236, v240
	v_permlane32_swap_b32_e32 v237, v241
	v_permlane32_swap_b32_e32 v238, v242
	v_permlane32_swap_b32_e32 v239, v243
	v_permlane16_swap_b32_e32 v228, v232
	v_permlane16_swap_b32_e32 v229, v233
	v_permlane16_swap_b32_e32 v230, v234
	v_permlane16_swap_b32_e32 v231, v235
	v_permlane16_swap_b32_e32 v236, v240
	v_permlane16_swap_b32_e32 v237, v241
	v_permlane16_swap_b32_e32 v238, v242
	v_permlane16_swap_b32_e32 v239, v243
	v_pk_fma_f32 v[108:109], v[108:109], v[144:145], v[228:229]
	v_pk_fma_f32 v[110:111], v[110:111], v[146:147], v[230:231]
	v_mul_f32_e32 v210, v109, v109
	v_fmac_f32_e32 v210, v108, v108
	v_fmac_f32_e32 v210, v110, v110
	v_fmac_f32_e32 v210, v111, v111
	v_pk_fma_f32 v[104:105], v[104:105], v[152:153], v[232:233]
	v_pk_fma_f32 v[106:107], v[106:107], v[154:155], v[234:235]
	v_fmac_f32_e32 v210, v104, v104
	v_fmac_f32_e32 v210, v105, v105
	v_fmac_f32_e32 v210, v106, v106
	v_fmac_f32_e32 v210, v107, v107
	v_pk_fma_f32 v[100:101], v[100:101], v[148:149], v[236:237]
	v_pk_fma_f32 v[102:103], v[102:103], v[150:151], v[238:239]
	v_fmac_f32_e32 v210, v100, v100
	v_fmac_f32_e32 v210, v101, v101
	v_fmac_f32_e32 v210, v102, v102
	v_fmac_f32_e32 v210, v103, v103
	v_pk_fma_f32 v[96:97], v[96:97], v[156:157], v[240:241]
	v_pk_fma_f32 v[98:99], v[98:99], v[158:159], v[242:243]
	v_fmac_f32_e32 v210, v96, v96
	v_fmac_f32_e32 v210, v97, v97
	v_fmac_f32_e32 v210, v98, v98
	v_fmac_f32_e32 v210, v99, v99
	s_cmp_lg_u64 s[2:3], 0
	s_cbranch_scc1 .Lnoap_C_3
	v_pk_mul_f32 v[228:229], v[64:65], v[108:109]
	v_pk_mul_f32 v[230:231], v[66:67], v[110:111]
	v_pk_mul_f32 v[232:233], v[72:73], v[104:105]
	v_pk_mul_f32 v[234:235], v[74:75], v[106:107]
	v_pk_mul_f32 v[236:237], v[68:69], v[100:101]
	v_pk_mul_f32 v[238:239], v[70:71], v[102:103]
	v_pk_mul_f32 v[240:241], v[76:77], v[96:97]
	v_pk_mul_f32 v[242:243], v[78:79], v[98:99]
	v_cvt_pk_bf16_f32 v228, v228, v229
	v_cvt_pk_bf16_f32 v229, v230, v231
	v_cvt_pk_bf16_f32 v230, v232, v233
	v_cvt_pk_bf16_f32 v231, v234, v235
	global_store_dwordx4 v208, v[228:231], s[42:43]
	v_cvt_pk_bf16_f32 v236, v236, v237
	v_cvt_pk_bf16_f32 v237, v238, v239
	v_cvt_pk_bf16_f32 v238, v240, v241
	v_cvt_pk_bf16_f32 v239, v242, v243
	global_store_dwordx4 v208, v[236:239], s[42:43] offset:256
; DI u32x4 pack8(const float* v) { u32x4 w; w.x = pk2(v[0], v[1]); w.y = pk2(v[2], v[3]); w.z = pk2(v[4], v[5]); w.w = pk2(v[6], v[7]); return w; }
; #define xor16_32(s) xor16_32_l((s), fr + 16 * fq)
;     DI void operator()(AccRef acc, const Unit& u, int wr, int wc, int fr, int fq) const {
;     ...
;             for (int m = 0; m < 4; ++m) {
;                 const int row = rb + 16 * m;
;                 const float* xi = row < MP ? xin_p + (size_t)row * 1024 : xin_s + (size_t)(row - MP) * 1024;
;                 float s = 0.f;
; #pragma unroll
;                 for (int bj = 0; bj < 2; ++bj) {
;                     const int c = u.pn * 256 + bj * 128 + cl;
;                     float v[8];
; #pragma unroll
;                     for (int n = 0; n < 2; ++n) {
;                         const f32x4 x = *(const f32x4*)(xi + c + 4 * n);
;                         const f32x4 y = x + gt[bj][n] * acc[ai][bj][m][n];
;                         *(f32x4*)(xout + (size_t)row * 1024 + c + 4 * n) = y;
; #pragma unroll
;                         for (int j = 0; j < 4; ++j) { s += y[j] * y[j]; v[4 * n + j] = ap ? y[j] * gs[bj][n][j] : 0.f; }
;                     }
;                     if (ap) *(u32x4*)(ap + (size_t)row * 1024 + c) = pack8(v);
;                 }
;                 s = xor16_32(s);
;                 if (fq == 0) ssq[(size_t)row * 16 + u.pn * 4 + wc] = s;
.Lnoap_C_3:
	ds_bpermute_b32 v211, v214, v210
	v_permlane16_swap_b32_e32 v108, v104
	v_permlane16_swap_b32_e32 v109, v105
	v_permlane16_swap_b32_e32 v110, v106
	v_permlane16_swap_b32_e32 v111, v107
	v_permlane16_swap_b32_e32 v100, v96
	v_permlane16_swap_b32_e32 v101, v97
	v_permlane16_swap_b32_e32 v102, v98
	v_permlane16_swap_b32_e32 v103, v99
	v_permlane32_swap_b32_e32 v108, v104
	v_permlane32_swap_b32_e32 v109, v105
	v_permlane32_swap_b32_e32 v110, v106
	v_permlane32_swap_b32_e32 v111, v107
	v_permlane32_swap_b32_e32 v100, v96
	v_permlane32_swap_b32_e32 v101, v97
	v_permlane32_swap_b32_e32 v102, v98
	v_permlane32_swap_b32_e32 v103, v99
	s_nop 1
	v_mov_b32_dpp v232, v104 row_ror:8 row_mask:0xf bank_mask:0xf
	v_mov_b32_dpp v233, v105 row_ror:8 row_mask:0xf bank_mask:0xf
	v_mov_b32_dpp v234, v106 row_ror:8 row_mask:0xf bank_mask:0xf
	v_mov_b32_dpp v235, v107 row_ror:8 row_mask:0xf bank_mask:0xf
	v_mov_b32_dpp v240, v96 row_ror:8 row_mask:0xf bank_mask:0xf
	v_mov_b32_dpp v241, v97 row_ror:8 row_mask:0xf bank_mask:0xf
	v_mov_b32_dpp v242, v98 row_ror:8 row_mask:0xf bank_mask:0xf
	v_mov_b32_dpp v243, v99 row_ror:8 row_mask:0xf bank_mask:0xf
	s_mov_b32 vcc_lo, 0xff00ff
	s_mov_b32 vcc_hi, 0xff00ff
	v_mov_b32_e32 v204, 0xffff8040
	v_mov_b32_e32 v205, 0x8040
	v_cndmask_b32_e64 v204, v204, 0, vcc
	v_cndmask_b32_e64 v205, 0, v205, vcc
	v_add_u32_e32 v204, v204, v207
	v_add_u32_e32 v205, v205, v207
	v_cndmask_b32_e32 v228, v232, v108, vcc
	v_cndmask_b32_e32 v229, v233, v109, vcc
	v_cndmask_b32_e32 v230, v234, v110, vcc
	v_cndmask_b32_e32 v231, v235, v111, vcc
	v_cndmask_b32_e32 v236, v240, v100, vcc
	v_cndmask_b32_e32 v237, v241, v101, vcc
	v_cndmask_b32_e32 v238, v242, v102, vcc
	v_cndmask_b32_e32 v239, v243, v103, vcc
	v_cndmask_b32_e32 v108, v108, v232, vcc
	v_cndmask_b32_e32 v109, v109, v233, vcc
	v_cndmask_b32_e32 v110, v110, v234, vcc
	v_cndmask_b32_e32 v111, v111, v235, vcc
	v_cndmask_b32_e32 v100, v100, v240, vcc
	v_cndmask_b32_e32 v101, v101, v241, vcc
	v_cndmask_b32_e32 v102, v102, v242, vcc
	v_cndmask_b32_e32 v103, v103, v243, vcc
	global_store_dwordx4 v204, v[228:231], s[8:9]
	global_store_dwordx4 v204, v[236:239], s[8:9] offset:512
	global_store_dwordx4 v205, v[108:111], s[8:9]
	global_store_dwordx4 v205, v[100:103], s[8:9] offset:512
	v_add_u32_e32 v207, 0x10000, v207
	v_add_u32_e32 v206, 0x50000, v206
	global_load_dwordx4 v[232:235], v206, s[70:71] offset:64
	global_load_dwordx4 v[240:243], v206, s[70:71] offset:576
	global_load_dwordx4 v[228:231], v206, s[70:71]
	global_load_dwordx4 v[236:239], v206, s[70:71] offset:512
	s_waitcnt lgkmcnt(0)
	v_add_f32_e32 v211, v210, v211
	ds_bpermute_b32 v212, v215, v211
	v_add_u32_e32 v208, 0x8000, v208
	s_waitcnt lgkmcnt(0)
	v_add_f32_e32 v211, v211, v212
	s_mov_b64 exec, 0xffff
	global_store_dword v209, v211, s[72:73]
	s_mov_b64 exec, -1
	v_add_u32_e32 v209, 0x400, v209
	s_waitcnt vmcnt(10)
	v_permlane32_swap_b32_e32 v244, v248
	v_permlane32_swap_b32_e32 v245, v249
	v_permlane32_swap_b32_e32 v246, v250
	v_permlane32_swap_b32_e32 v247, v251
	v_permlane32_swap_b32_e32 v216, v220
	v_permlane32_swap_b32_e32 v217, v221
	v_permlane32_swap_b32_e32 v218, v222
	v_permlane32_swap_b32_e32 v219, v223
	v_permlane16_swap_b32_e32 v244, v248
	v_permlane16_swap_b32_e32 v245, v249
	v_permlane16_swap_b32_e32 v246, v250
	v_permlane16_swap_b32_e32 v247, v251
	v_permlane16_swap_b32_e32 v216, v220
	v_permlane16_swap_b32_e32 v217, v221
	v_permlane16_swap_b32_e32 v218, v222
	v_permlane16_swap_b32_e32 v219, v223
	v_pk_fma_f32 v[92:93], v[92:93], v[144:145], v[244:245]
	v_pk_fma_f32 v[94:95], v[94:95], v[146:147], v[246:247]
	v_mul_f32_e32 v210, v93, v93
	v_fmac_f32_e32 v210, v92, v92
	v_fmac_f32_e32 v210, v94, v94
	v_fmac_f32_e32 v210, v95, v95
	v_pk_fma_f32 v[88:89], v[88:89], v[152:153], v[248:249]
	v_pk_fma_f32 v[90:91], v[90:91], v[154:155], v[250:251]
	v_fmac_f32_e32 v210, v88, v88
	v_fmac_f32_e32 v210, v89, v89
	v_fmac_f32_e32 v210, v90, v90
	v_fmac_f32_e32 v210, v91, v91
	v_pk_fma_f32 v[84:85], v[84:85], v[148:149], v[216:217]
	v_pk_fma_f32 v[86:87], v[86:87], v[150:151], v[218:219]
	v_fmac_f32_e32 v210, v84, v84
	v_fmac_f32_e32 v210, v85, v85
	v_fmac_f32_e32 v210, v86, v86
	v_fmac_f32_e32 v210, v87, v87
	v_pk_fma_f32 v[80:81], v[80:81], v[156:157], v[220:221]
	v_pk_fma_f32 v[82:83], v[82:83], v[158:159], v[222:223]
	v_fmac_f32_e32 v210, v80, v80
	v_fmac_f32_e32 v210, v81, v81
	v_fmac_f32_e32 v210, v82, v82
	v_fmac_f32_e32 v210, v83, v83
	s_cmp_lg_u64 s[2:3], 0
	s_cbranch_scc1 .Lnoap_C_4
	v_pk_mul_f32 v[244:245], v[64:65], v[92:93]
	v_pk_mul_f32 v[246:247], v[66:67], v[94:95]
	v_pk_mul_f32 v[248:249], v[72:73], v[88:89]
	v_pk_mul_f32 v[250:251], v[74:75], v[90:91]
	v_pk_mul_f32 v[216:217], v[68:69], v[84:85]
	v_pk_mul_f32 v[218:219], v[70:71], v[86:87]
	v_pk_mul_f32 v[220:221], v[76:77], v[80:81]
	v_pk_mul_f32 v[222:223], v[78:79], v[82:83]
	v_cvt_pk_bf16_f32 v244, v244, v245
	v_cvt_pk_bf16_f32 v245, v246, v247
	v_cvt_pk_bf16_f32 v246, v248, v249
	v_cvt_pk_bf16_f32 v247, v250, v251
	global_store_dwordx4 v208, v[244:247], s[42:43]
	v_cvt_pk_bf16_f32 v216, v216, v217
	v_cvt_pk_bf16_f32 v217, v218, v219
	v_cvt_pk_bf16_f32 v218, v220, v221
	v_cvt_pk_bf16_f32 v219, v222, v223
	global_store_dwordx4 v208, v[216:219], s[42:43] offset:256
; DI u32x4 pack8(const float* v) { u32x4 w; w.x = pk2(v[0], v[1]); w.y = pk2(v[2], v[3]); w.z = pk2(v[4], v[5]); w.w = pk2(v[6], v[7]); return w; }
; #define xor16_32(s) xor16_32_l((s), fr + 16 * fq)
;     DI void operator()(AccRef acc, const Unit& u, int wr, int wc, int fr, int fq) const {
;     ...
;             const int rb = u.pm * 256 + ai * 128 + wr * 64 + fr;
;             int mb, pos0, kv0; row_info(rb, mb, pos0, kv0);
;             f32x4 gt[2][2], gs[2][2];
; #pragma unroll
;             for (int bj = 0; bj < 2; ++bj)
; #pragma unroll
;                 for (int n = 0; n < 2; ++n) {
;                     const int c = u.pn * 256 + bj * 128 + cl + 4 * n;
;                     gt[bj][n] = *(const f32x4*)(gate + (size_t)mb * 6144 + c);
;                     if (ap) { const f32x4 g = *(const f32x4*)(gn + c), s = *(const f32x4*)(scn + (size_t)mb * 6144 + c); gs[bj][n] = g * (s + 1.f); }
;                 }
;     ...
;             for (int m = 0; m < 4; ++m) {
;                 const int row = rb + 16 * m;
;                 const float* xi = row < MP ? xin_p + (size_t)row * 1024 : xin_s + (size_t)(row - MP) * 1024;
;                 float s = 0.f;
; #pragma unroll
;                 for (int bj = 0; bj < 2; ++bj) {
;                     const int c = u.pn * 256 + bj * 128 + cl;
;                     float v[8];
; #pragma unroll
;                     for (int n = 0; n < 2; ++n) {
;                         const f32x4 x = *(const f32x4*)(xi + c + 4 * n);
;                         const f32x4 y = x + gt[bj][n] * acc[ai][bj][m][n];
;                         *(f32x4*)(xout + (size_t)row * 1024 + c + 4 * n) = y;
; #pragma unroll
;                         for (int j = 0; j < 4; ++j) { s += y[j] * y[j]; v[4 * n + j] = ap ? y[j] * gs[bj][n][j] : 0.f; }
;                     }
;                     if (ap) *(u32x4*)(ap + (size_t)row * 1024 + c) = pack8(v);
;                 }
;                 s = xor16_32(s);
;                 if (fq == 0) ssq[(size_t)row * 16 + u.pn * 4 + wc] = s;
.Lnoap_C_4:
	ds_bpermute_b32 v211, v214, v210
	v_permlane16_swap_b32_e32 v92, v88
	v_permlane16_swap_b32_e32 v93, v89
	v_permlane16_swap_b32_e32 v94, v90
	v_permlane16_swap_b32_e32 v95, v91
	v_permlane16_swap_b32_e32 v84, v80
	v_permlane16_swap_b32_e32 v85, v81
	v_permlane16_swap_b32_e32 v86, v82
	v_permlane16_swap_b32_e32 v87, v83
	v_permlane32_swap_b32_e32 v92, v88
	v_permlane32_swap_b32_e32 v93, v89
	v_permlane32_swap_b32_e32 v94, v90
	v_permlane32_swap_b32_e32 v95, v91
	v_permlane32_swap_b32_e32 v84, v80
	v_permlane32_swap_b32_e32 v85, v81
	v_permlane32_swap_b32_e32 v86, v82
	v_permlane32_swap_b32_e32 v87, v83
	s_nop 1
	v_mov_b32_dpp v248, v88 row_ror:8 row_mask:0xf bank_mask:0xf
	v_mov_b32_dpp v249, v89 row_ror:8 row_mask:0xf bank_mask:0xf
	v_mov_b32_dpp v250, v90 row_ror:8 row_mask:0xf bank_mask:0xf
	v_mov_b32_dpp v251, v91 row_ror:8 row_mask:0xf bank_mask:0xf
	v_mov_b32_dpp v220, v80 row_ror:8 row_mask:0xf bank_mask:0xf
	v_mov_b32_dpp v221, v81 row_ror:8 row_mask:0xf bank_mask:0xf
	v_mov_b32_dpp v222, v82 row_ror:8 row_mask:0xf bank_mask:0xf
	v_mov_b32_dpp v223, v83 row_ror:8 row_mask:0xf bank_mask:0xf
	s_mov_b32 vcc_lo, 0xff00ff
	s_mov_b32 vcc_hi, 0xff00ff
	v_mov_b32_e32 v204, 0xffff8040
	v_mov_b32_e32 v205, 0x8040
	v_cndmask_b32_e64 v204, v204, 0, vcc
	v_cndmask_b32_e64 v205, 0, v205, vcc
	v_add_u32_e32 v204, v204, v207
	v_add_u32_e32 v205, v205, v207
	v_cndmask_b32_e32 v244, v248, v92, vcc
	v_cndmask_b32_e32 v245, v249, v93, vcc
	v_cndmask_b32_e32 v246, v250, v94, vcc
	v_cndmask_b32_e32 v247, v251, v95, vcc
	v_cndmask_b32_e32 v216, v220, v84, vcc
	v_cndmask_b32_e32 v217, v221, v85, vcc
	v_cndmask_b32_e32 v218, v222, v86, vcc
	v_cndmask_b32_e32 v219, v223, v87, vcc
	v_cndmask_b32_e32 v92, v92, v248, vcc
	v_cndmask_b32_e32 v93, v93, v249, vcc
	v_cndmask_b32_e32 v94, v94, v250, vcc
	v_cndmask_b32_e32 v95, v95, v251, vcc
	v_cndmask_b32_e32 v84, v84, v220, vcc
	v_cndmask_b32_e32 v85, v85, v221, vcc
	v_cndmask_b32_e32 v86, v86, v222, vcc
	v_cndmask_b32_e32 v87, v87, v223, vcc
	global_store_dwordx4 v204, v[244:247], s[8:9]
	global_store_dwordx4 v204, v[216:219], s[8:9] offset:512
	global_store_dwordx4 v205, v[92:95], s[8:9]
	global_store_dwordx4 v205, v[84:87], s[8:9] offset:512
	v_add_u32_e32 v207, 0x50000, v207
	v_add_u32_e32 v206, 0x10000, v206
	global_load_dwordx4 v[248:251], v206, s[70:71] offset:64
	global_load_dwordx4 v[220:223], v206, s[70:71] offset:576
	global_load_dwordx4 v[244:247], v206, s[70:71]
	global_load_dwordx4 v[216:219], v206, s[70:71] offset:512
	s_waitcnt lgkmcnt(0)
	v_add_f32_e32 v211, v210, v211
	ds_bpermute_b32 v212, v215, v211
	v_add_u32_e32 v208, 0x28000, v208
	s_waitcnt lgkmcnt(0)
	v_add_f32_e32 v211, v211, v212
	s_mov_b64 exec, 0xffff
	global_store_dword v209, v211, s[72:73]
	s_mov_b64 exec, -1
	v_add_u32_e32 v209, 0x1400, v209
	v_add_u32_e32 v224, 0xffffc080, v176
	v_add_u32_e32 v96, 0x80, v176
	s_waitcnt lgkmcnt(0)
	v_lshrrev_b32_e32 v81, 6, v224
	v_cmp_gt_i32_e32 vcc, s94, v96
	v_ashrrev_i32_e32 v80, 11, v96
	v_add_u32_e32 v81, 8, v81
	v_cndmask_b32_e32 v84, v81, v80, vcc
	v_mov_b64_e32 v[80:81], s[28:29]
	v_mad_i64_i32 v[80:81], s[12:13], v84, s75, v[80:81]
	v_mov_b64_e32 v[82:83], s[30:31]
	v_lshl_add_u64 v[92:93], v[172:173], 2, v[80:81]
	v_mad_i64_i32 v[84:85], s[12:13], v84, s75, v[82:83]
	global_load_dwordx4 v[80:83], v[92:93], off
	s_movk_i32 s6, 0x3fff
	v_cmp_lt_i32_e64 s[6:7], s6, v96
	s_and_b64 vcc, exec, s[2:3]
	s_cbranch_vccnz .LBB0_1567
	v_lshl_add_u64 v[64:65], v[84:85], 0, v[174:175]
	global_load_dwordx4 v[64:67], v[64:65], off
	s_nop 0
	global_load_dwordx4 v[86:89], v[178:179], off
	s_waitcnt vmcnt(1)
	v_pk_add_f32 v[66:67], v[66:67], 1.0 op_sel_hi:[1,0]
	v_pk_add_f32 v[64:65], v[64:65], 1.0 op_sel_hi:[1,0]
	s_waitcnt vmcnt(0)
	v_pk_mul_f32 v[66:67], v[88:89], v[66:67]
	v_pk_mul_f32 v[64:65], v[86:87], v[64:65]
	global_load_dwordx4 v[88:91], v[92:93], off offset:16
	s_and_b64 vcc, exec, s[2:3]
	v_lshl_add_u64 v[98:99], v[172:173], 2, v[84:85]
	s_cbranch_vccz .LBB0_1568

; DI u32x4 pack8(const float* v) { u32x4 w; w.x = pk2(v[0], v[1]); w.y = pk2(v[2], v[3]); w.z = pk2(v[4], v[5]); w.w = pk2(v[6], v[7]); return w; }
; #define xor16_32(s) xor16_32_l((s), fr + 16 * fq)
;     DI void operator()(AccRef acc, const Unit& u, int wr, int wc, int fr, int fq) const {
;     ...
;             for (int m = 0; m < 4; ++m) {
;                 const int row = rb + 16 * m;
;                 const float* xi = row < MP ? xin_p + (size_t)row * 1024 : xin_s + (size_t)(row - MP) * 1024;
;                 float s = 0.f;
; #pragma unroll
;                 for (int bj = 0; bj < 2; ++bj) {
;                     const int c = u.pn * 256 + bj * 128 + cl;
;                     float v[8];
; #pragma unroll
;                     for (int n = 0; n < 2; ++n) {
;                         const f32x4 x = *(const f32x4*)(xi + c + 4 * n);
;                         const f32x4 y = x + gt[bj][n] * acc[ai][bj][m][n];
;                         *(f32x4*)(xout + (size_t)row * 1024 + c + 4 * n) = y;
; #pragma unroll
;                         for (int j = 0; j < 4; ++j) { s += y[j] * y[j]; v[4 * n + j] = ap ? y[j] * gs[bj][n][j] : 0.f; }
;                     }
;                     if (ap) *(u32x4*)(ap + (size_t)row * 1024 + c) = pack8(v);
;                 }
;                 s = xor16_32(s);
;                 if (fq == 0) ssq[(size_t)row * 16 + u.pn * 4 + wc] = s;
.Lnoap_C_5:
	ds_bpermute_b32 v211, v214, v210
	v_permlane16_swap_b32_e32 v60, v56
	v_permlane16_swap_b32_e32 v61, v57
	v_permlane16_swap_b32_e32 v62, v58
	v_permlane16_swap_b32_e32 v63, v59
	v_permlane16_swap_b32_e32 v52, v48
	v_permlane16_swap_b32_e32 v53, v49
	v_permlane16_swap_b32_e32 v54, v50
	v_permlane16_swap_b32_e32 v55, v51
	v_permlane32_swap_b32_e32 v60, v56
	v_permlane32_swap_b32_e32 v61, v57
	v_permlane32_swap_b32_e32 v62, v58
	v_permlane32_swap_b32_e32 v63, v59
	v_permlane32_swap_b32_e32 v52, v48
	v_permlane32_swap_b32_e32 v53, v49
	v_permlane32_swap_b32_e32 v54, v50
	v_permlane32_swap_b32_e32 v55, v51
	s_nop 1
	v_mov_b32_dpp v232, v56 row_ror:8 row_mask:0xf bank_mask:0xf
	v_mov_b32_dpp v233, v57 row_ror:8 row_mask:0xf bank_mask:0xf
	v_mov_b32_dpp v234, v58 row_ror:8 row_mask:0xf bank_mask:0xf
	v_mov_b32_dpp v235, v59 row_ror:8 row_mask:0xf bank_mask:0xf
	v_mov_b32_dpp v240, v48 row_ror:8 row_mask:0xf bank_mask:0xf
	v_mov_b32_dpp v241, v49 row_ror:8 row_mask:0xf bank_mask:0xf
	v_mov_b32_dpp v242, v50 row_ror:8 row_mask:0xf bank_mask:0xf
	v_mov_b32_dpp v243, v51 row_ror:8 row_mask:0xf bank_mask:0xf
	s_mov_b32 vcc_lo, 0xff00ff
	s_mov_b32 vcc_hi, 0xff00ff
	v_mov_b32_e32 v204, 0xffff8040
	v_mov_b32_e32 v205, 0x8040
	v_cndmask_b32_e64 v204, v204, 0, vcc
	v_cndmask_b32_e64 v205, 0, v205, vcc
	v_add_u32_e32 v204, v204, v207
	v_add_u32_e32 v205, v205, v207
	v_cndmask_b32_e32 v228, v232, v60, vcc
	v_cndmask_b32_e32 v229, v233, v61, vcc
	v_cndmask_b32_e32 v230, v234, v62, vcc
	v_cndmask_b32_e32 v231, v235, v63, vcc
	v_cndmask_b32_e32 v236, v240, v52, vcc
	v_cndmask_b32_e32 v237, v241, v53, vcc
	v_cndmask_b32_e32 v238, v242, v54, vcc
	v_cndmask_b32_e32 v239, v243, v55, vcc
	v_cndmask_b32_e32 v60, v60, v232, vcc
	v_cndmask_b32_e32 v61, v61, v233, vcc
	v_cndmask_b32_e32 v62, v62, v234, vcc
	v_cndmask_b32_e32 v63, v63, v235, vcc
	v_cndmask_b32_e32 v52, v52, v240, vcc
	v_cndmask_b32_e32 v53, v53, v241, vcc
	v_cndmask_b32_e32 v54, v54, v242, vcc
	v_cndmask_b32_e32 v55, v55, v243, vcc
	global_store_dwordx4 v204, v[228:231], s[8:9]
	global_store_dwordx4 v204, v[236:239], s[8:9] offset:512
	global_store_dwordx4 v205, v[60:63], s[8:9]
	global_store_dwordx4 v205, v[52:55], s[8:9] offset:512
	v_add_u32_e32 v207, 0x10000, v207
	v_add_u32_e32 v206, 0x10000, v206
	global_load_dwordx4 v[232:235], v206, s[70:71] offset:64
	global_load_dwordx4 v[240:243], v206, s[70:71] offset:576
	global_load_dwordx4 v[228:231], v206, s[70:71]
	global_load_dwordx4 v[236:239], v206, s[70:71] offset:512
	s_waitcnt lgkmcnt(0)
	v_add_f32_e32 v211, v210, v211
	ds_bpermute_b32 v212, v215, v211
	v_add_u32_e32 v208, 0x8000, v208
	s_waitcnt lgkmcnt(0)
	v_add_f32_e32 v211, v211, v212
	s_mov_b64 exec, 0xffff
	global_store_dword v209, v211, s[72:73]
	s_mov_b64 exec, -1
	v_add_u32_e32 v209, 0x400, v209
	v_permlane32_swap_b32_e32 v244, v248
	v_permlane32_swap_b32_e32 v245, v249
	v_permlane32_swap_b32_e32 v246, v250
	v_permlane32_swap_b32_e32 v247, v251
	v_permlane32_swap_b32_e32 v216, v220
	v_permlane32_swap_b32_e32 v217, v221
	v_permlane32_swap_b32_e32 v218, v222
	v_permlane32_swap_b32_e32 v219, v223
	v_permlane16_swap_b32_e32 v244, v248
	v_permlane16_swap_b32_e32 v245, v249
	v_permlane16_swap_b32_e32 v246, v250
	v_permlane16_swap_b32_e32 v247, v251
	v_permlane16_swap_b32_e32 v216, v220
	v_permlane16_swap_b32_e32 v217, v221
	v_permlane16_swap_b32_e32 v218, v222
	v_permlane16_swap_b32_e32 v219, v223
	v_pk_fma_f32 v[44:45], v[44:45], v[80:81], v[244:245]
	v_pk_fma_f32 v[46:47], v[46:47], v[82:83], v[246:247]
	v_mul_f32_e32 v210, v45, v45
	v_fmac_f32_e32 v210, v44, v44
	v_fmac_f32_e32 v210, v46, v46
	v_fmac_f32_e32 v210, v47, v47
	v_pk_fma_f32 v[40:41], v[40:41], v[88:89], v[248:249]
	v_pk_fma_f32 v[42:43], v[42:43], v[90:91], v[250:251]
	v_fmac_f32_e32 v210, v40, v40
	v_fmac_f32_e32 v210, v41, v41
	v_fmac_f32_e32 v210, v42, v42
	v_fmac_f32_e32 v210, v43, v43
	v_pk_fma_f32 v[36:37], v[36:37], v[84:85], v[216:217]
	v_pk_fma_f32 v[38:39], v[38:39], v[86:87], v[218:219]
	v_fmac_f32_e32 v210, v36, v36
	v_fmac_f32_e32 v210, v37, v37
	v_fmac_f32_e32 v210, v38, v38
	v_fmac_f32_e32 v210, v39, v39
	v_pk_fma_f32 v[32:33], v[32:33], v[92:93], v[220:221]
	v_pk_fma_f32 v[34:35], v[34:35], v[94:95], v[222:223]
	v_fmac_f32_e32 v210, v32, v32
	v_fmac_f32_e32 v210, v33, v33
	v_fmac_f32_e32 v210, v34, v34
	v_fmac_f32_e32 v210, v35, v35
	s_cmp_lg_u64 s[2:3], 0
	s_cbranch_scc1 .Lnoap_C_6
	v_pk_mul_f32 v[244:245], v[64:65], v[44:45]
	v_pk_mul_f32 v[246:247], v[66:67], v[46:47]
	v_pk_mul_f32 v[248:249], v[72:73], v[40:41]
	v_pk_mul_f32 v[250:251], v[74:75], v[42:43]
	v_pk_mul_f32 v[216:217], v[68:69], v[36:37]
	v_pk_mul_f32 v[218:219], v[70:71], v[38:39]
	v_pk_mul_f32 v[220:221], v[76:77], v[32:33]
	v_pk_mul_f32 v[222:223], v[78:79], v[34:35]
	v_cvt_pk_bf16_f32 v244, v244, v245
	v_cvt_pk_bf16_f32 v245, v246, v247
	v_cvt_pk_bf16_f32 v246, v248, v249
	v_cvt_pk_bf16_f32 v247, v250, v251
	global_store_dwordx4 v208, v[244:247], s[42:43]
	v_cvt_pk_bf16_f32 v216, v216, v217
	v_cvt_pk_bf16_f32 v217, v218, v219
	v_cvt_pk_bf16_f32 v218, v220, v221
	v_cvt_pk_bf16_f32 v219, v222, v223
	global_store_dwordx4 v208, v[216:219], s[42:43] offset:256
; DI u32x4 pack8(const float* v) { u32x4 w; w.x = pk2(v[0], v[1]); w.y = pk2(v[2], v[3]); w.z = pk2(v[4], v[5]); w.w = pk2(v[6], v[7]); return w; }
; #define xor16_32(s) xor16_32_l((s), fr + 16 * fq)
;     DI void operator()(AccRef acc, const Unit& u, int wr, int wc, int fr, int fq) const {
;     ...
;             for (int m = 0; m < 4; ++m) {
;                 const int row = rb + 16 * m;
;                 const float* xi = row < MP ? xin_p + (size_t)row * 1024 : xin_s + (size_t)(row - MP) * 1024;
;                 float s = 0.f;
; #pragma unroll
;                 for (int bj = 0; bj < 2; ++bj) {
;                     const int c = u.pn * 256 + bj * 128 + cl;
;                     float v[8];
; #pragma unroll
;                     for (int n = 0; n < 2; ++n) {
;                         const f32x4 x = *(const f32x4*)(xi + c + 4 * n);
;                         const f32x4 y = x + gt[bj][n] * acc[ai][bj][m][n];
;                         *(f32x4*)(xout + (size_t)row * 1024 + c + 4 * n) = y;
; #pragma unroll
;                         for (int j = 0; j < 4; ++j) { s += y[j] * y[j]; v[4 * n + j] = ap ? y[j] * gs[bj][n][j] : 0.f; }
;                     }
;                     if (ap) *(u32x4*)(ap + (size_t)row * 1024 + c) = pack8(v);
;                 }
;                 s = xor16_32(s);
;                 if (fq == 0) ssq[(size_t)row * 16 + u.pn * 4 + wc] = s;
.Lnoap_C_6:
	ds_bpermute_b32 v211, v214, v210
	v_permlane16_swap_b32_e32 v44, v40
	v_permlane16_swap_b32_e32 v45, v41
	v_permlane16_swap_b32_e32 v46, v42
	v_permlane16_swap_b32_e32 v47, v43
	v_permlane16_swap_b32_e32 v36, v32
	v_permlane16_swap_b32_e32 v37, v33
	v_permlane16_swap_b32_e32 v38, v34
	v_permlane16_swap_b32_e32 v39, v35
	v_permlane32_swap_b32_e32 v44, v40
	v_permlane32_swap_b32_e32 v45, v41
	v_permlane32_swap_b32_e32 v46, v42
	v_permlane32_swap_b32_e32 v47, v43
	v_permlane32_swap_b32_e32 v36, v32
	v_permlane32_swap_b32_e32 v37, v33
	v_permlane32_swap_b32_e32 v38, v34
	v_permlane32_swap_b32_e32 v39, v35
	s_nop 1
	v_mov_b32_dpp v248, v40 row_ror:8 row_mask:0xf bank_mask:0xf
	v_mov_b32_dpp v249, v41 row_ror:8 row_mask:0xf bank_mask:0xf
	v_mov_b32_dpp v250, v42 row_ror:8 row_mask:0xf bank_mask:0xf
	v_mov_b32_dpp v251, v43 row_ror:8 row_mask:0xf bank_mask:0xf
	v_mov_b32_dpp v220, v32 row_ror:8 row_mask:0xf bank_mask:0xf
	v_mov_b32_dpp v221, v33 row_ror:8 row_mask:0xf bank_mask:0xf
	v_mov_b32_dpp v222, v34 row_ror:8 row_mask:0xf bank_mask:0xf
	v_mov_b32_dpp v223, v35 row_ror:8 row_mask:0xf bank_mask:0xf
	s_mov_b32 vcc_lo, 0xff00ff
	s_mov_b32 vcc_hi, 0xff00ff
	v_mov_b32_e32 v204, 0xffff8040
	v_mov_b32_e32 v205, 0x8040
	v_cndmask_b32_e64 v204, v204, 0, vcc
	v_cndmask_b32_e64 v205, 0, v205, vcc
	v_add_u32_e32 v204, v204, v207
	v_add_u32_e32 v205, v205, v207
	v_cndmask_b32_e32 v244, v248, v44, vcc
	v_cndmask_b32_e32 v245, v249, v45, vcc
	v_cndmask_b32_e32 v246, v250, v46, vcc
	v_cndmask_b32_e32 v247, v251, v47, vcc
	v_cndmask_b32_e32 v216, v220, v36, vcc
	v_cndmask_b32_e32 v217, v221, v37, vcc
	v_cndmask_b32_e32 v218, v222, v38, vcc
	v_cndmask_b32_e32 v219, v223, v39, vcc
	v_cndmask_b32_e32 v44, v44, v248, vcc
	v_cndmask_b32_e32 v45, v45, v249, vcc
	v_cndmask_b32_e32 v46, v46, v250, vcc
	v_cndmask_b32_e32 v47, v47, v251, vcc
	v_cndmask_b32_e32 v36, v36, v220, vcc
	v_cndmask_b32_e32 v37, v37, v221, vcc
	v_cndmask_b32_e32 v38, v38, v222, vcc
	v_cndmask_b32_e32 v39, v39, v223, vcc
	global_store_dwordx4 v204, v[244:247], s[8:9]
	global_store_dwordx4 v204, v[216:219], s[8:9] offset:512
	global_store_dwordx4 v205, v[44:47], s[8:9]
	global_store_dwordx4 v205, v[36:39], s[8:9] offset:512
	v_add_u32_e32 v207, 0x10000, v207
	v_add_u32_e32 v206, 0x10000, v206
	global_load_dwordx4 v[248:251], v206, s[70:71] offset:64
	global_load_dwordx4 v[220:223], v206, s[70:71] offset:576
	global_load_dwordx4 v[244:247], v206, s[70:71]
	global_load_dwordx4 v[216:219], v206, s[70:71] offset:512
	s_waitcnt lgkmcnt(0)
	v_add_f32_e32 v211, v210, v211
	ds_bpermute_b32 v212, v215, v211
	v_add_u32_e32 v208, 0x8000, v208
	s_waitcnt lgkmcnt(0)
	v_add_f32_e32 v211, v211, v212
	s_mov_b64 exec, 0xffff
	global_store_dword v209, v211, s[72:73]
	s_mov_b64 exec, -1
	v_add_u32_e32 v209, 0x400, v209
	s_waitcnt vmcnt(10)
	v_permlane32_swap_b32_e32 v228, v232
	v_permlane32_swap_b32_e32 v229, v233
	v_permlane32_swap_b32_e32 v230, v234
	v_permlane32_swap_b32_e32 v231, v235
	v_permlane32_swap_b32_e32 v236, v240
	v_permlane32_swap_b32_e32 v237, v241
	v_permlane32_swap_b32_e32 v238, v242
	v_permlane32_swap_b32_e32 v239, v243
	v_permlane16_swap_b32_e32 v228, v232
	v_permlane16_swap_b32_e32 v229, v233
	v_permlane16_swap_b32_e32 v230, v234
	v_permlane16_swap_b32_e32 v231, v235
	v_permlane16_swap_b32_e32 v236, v240
	v_permlane16_swap_b32_e32 v237, v241
	v_permlane16_swap_b32_e32 v238, v242
	v_permlane16_swap_b32_e32 v239, v243
	v_pk_fma_f32 v[28:29], v[28:29], v[80:81], v[228:229]
	v_pk_fma_f32 v[30:31], v[30:31], v[82:83], v[230:231]
	v_mul_f32_e32 v210, v29, v29
	v_fmac_f32_e32 v210, v28, v28
	v_fmac_f32_e32 v210, v30, v30
	v_fmac_f32_e32 v210, v31, v31
	v_pk_fma_f32 v[24:25], v[24:25], v[88:89], v[232:233]
	v_pk_fma_f32 v[26:27], v[26:27], v[90:91], v[234:235]
	v_fmac_f32_e32 v210, v24, v24
	v_fmac_f32_e32 v210, v25, v25
	v_fmac_f32_e32 v210, v26, v26
	v_fmac_f32_e32 v210, v27, v27
	v_pk_fma_f32 v[20:21], v[20:21], v[84:85], v[236:237]
	v_pk_fma_f32 v[22:23], v[22:23], v[86:87], v[238:239]
	v_fmac_f32_e32 v210, v20, v20
	v_fmac_f32_e32 v210, v21, v21
	v_fmac_f32_e32 v210, v22, v22
	v_fmac_f32_e32 v210, v23, v23
	v_pk_fma_f32 v[16:17], v[16:17], v[92:93], v[240:241]
	v_pk_fma_f32 v[18:19], v[18:19], v[94:95], v[242:243]
	v_fmac_f32_e32 v210, v16, v16
	v_fmac_f32_e32 v210, v17, v17
	v_fmac_f32_e32 v210, v18, v18
	v_fmac_f32_e32 v210, v19, v19
	s_cmp_lg_u64 s[2:3], 0
	s_cbranch_scc1 .Lnoap_C_7
	v_pk_mul_f32 v[228:229], v[64:65], v[28:29]
	v_pk_mul_f32 v[230:231], v[66:67], v[30:31]
	v_pk_mul_f32 v[232:233], v[72:73], v[24:25]
	v_pk_mul_f32 v[234:235], v[74:75], v[26:27]
	v_pk_mul_f32 v[236:237], v[68:69], v[20:21]
	v_pk_mul_f32 v[238:239], v[70:71], v[22:23]
	v_pk_mul_f32 v[240:241], v[76:77], v[16:17]
	v_pk_mul_f32 v[242:243], v[78:79], v[18:19]
	v_cvt_pk_bf16_f32 v228, v228, v229
	v_cvt_pk_bf16_f32 v229, v230, v231
	v_cvt_pk_bf16_f32 v230, v232, v233
	v_cvt_pk_bf16_f32 v231, v234, v235
	global_store_dwordx4 v208, v[228:231], s[42:43]
	v_cvt_pk_bf16_f32 v236, v236, v237
	v_cvt_pk_bf16_f32 v237, v238, v239
	v_cvt_pk_bf16_f32 v238, v240, v241
	v_cvt_pk_bf16_f32 v239, v242, v243
	global_store_dwordx4 v208, v[236:239], s[42:43] offset:256
; DI u32x4 pack8(const float* v) { u32x4 w; w.x = pk2(v[0], v[1]); w.y = pk2(v[2], v[3]); w.z = pk2(v[4], v[5]); w.w = pk2(v[6], v[7]); return w; }
; #define xor16_32(s) xor16_32_l((s), fr + 16 * fq)
;     DI void operator()(AccRef acc, const Unit& u, int wr, int wc, int fr, int fq) const {
;     ...
;             for (int m = 0; m < 4; ++m) {
;                 const int row = rb + 16 * m;
;                 const float* xi = row < MP ? xin_p + (size_t)row * 1024 : xin_s + (size_t)(row - MP) * 1024;
;                 float s = 0.f;
; #pragma unroll
;                 for (int bj = 0; bj < 2; ++bj) {
;                     const int c = u.pn * 256 + bj * 128 + cl;
;                     float v[8];
; #pragma unroll
;                     for (int n = 0; n < 2; ++n) {
;                         const f32x4 x = *(const f32x4*)(xi + c + 4 * n);
;                         const f32x4 y = x + gt[bj][n] * acc[ai][bj][m][n];
;                         *(f32x4*)(xout + (size_t)row * 1024 + c + 4 * n) = y;
; #pragma unroll
;                         for (int j = 0; j < 4; ++j) { s += y[j] * y[j]; v[4 * n + j] = ap ? y[j] * gs[bj][n][j] : 0.f; }
;                     }
;                     if (ap) *(u32x4*)(ap + (size_t)row * 1024 + c) = pack8(v);
;                 }
;                 s = xor16_32(s);
;                 if (fq == 0) ssq[(size_t)row * 16 + u.pn * 4 + wc] = s;
.Lnoap_C_7:
	ds_bpermute_b32 v211, v214, v210
	v_permlane16_swap_b32_e32 v28, v24
	v_permlane16_swap_b32_e32 v29, v25
	v_permlane16_swap_b32_e32 v30, v26
	v_permlane16_swap_b32_e32 v31, v27
	v_permlane16_swap_b32_e32 v20, v16
	v_permlane16_swap_b32_e32 v21, v17
	v_permlane16_swap_b32_e32 v22, v18
	v_permlane16_swap_b32_e32 v23, v19
	v_permlane32_swap_b32_e32 v28, v24
	v_permlane32_swap_b32_e32 v29, v25
	v_permlane32_swap_b32_e32 v30, v26
	v_permlane32_swap_b32_e32 v31, v27
	v_permlane32_swap_b32_e32 v20, v16
	v_permlane32_swap_b32_e32 v21, v17
	v_permlane32_swap_b32_e32 v22, v18
	v_permlane32_swap_b32_e32 v23, v19
	s_nop 1
	v_mov_b32_dpp v232, v24 row_ror:8 row_mask:0xf bank_mask:0xf
	v_mov_b32_dpp v233, v25 row_ror:8 row_mask:0xf bank_mask:0xf
	v_mov_b32_dpp v234, v26 row_ror:8 row_mask:0xf bank_mask:0xf
	v_mov_b32_dpp v235, v27 row_ror:8 row_mask:0xf bank_mask:0xf
	v_mov_b32_dpp v240, v16 row_ror:8 row_mask:0xf bank_mask:0xf
	v_mov_b32_dpp v241, v17 row_ror:8 row_mask:0xf bank_mask:0xf
	v_mov_b32_dpp v242, v18 row_ror:8 row_mask:0xf bank_mask:0xf
	v_mov_b32_dpp v243, v19 row_ror:8 row_mask:0xf bank_mask:0xf
	s_mov_b32 vcc_lo, 0xff00ff
	s_mov_b32 vcc_hi, 0xff00ff
	v_mov_b32_e32 v204, 0xffff8040
	v_mov_b32_e32 v205, 0x8040
	v_cndmask_b32_e64 v204, v204, 0, vcc
	v_cndmask_b32_e64 v205, 0, v205, vcc
	v_add_u32_e32 v204, v204, v207
	v_add_u32_e32 v205, v205, v207
	v_cndmask_b32_e32 v228, v232, v28, vcc
	v_cndmask_b32_e32 v229, v233, v29, vcc
	v_cndmask_b32_e32 v230, v234, v30, vcc
	v_cndmask_b32_e32 v231, v235, v31, vcc
	v_cndmask_b32_e32 v236, v240, v20, vcc
	v_cndmask_b32_e32 v237, v241, v21, vcc
	v_cndmask_b32_e32 v238, v242, v22, vcc
	v_cndmask_b32_e32 v239, v243, v23, vcc
	v_cndmask_b32_e32 v28, v28, v232, vcc
	v_cndmask_b32_e32 v29, v29, v233, vcc
	v_cndmask_b32_e32 v30, v30, v234, vcc
	v_cndmask_b32_e32 v31, v31, v235, vcc
	v_cndmask_b32_e32 v20, v20, v240, vcc
	v_cndmask_b32_e32 v21, v21, v241, vcc
	v_cndmask_b32_e32 v22, v22, v242, vcc
	v_cndmask_b32_e32 v23, v23, v243, vcc
	global_store_dwordx4 v204, v[228:231], s[8:9]
	global_store_dwordx4 v204, v[236:239], s[8:9] offset:512
	global_store_dwordx4 v205, v[28:31], s[8:9]
	global_store_dwordx4 v205, v[20:23], s[8:9] offset:512
	v_add_u32_e32 v207, 0x10000, v207
	s_waitcnt lgkmcnt(0)
	v_add_f32_e32 v211, v210, v211
	ds_bpermute_b32 v212, v215, v211
	v_add_u32_e32 v208, 0x8000, v208
	s_waitcnt lgkmcnt(0)
	v_add_f32_e32 v211, v211, v212
	s_mov_b64 exec, 0xffff
	global_store_dword v209, v211, s[72:73]
	s_mov_b64 exec, -1
	v_add_u32_e32 v209, 0x400, v209
	s_waitcnt vmcnt(6)
	v_permlane32_swap_b32_e32 v244, v248
	v_permlane32_swap_b32_e32 v245, v249
	v_permlane32_swap_b32_e32 v246, v250
	v_permlane32_swap_b32_e32 v247, v251
	v_permlane32_swap_b32_e32 v216, v220
	v_permlane32_swap_b32_e32 v217, v221
	v_permlane32_swap_b32_e32 v218, v222
	v_permlane32_swap_b32_e32 v219, v223
	v_permlane16_swap_b32_e32 v244, v248
	v_permlane16_swap_b32_e32 v245, v249
	v_permlane16_swap_b32_e32 v246, v250
	v_permlane16_swap_b32_e32 v247, v251
	v_permlane16_swap_b32_e32 v216, v220
	v_permlane16_swap_b32_e32 v217, v221
	v_permlane16_swap_b32_e32 v218, v222
	v_permlane16_swap_b32_e32 v219, v223
	v_pk_fma_f32 v[12:13], v[12:13], v[80:81], v[244:245]
	v_pk_fma_f32 v[14:15], v[14:15], v[82:83], v[246:247]
	v_mul_f32_e32 v210, v13, v13
	v_fmac_f32_e32 v210, v12, v12
	v_fmac_f32_e32 v210, v14, v14
	v_fmac_f32_e32 v210, v15, v15
	v_pk_fma_f32 v[8:9], v[8:9], v[88:89], v[248:249]
	v_pk_fma_f32 v[10:11], v[10:11], v[90:91], v[250:251]
	v_fmac_f32_e32 v210, v8, v8
	v_fmac_f32_e32 v210, v9, v9
	v_fmac_f32_e32 v210, v10, v10
	v_fmac_f32_e32 v210, v11, v11
	v_pk_fma_f32 v[4:5], v[4:5], v[84:85], v[216:217]
	v_pk_fma_f32 v[6:7], v[6:7], v[86:87], v[218:219]
	v_fmac_f32_e32 v210, v4, v4
	v_fmac_f32_e32 v210, v5, v5
	v_fmac_f32_e32 v210, v6, v6
	v_fmac_f32_e32 v210, v7, v7
	v_pk_fma_f32 v[0:1], v[0:1], v[92:93], v[220:221]
	v_pk_fma_f32 v[2:3], v[2:3], v[94:95], v[222:223]
	v_fmac_f32_e32 v210, v0, v0
	v_fmac_f32_e32 v210, v1, v1
	v_fmac_f32_e32 v210, v2, v2
	v_fmac_f32_e32 v210, v3, v3
	s_cmp_lg_u64 s[2:3], 0
	s_cbranch_scc1 .Lnoap_C_8
	v_pk_mul_f32 v[244:245], v[64:65], v[12:13]
	v_pk_mul_f32 v[246:247], v[66:67], v[14:15]
	v_pk_mul_f32 v[248:249], v[72:73], v[8:9]
	v_pk_mul_f32 v[250:251], v[74:75], v[10:11]
	v_pk_mul_f32 v[216:217], v[68:69], v[4:5]
	v_pk_mul_f32 v[218:219], v[70:71], v[6:7]
	v_pk_mul_f32 v[220:221], v[76:77], v[0:1]
	v_pk_mul_f32 v[222:223], v[78:79], v[2:3]
	v_cvt_pk_bf16_f32 v244, v244, v245
	v_cvt_pk_bf16_f32 v245, v246, v247
	v_cvt_pk_bf16_f32 v246, v248, v249
	v_cvt_pk_bf16_f32 v247, v250, v251
	global_store_dwordx4 v208, v[244:247], s[42:43]
	v_cvt_pk_bf16_f32 v216, v216, v217
	v_cvt_pk_bf16_f32 v217, v218, v219
	v_cvt_pk_bf16_f32 v218, v220, v221
	v_cvt_pk_bf16_f32 v219, v222, v223
	global_store_dwordx4 v208, v[216:219], s[42:43] offset:256
; DI u32x4 pack8(const float* v) { u32x4 w; w.x = pk2(v[0], v[1]); w.y = pk2(v[2], v[3]); w.z = pk2(v[4], v[5]); w.w = pk2(v[6], v[7]); return w; }
; #define xor16_32(s) xor16_32_l((s), fr + 16 * fq)
;     DI void operator()(AccRef acc, const Unit& u, int wr, int wc, int fr, int fq) const {
;     ...
;             for (int m = 0; m < 4; ++m) {
;                 const int row = rb + 16 * m;
;                 const float* xi = row < MP ? xin_p + (size_t)row * 1024 : xin_s + (size_t)(row - MP) * 1024;
;                 float s = 0.f;
; #pragma unroll
;                 for (int bj = 0; bj < 2; ++bj) {
;                     const int c = u.pn * 256 + bj * 128 + cl;
;                     float v[8];
; #pragma unroll
;                     for (int n = 0; n < 2; ++n) {
;                         const f32x4 x = *(const f32x4*)(xi + c + 4 * n);
;                         const f32x4 y = x + gt[bj][n] * acc[ai][bj][m][n];
;                         *(f32x4*)(xout + (size_t)row * 1024 + c + 4 * n) = y;
; #pragma unroll
;                         for (int j = 0; j < 4; ++j) { s += y[j] * y[j]; v[4 * n + j] = ap ? y[j] * gs[bj][n][j] : 0.f; }
;                     }
;                     if (ap) *(u32x4*)(ap + (size_t)row * 1024 + c) = pack8(v);
;                 }
;                 s = xor16_32(s);
;                 if (fq == 0) ssq[(size_t)row * 16 + u.pn * 4 + wc] = s;
.Lnoap_C_8:
	ds_bpermute_b32 v211, v214, v210
	v_permlane16_swap_b32_e32 v12, v8
	v_permlane16_swap_b32_e32 v13, v9
	v_permlane16_swap_b32_e32 v14, v10
	v_permlane16_swap_b32_e32 v15, v11
	v_permlane16_swap_b32_e32 v4, v0
	v_permlane16_swap_b32_e32 v5, v1
	v_permlane16_swap_b32_e32 v6, v2
	v_permlane16_swap_b32_e32 v7, v3
	v_permlane32_swap_b32_e32 v12, v8
	v_permlane32_swap_b32_e32 v13, v9
	v_permlane32_swap_b32_e32 v14, v10
	v_permlane32_swap_b32_e32 v15, v11
	v_permlane32_swap_b32_e32 v4, v0
	v_permlane32_swap_b32_e32 v5, v1
	v_permlane32_swap_b32_e32 v6, v2
	v_permlane32_swap_b32_e32 v7, v3
	s_nop 1
	v_mov_b32_dpp v248, v8 row_ror:8 row_mask:0xf bank_mask:0xf
	v_mov_b32_dpp v249, v9 row_ror:8 row_mask:0xf bank_mask:0xf
	v_mov_b32_dpp v250, v10 row_ror:8 row_mask:0xf bank_mask:0xf
	v_mov_b32_dpp v251, v11 row_ror:8 row_mask:0xf bank_mask:0xf
	v_mov_b32_dpp v220, v0 row_ror:8 row_mask:0xf bank_mask:0xf
	v_mov_b32_dpp v221, v1 row_ror:8 row_mask:0xf bank_mask:0xf
	v_mov_b32_dpp v222, v2 row_ror:8 row_mask:0xf bank_mask:0xf
	v_mov_b32_dpp v223, v3 row_ror:8 row_mask:0xf bank_mask:0xf
	s_mov_b32 vcc_lo, 0xff00ff
	s_mov_b32 vcc_hi, 0xff00ff
	v_mov_b32_e32 v204, 0xffff8040
	v_mov_b32_e32 v205, 0x8040
	v_cndmask_b32_e64 v204, v204, 0, vcc
	v_cndmask_b32_e64 v205, 0, v205, vcc
	v_add_u32_e32 v204, v204, v207
	v_add_u32_e32 v205, v205, v207
	v_cndmask_b32_e32 v244, v248, v12, vcc
	v_cndmask_b32_e32 v245, v249, v13, vcc
	v_cndmask_b32_e32 v246, v250, v14, vcc
	v_cndmask_b32_e32 v247, v251, v15, vcc
	v_cndmask_b32_e32 v216, v220, v4, vcc
	v_cndmask_b32_e32 v217, v221, v5, vcc
	v_cndmask_b32_e32 v218, v222, v6, vcc
	v_cndmask_b32_e32 v219, v223, v7, vcc
	v_cndmask_b32_e32 v12, v12, v248, vcc
	v_cndmask_b32_e32 v13, v13, v249, vcc
	v_cndmask_b32_e32 v14, v14, v250, vcc
	v_cndmask_b32_e32 v15, v15, v251, vcc
	v_cndmask_b32_e32 v4, v4, v220, vcc
	v_cndmask_b32_e32 v5, v5, v221, vcc
	v_cndmask_b32_e32 v6, v6, v222, vcc
	v_cndmask_b32_e32 v7, v7, v223, vcc
	global_store_dwordx4 v204, v[244:247], s[8:9]
	global_store_dwordx4 v204, v[216:219], s[8:9] offset:512
	global_store_dwordx4 v205, v[12:15], s[8:9]
	global_store_dwordx4 v205, v[4:7], s[8:9] offset:512
	s_waitcnt lgkmcnt(0)
	v_add_f32_e32 v211, v210, v211
	ds_bpermute_b32 v212, v215, v211
	s_waitcnt lgkmcnt(0)
	v_add_f32_e32 v211, v211, v212
	s_mov_b64 exec, 0xffff
	global_store_dword v209, v211, s[72:73]
	s_mov_b64 exec, -1
	s_and_b64 vcc, exec, s[0:1]
	s_mov_b64 s[0:1], -1
	s_cbranch_vccnz .LBB0_1500
	s_andn2_b64 vcc, exec, s[16:17]
	s_cbranch_vccnz .LBB0_1499
	s_barrier
	s_branch .LBB0_1499

; DI u32x4 pack8(const float* v) { u32x4 w; w.x = pk2(v[0], v[1]); w.y = pk2(v[2], v[3]); w.z = pk2(v[4], v[5]); w.w = pk2(v[6], v[7]); return w; }
; #define xor16_32(s) xor16_32_l((s), fr + 16 * fq)
;     DI void operator()(AccRef acc, const Unit& u, int wr, int wc, int fr, int fq) const {
;     ...
;             for (int m = 0; m < 4; ++m) {
;                 const int row = rb + 16 * m;
;                 const float* xi = row < MP ? xin_p + (size_t)row * 1024 : xin_s + (size_t)(row - MP) * 1024;
;                 float s = 0.f;
; #pragma unroll
;                 for (int bj = 0; bj < 2; ++bj) {
;                     const int c = u.pn * 256 + bj * 128 + cl;
;                     float v[8];
; #pragma unroll
;                     for (int n = 0; n < 2; ++n) {
;                         const f32x4 x = *(const f32x4*)(xi + c + 4 * n);
;                         const f32x4 y = x + gt[bj][n] * acc[ai][bj][m][n];
;                         *(f32x4*)(xout + (size_t)row * 1024 + c + 4 * n) = y;
; #pragma unroll
;                         for (int j = 0; j < 4; ++j) { s += y[j] * y[j]; v[4 * n + j] = ap ? y[j] * gs[bj][n][j] : 0.f; }
;                     }
;                     if (ap) *(u32x4*)(ap + (size_t)row * 1024 + c) = pack8(v);
;                 }
;                 s = xor16_32(s);
;                 if (fq == 0) ssq[(size_t)row * 16 + u.pn * 4 + wc] = s;
.Lnoap_D_1:
	ds_bpermute_b32 v211, v214, v210
	v_permlane16_swap_b32_e32 v140, v136
	v_permlane16_swap_b32_e32 v141, v137
	v_permlane16_swap_b32_e32 v142, v138
	v_permlane16_swap_b32_e32 v143, v139
	v_permlane16_swap_b32_e32 v132, v128
	v_permlane16_swap_b32_e32 v133, v129
	v_permlane16_swap_b32_e32 v134, v130
	v_permlane16_swap_b32_e32 v135, v131
	v_permlane32_swap_b32_e32 v140, v136
	v_permlane32_swap_b32_e32 v141, v137
	v_permlane32_swap_b32_e32 v142, v138
	v_permlane32_swap_b32_e32 v143, v139
	v_permlane32_swap_b32_e32 v132, v128
	v_permlane32_swap_b32_e32 v133, v129
	v_permlane32_swap_b32_e32 v134, v130
	v_permlane32_swap_b32_e32 v135, v131
	s_nop 1
	v_mov_b32_dpp v232, v136 row_ror:8 row_mask:0xf bank_mask:0xf
	v_mov_b32_dpp v233, v137 row_ror:8 row_mask:0xf bank_mask:0xf
	v_mov_b32_dpp v234, v138 row_ror:8 row_mask:0xf bank_mask:0xf
	v_mov_b32_dpp v235, v139 row_ror:8 row_mask:0xf bank_mask:0xf
	v_mov_b32_dpp v240, v128 row_ror:8 row_mask:0xf bank_mask:0xf
	v_mov_b32_dpp v241, v129 row_ror:8 row_mask:0xf bank_mask:0xf
	v_mov_b32_dpp v242, v130 row_ror:8 row_mask:0xf bank_mask:0xf
	v_mov_b32_dpp v243, v131 row_ror:8 row_mask:0xf bank_mask:0xf
	s_mov_b32 vcc_lo, 0xff00ff
	s_mov_b32 vcc_hi, 0xff00ff
	v_mov_b32_e32 v204, 0xffff8040
	v_mov_b32_e32 v205, 0x8040
	v_cndmask_b32_e64 v204, v204, 0, vcc
	v_cndmask_b32_e64 v205, 0, v205, vcc
	v_add_u32_e32 v204, v204, v207
	v_add_u32_e32 v205, v205, v207
	v_cndmask_b32_e32 v228, v232, v140, vcc
	v_cndmask_b32_e32 v229, v233, v141, vcc
	v_cndmask_b32_e32 v230, v234, v142, vcc
	v_cndmask_b32_e32 v231, v235, v143, vcc
	v_cndmask_b32_e32 v236, v240, v132, vcc
	v_cndmask_b32_e32 v237, v241, v133, vcc
	v_cndmask_b32_e32 v238, v242, v134, vcc
	v_cndmask_b32_e32 v239, v243, v135, vcc
	v_cndmask_b32_e32 v140, v140, v232, vcc
	v_cndmask_b32_e32 v141, v141, v233, vcc
	v_cndmask_b32_e32 v142, v142, v234, vcc
	v_cndmask_b32_e32 v143, v143, v235, vcc
	v_cndmask_b32_e32 v132, v132, v240, vcc
	v_cndmask_b32_e32 v133, v133, v241, vcc
	v_cndmask_b32_e32 v134, v134, v242, vcc
	v_cndmask_b32_e32 v135, v135, v243, vcc
	global_store_dwordx4 v204, v[228:231], s[84:85]
	global_store_dwordx4 v204, v[236:239], s[84:85] offset:512
	global_store_dwordx4 v205, v[140:143], s[84:85]
	global_store_dwordx4 v205, v[132:135], s[84:85] offset:512
	v_add_u32_e32 v207, 0x10000, v207
	global_load_dwordx4 v[232:235], v206, s[70:71] offset:64
	global_load_dwordx4 v[240:243], v206, s[70:71] offset:576
	global_load_dwordx4 v[228:231], v206, s[70:71]
	global_load_dwordx4 v[236:239], v206, s[70:71] offset:512
	s_waitcnt lgkmcnt(0)
	v_add_f32_e32 v211, v210, v211
	ds_bpermute_b32 v212, v215, v211
	v_add_u32_e32 v208, 0x8000, v208
	s_waitcnt lgkmcnt(0)
	v_add_f32_e32 v211, v211, v212
	s_mov_b64 exec, 0xffff
	global_store_dword v209, v211, s[72:73]
	s_mov_b64 exec, -1
	v_add_u32_e32 v209, 0x400, v209
	s_waitcnt vmcnt(9)
	v_permlane32_swap_b32_e32 v244, v248
	v_permlane32_swap_b32_e32 v245, v249
	v_permlane32_swap_b32_e32 v246, v250
	v_permlane32_swap_b32_e32 v247, v251
	v_permlane32_swap_b32_e32 v216, v220
	v_permlane32_swap_b32_e32 v217, v221
	v_permlane32_swap_b32_e32 v218, v222
	v_permlane32_swap_b32_e32 v219, v223
	v_permlane16_swap_b32_e32 v244, v248
	v_permlane16_swap_b32_e32 v245, v249
	v_permlane16_swap_b32_e32 v246, v250
	v_permlane16_swap_b32_e32 v247, v251
	v_permlane16_swap_b32_e32 v216, v220
	v_permlane16_swap_b32_e32 v217, v221
	v_permlane16_swap_b32_e32 v218, v222
	v_permlane16_swap_b32_e32 v219, v223
	v_pk_fma_f32 v[124:125], v[124:125], v[144:145], v[244:245]
	v_pk_fma_f32 v[126:127], v[126:127], v[146:147], v[246:247]
	v_mul_f32_e32 v210, v125, v125
	v_fmac_f32_e32 v210, v124, v124
	v_fmac_f32_e32 v210, v126, v126
	v_fmac_f32_e32 v210, v127, v127
	v_pk_fma_f32 v[120:121], v[120:121], v[152:153], v[248:249]
	v_pk_fma_f32 v[122:123], v[122:123], v[154:155], v[250:251]
	v_fmac_f32_e32 v210, v120, v120
	v_fmac_f32_e32 v210, v121, v121
	v_fmac_f32_e32 v210, v122, v122
	v_fmac_f32_e32 v210, v123, v123
	v_pk_fma_f32 v[116:117], v[116:117], v[148:149], v[216:217]
	v_pk_fma_f32 v[118:119], v[118:119], v[150:151], v[218:219]
	v_fmac_f32_e32 v210, v116, v116
	v_fmac_f32_e32 v210, v117, v117
	v_fmac_f32_e32 v210, v118, v118
	v_fmac_f32_e32 v210, v119, v119
	v_pk_fma_f32 v[112:113], v[112:113], v[156:157], v[220:221]
	v_pk_fma_f32 v[114:115], v[114:115], v[158:159], v[222:223]
	v_fmac_f32_e32 v210, v112, v112
	v_fmac_f32_e32 v210, v113, v113
	v_fmac_f32_e32 v210, v114, v114
	v_fmac_f32_e32 v210, v115, v115
	s_cmp_lg_u64 s[0:1], 0
	s_cbranch_scc1 .Lnoap_D_2
	v_pk_mul_f32 v[244:245], v[64:65], v[124:125]
	v_pk_mul_f32 v[246:247], v[66:67], v[126:127]
	v_pk_mul_f32 v[248:249], v[72:73], v[120:121]
	v_pk_mul_f32 v[250:251], v[74:75], v[122:123]
	v_pk_mul_f32 v[216:217], v[68:69], v[116:117]
	v_pk_mul_f32 v[218:219], v[70:71], v[118:119]
	v_pk_mul_f32 v[220:221], v[76:77], v[112:113]
	v_pk_mul_f32 v[222:223], v[78:79], v[114:115]
	v_cvt_pk_bf16_f32 v244, v244, v245
	v_cvt_pk_bf16_f32 v245, v246, v247
	v_cvt_pk_bf16_f32 v246, v248, v249
	v_cvt_pk_bf16_f32 v247, v250, v251
	global_store_dwordx4 v208, v[244:247], s[28:29]
	v_cvt_pk_bf16_f32 v216, v216, v217
	v_cvt_pk_bf16_f32 v217, v218, v219
	v_cvt_pk_bf16_f32 v218, v220, v221
	v_cvt_pk_bf16_f32 v219, v222, v223
	global_store_dwordx4 v208, v[216:219], s[28:29] offset:256
; DI u32x4 pack8(const float* v) { u32x4 w; w.x = pk2(v[0], v[1]); w.y = pk2(v[2], v[3]); w.z = pk2(v[4], v[5]); w.w = pk2(v[6], v[7]); return w; }
; #define xor16_32(s) xor16_32_l((s), fr + 16 * fq)
;     DI void operator()(AccRef acc, const Unit& u, int wr, int wc, int fr, int fq) const {
;     ...
;             for (int m = 0; m < 4; ++m) {
;                 const int row = rb + 16 * m;
;                 const float* xi = row < MP ? xin_p + (size_t)row * 1024 : xin_s + (size_t)(row - MP) * 1024;
;                 float s = 0.f;
; #pragma unroll
;                 for (int bj = 0; bj < 2; ++bj) {
;                     const int c = u.pn * 256 + bj * 128 + cl;
;                     float v[8];
; #pragma unroll
;                     for (int n = 0; n < 2; ++n) {
;                         const f32x4 x = *(const f32x4*)(xi + c + 4 * n);
;                         const f32x4 y = x + gt[bj][n] * acc[ai][bj][m][n];
;                         *(f32x4*)(xout + (size_t)row * 1024 + c + 4 * n) = y;
; #pragma unroll
;                         for (int j = 0; j < 4; ++j) { s += y[j] * y[j]; v[4 * n + j] = ap ? y[j] * gs[bj][n][j] : 0.f; }
;                     }
;                     if (ap) *(u32x4*)(ap + (size_t)row * 1024 + c) = pack8(v);
;                 }
;                 s = xor16_32(s);
;                 if (fq == 0) ssq[(size_t)row * 16 + u.pn * 4 + wc] = s;
.Lnoap_D_2:
	ds_bpermute_b32 v211, v214, v210
	v_permlane16_swap_b32_e32 v124, v120
	v_permlane16_swap_b32_e32 v125, v121
	v_permlane16_swap_b32_e32 v126, v122
	v_permlane16_swap_b32_e32 v127, v123
	v_permlane16_swap_b32_e32 v116, v112
	v_permlane16_swap_b32_e32 v117, v113
	v_permlane16_swap_b32_e32 v118, v114
	v_permlane16_swap_b32_e32 v119, v115
	v_permlane32_swap_b32_e32 v124, v120
	v_permlane32_swap_b32_e32 v125, v121
	v_permlane32_swap_b32_e32 v126, v122
	v_permlane32_swap_b32_e32 v127, v123
	v_permlane32_swap_b32_e32 v116, v112
	v_permlane32_swap_b32_e32 v117, v113
	v_permlane32_swap_b32_e32 v118, v114
	v_permlane32_swap_b32_e32 v119, v115
	s_nop 1
	v_mov_b32_dpp v248, v120 row_ror:8 row_mask:0xf bank_mask:0xf
	v_mov_b32_dpp v249, v121 row_ror:8 row_mask:0xf bank_mask:0xf
	v_mov_b32_dpp v250, v122 row_ror:8 row_mask:0xf bank_mask:0xf
	v_mov_b32_dpp v251, v123 row_ror:8 row_mask:0xf bank_mask:0xf
	v_mov_b32_dpp v220, v112 row_ror:8 row_mask:0xf bank_mask:0xf
	v_mov_b32_dpp v221, v113 row_ror:8 row_mask:0xf bank_mask:0xf
	v_mov_b32_dpp v222, v114 row_ror:8 row_mask:0xf bank_mask:0xf
	v_mov_b32_dpp v223, v115 row_ror:8 row_mask:0xf bank_mask:0xf
	s_mov_b32 vcc_lo, 0xff00ff
	s_mov_b32 vcc_hi, 0xff00ff
	v_mov_b32_e32 v204, 0xffff8040
	v_mov_b32_e32 v205, 0x8040
	v_cndmask_b32_e64 v204, v204, 0, vcc
	v_cndmask_b32_e64 v205, 0, v205, vcc
	v_add_u32_e32 v204, v204, v207
	v_add_u32_e32 v205, v205, v207
	v_cndmask_b32_e32 v244, v248, v124, vcc
	v_cndmask_b32_e32 v245, v249, v125, vcc
	v_cndmask_b32_e32 v246, v250, v126, vcc
	v_cndmask_b32_e32 v247, v251, v127, vcc
	v_cndmask_b32_e32 v216, v220, v116, vcc
	v_cndmask_b32_e32 v217, v221, v117, vcc
	v_cndmask_b32_e32 v218, v222, v118, vcc
	v_cndmask_b32_e32 v219, v223, v119, vcc
	v_cndmask_b32_e32 v124, v124, v248, vcc
	v_cndmask_b32_e32 v125, v125, v249, vcc
	v_cndmask_b32_e32 v126, v126, v250, vcc
	v_cndmask_b32_e32 v127, v127, v251, vcc
	v_cndmask_b32_e32 v116, v116, v220, vcc
	v_cndmask_b32_e32 v117, v117, v221, vcc
	v_cndmask_b32_e32 v118, v118, v222, vcc
	v_cndmask_b32_e32 v119, v119, v223, vcc
	global_store_dwordx4 v204, v[244:247], s[84:85]
	global_store_dwordx4 v204, v[216:219], s[84:85] offset:512
	global_store_dwordx4 v205, v[124:127], s[84:85]
	global_store_dwordx4 v205, v[116:119], s[84:85] offset:512
	v_add_u32_e32 v207, 0x10000, v207
	v_add_u32_e32 v206, 0x10000, v206
	global_load_dwordx4 v[248:251], v206, s[70:71] offset:64
	global_load_dwordx4 v[220:223], v206, s[70:71] offset:576
	global_load_dwordx4 v[244:247], v206, s[70:71]
	global_load_dwordx4 v[216:219], v206, s[70:71] offset:512
	s_waitcnt lgkmcnt(0)
	v_add_f32_e32 v211, v210, v211
	ds_bpermute_b32 v212, v215, v211
	v_add_u32_e32 v208, 0x8000, v208
	s_waitcnt lgkmcnt(0)
	v_add_f32_e32 v211, v211, v212
	s_mov_b64 exec, 0xffff
	global_store_dword v209, v211, s[72:73]
	s_mov_b64 exec, -1
	v_add_u32_e32 v209, 0x400, v209
	s_waitcnt vmcnt(10)
	v_permlane32_swap_b32_e32 v228, v232
	v_permlane32_swap_b32_e32 v229, v233
	v_permlane32_swap_b32_e32 v230, v234
	v_permlane32_swap_b32_e32 v231, v235
	v_permlane32_swap_b32_e32 v236, v240
	v_permlane32_swap_b32_e32 v237, v241
	v_permlane32_swap_b32_e32 v238, v242
	v_permlane32_swap_b32_e32 v239, v243
	v_permlane16_swap_b32_e32 v228, v232
	v_permlane16_swap_b32_e32 v229, v233
	v_permlane16_swap_b32_e32 v230, v234
	v_permlane16_swap_b32_e32 v231, v235
	v_permlane16_swap_b32_e32 v236, v240
	v_permlane16_swap_b32_e32 v237, v241
	v_permlane16_swap_b32_e32 v238, v242
	v_permlane16_swap_b32_e32 v239, v243
	v_pk_fma_f32 v[108:109], v[108:109], v[144:145], v[228:229]
	v_pk_fma_f32 v[110:111], v[110:111], v[146:147], v[230:231]
	v_mul_f32_e32 v210, v109, v109
	v_fmac_f32_e32 v210, v108, v108
	v_fmac_f32_e32 v210, v110, v110
	v_fmac_f32_e32 v210, v111, v111
	v_pk_fma_f32 v[104:105], v[104:105], v[152:153], v[232:233]
	v_pk_fma_f32 v[106:107], v[106:107], v[154:155], v[234:235]
	v_fmac_f32_e32 v210, v104, v104
	v_fmac_f32_e32 v210, v105, v105
	v_fmac_f32_e32 v210, v106, v106
	v_fmac_f32_e32 v210, v107, v107
	v_pk_fma_f32 v[100:101], v[100:101], v[148:149], v[236:237]
	v_pk_fma_f32 v[102:103], v[102:103], v[150:151], v[238:239]
	v_fmac_f32_e32 v210, v100, v100
	v_fmac_f32_e32 v210, v101, v101
	v_fmac_f32_e32 v210, v102, v102
	v_fmac_f32_e32 v210, v103, v103
	v_pk_fma_f32 v[96:97], v[96:97], v[156:157], v[240:241]
	v_pk_fma_f32 v[98:99], v[98:99], v[158:159], v[242:243]
	v_fmac_f32_e32 v210, v96, v96
	v_fmac_f32_e32 v210, v97, v97
	v_fmac_f32_e32 v210, v98, v98
	v_fmac_f32_e32 v210, v99, v99
	s_cmp_lg_u64 s[0:1], 0
	s_cbranch_scc1 .Lnoap_D_3
	v_pk_mul_f32 v[228:229], v[64:65], v[108:109]
	v_pk_mul_f32 v[230:231], v[66:67], v[110:111]
	v_pk_mul_f32 v[232:233], v[72:73], v[104:105]
	v_pk_mul_f32 v[234:235], v[74:75], v[106:107]
	v_pk_mul_f32 v[236:237], v[68:69], v[100:101]
	v_pk_mul_f32 v[238:239], v[70:71], v[102:103]
	v_pk_mul_f32 v[240:241], v[76:77], v[96:97]
	v_pk_mul_f32 v[242:243], v[78:79], v[98:99]
	v_cvt_pk_bf16_f32 v228, v228, v229
	v_cvt_pk_bf16_f32 v229, v230, v231
	v_cvt_pk_bf16_f32 v230, v232, v233
	v_cvt_pk_bf16_f32 v231, v234, v235
	global_store_dwordx4 v208, v[228:231], s[28:29]
	v_cvt_pk_bf16_f32 v236, v236, v237
	v_cvt_pk_bf16_f32 v237, v238, v239
	v_cvt_pk_bf16_f32 v238, v240, v241
	v_cvt_pk_bf16_f32 v239, v242, v243
	global_store_dwordx4 v208, v[236:239], s[28:29] offset:256
; DI u32x4 pack8(const float* v) { u32x4 w; w.x = pk2(v[0], v[1]); w.y = pk2(v[2], v[3]); w.z = pk2(v[4], v[5]); w.w = pk2(v[6], v[7]); return w; }
; #define xor16_32(s) xor16_32_l((s), fr + 16 * fq)
;     DI void operator()(AccRef acc, const Unit& u, int wr, int wc, int fr, int fq) const {
;     ...
;             for (int m = 0; m < 4; ++m) {
;                 const int row = rb + 16 * m;
;                 const float* xi = row < MP ? xin_p + (size_t)row * 1024 : xin_s + (size_t)(row - MP) * 1024;
;                 float s = 0.f;
; #pragma unroll
;                 for (int bj = 0; bj < 2; ++bj) {
;                     const int c = u.pn * 256 + bj * 128 + cl;
;                     float v[8];
; #pragma unroll
;                     for (int n = 0; n < 2; ++n) {
;                         const f32x4 x = *(const f32x4*)(xi + c + 4 * n);
;                         const f32x4 y = x + gt[bj][n] * acc[ai][bj][m][n];
;                         *(f32x4*)(xout + (size_t)row * 1024 + c + 4 * n) = y;
; #pragma unroll
;                         for (int j = 0; j < 4; ++j) { s += y[j] * y[j]; v[4 * n + j] = ap ? y[j] * gs[bj][n][j] : 0.f; }
;                     }
;                     if (ap) *(u32x4*)(ap + (size_t)row * 1024 + c) = pack8(v);
;                 }
;                 s = xor16_32(s);
;                 if (fq == 0) ssq[(size_t)row * 16 + u.pn * 4 + wc] = s;
.Lnoap_D_3:
	ds_bpermute_b32 v211, v214, v210
	v_permlane16_swap_b32_e32 v108, v104
	v_permlane16_swap_b32_e32 v109, v105
	v_permlane16_swap_b32_e32 v110, v106
	v_permlane16_swap_b32_e32 v111, v107
	v_permlane16_swap_b32_e32 v100, v96
	v_permlane16_swap_b32_e32 v101, v97
	v_permlane16_swap_b32_e32 v102, v98
	v_permlane16_swap_b32_e32 v103, v99
	v_permlane32_swap_b32_e32 v108, v104
	v_permlane32_swap_b32_e32 v109, v105
	v_permlane32_swap_b32_e32 v110, v106
	v_permlane32_swap_b32_e32 v111, v107
	v_permlane32_swap_b32_e32 v100, v96
	v_permlane32_swap_b32_e32 v101, v97
	v_permlane32_swap_b32_e32 v102, v98
	v_permlane32_swap_b32_e32 v103, v99
	s_nop 1
	v_mov_b32_dpp v232, v104 row_ror:8 row_mask:0xf bank_mask:0xf
	v_mov_b32_dpp v233, v105 row_ror:8 row_mask:0xf bank_mask:0xf
	v_mov_b32_dpp v234, v106 row_ror:8 row_mask:0xf bank_mask:0xf
	v_mov_b32_dpp v235, v107 row_ror:8 row_mask:0xf bank_mask:0xf
	v_mov_b32_dpp v240, v96 row_ror:8 row_mask:0xf bank_mask:0xf
	v_mov_b32_dpp v241, v97 row_ror:8 row_mask:0xf bank_mask:0xf
	v_mov_b32_dpp v242, v98 row_ror:8 row_mask:0xf bank_mask:0xf
	v_mov_b32_dpp v243, v99 row_ror:8 row_mask:0xf bank_mask:0xf
	s_mov_b32 vcc_lo, 0xff00ff
	s_mov_b32 vcc_hi, 0xff00ff
	v_mov_b32_e32 v204, 0xffff8040
	v_mov_b32_e32 v205, 0x8040
	v_cndmask_b32_e64 v204, v204, 0, vcc
	v_cndmask_b32_e64 v205, 0, v205, vcc
	v_add_u32_e32 v204, v204, v207
	v_add_u32_e32 v205, v205, v207
	v_cndmask_b32_e32 v228, v232, v108, vcc
	v_cndmask_b32_e32 v229, v233, v109, vcc
	v_cndmask_b32_e32 v230, v234, v110, vcc
	v_cndmask_b32_e32 v231, v235, v111, vcc
	v_cndmask_b32_e32 v236, v240, v100, vcc
	v_cndmask_b32_e32 v237, v241, v101, vcc
	v_cndmask_b32_e32 v238, v242, v102, vcc
	v_cndmask_b32_e32 v239, v243, v103, vcc
	v_cndmask_b32_e32 v108, v108, v232, vcc
	v_cndmask_b32_e32 v109, v109, v233, vcc
	v_cndmask_b32_e32 v110, v110, v234, vcc
	v_cndmask_b32_e32 v111, v111, v235, vcc
	v_cndmask_b32_e32 v100, v100, v240, vcc
	v_cndmask_b32_e32 v101, v101, v241, vcc
	v_cndmask_b32_e32 v102, v102, v242, vcc
	v_cndmask_b32_e32 v103, v103, v243, vcc
	global_store_dwordx4 v204, v[228:231], s[84:85]
	global_store_dwordx4 v204, v[236:239], s[84:85] offset:512
	global_store_dwordx4 v205, v[108:111], s[84:85]
	global_store_dwordx4 v205, v[100:103], s[84:85] offset:512
	v_add_u32_e32 v207, 0x10000, v207
	v_add_u32_e32 v206, 0x50000, v206
	global_load_dwordx4 v[232:235], v206, s[70:71] offset:64
	global_load_dwordx4 v[240:243], v206, s[70:71] offset:576
	global_load_dwordx4 v[228:231], v206, s[70:71]
	global_load_dwordx4 v[236:239], v206, s[70:71] offset:512
	s_waitcnt lgkmcnt(0)
	v_add_f32_e32 v211, v210, v211
	ds_bpermute_b32 v212, v215, v211
	v_add_u32_e32 v208, 0x8000, v208
	s_waitcnt lgkmcnt(0)
	v_add_f32_e32 v211, v211, v212
	s_mov_b64 exec, 0xffff
	global_store_dword v209, v211, s[72:73]
	s_mov_b64 exec, -1
	v_add_u32_e32 v209, 0x400, v209
	s_waitcnt vmcnt(10)
	v_permlane32_swap_b32_e32 v244, v248
	v_permlane32_swap_b32_e32 v245, v249
	v_permlane32_swap_b32_e32 v246, v250
	v_permlane32_swap_b32_e32 v247, v251
	v_permlane32_swap_b32_e32 v216, v220
	v_permlane32_swap_b32_e32 v217, v221
	v_permlane32_swap_b32_e32 v218, v222
	v_permlane32_swap_b32_e32 v219, v223
	v_permlane16_swap_b32_e32 v244, v248
	v_permlane16_swap_b32_e32 v245, v249
	v_permlane16_swap_b32_e32 v246, v250
	v_permlane16_swap_b32_e32 v247, v251
	v_permlane16_swap_b32_e32 v216, v220
	v_permlane16_swap_b32_e32 v217, v221
	v_permlane16_swap_b32_e32 v218, v222
	v_permlane16_swap_b32_e32 v219, v223
	v_pk_fma_f32 v[92:93], v[92:93], v[144:145], v[244:245]
	v_pk_fma_f32 v[94:95], v[94:95], v[146:147], v[246:247]
	v_mul_f32_e32 v210, v93, v93
	v_fmac_f32_e32 v210, v92, v92
	v_fmac_f32_e32 v210, v94, v94
	v_fmac_f32_e32 v210, v95, v95
	v_pk_fma_f32 v[88:89], v[88:89], v[152:153], v[248:249]
	v_pk_fma_f32 v[90:91], v[90:91], v[154:155], v[250:251]
	v_fmac_f32_e32 v210, v88, v88
	v_fmac_f32_e32 v210, v89, v89
	v_fmac_f32_e32 v210, v90, v90
	v_fmac_f32_e32 v210, v91, v91
	v_pk_fma_f32 v[84:85], v[84:85], v[148:149], v[216:217]
	v_pk_fma_f32 v[86:87], v[86:87], v[150:151], v[218:219]
	v_fmac_f32_e32 v210, v84, v84
	v_fmac_f32_e32 v210, v85, v85
	v_fmac_f32_e32 v210, v86, v86
	v_fmac_f32_e32 v210, v87, v87
	v_pk_fma_f32 v[80:81], v[80:81], v[156:157], v[220:221]
	v_pk_fma_f32 v[82:83], v[82:83], v[158:159], v[222:223]
	v_fmac_f32_e32 v210, v80, v80
	v_fmac_f32_e32 v210, v81, v81
	v_fmac_f32_e32 v210, v82, v82
	v_fmac_f32_e32 v210, v83, v83
	s_cmp_lg_u64 s[0:1], 0
	s_cbranch_scc1 .Lnoap_D_4
	v_pk_mul_f32 v[244:245], v[64:65], v[92:93]
	v_pk_mul_f32 v[246:247], v[66:67], v[94:95]
	v_pk_mul_f32 v[248:249], v[72:73], v[88:89]
	v_pk_mul_f32 v[250:251], v[74:75], v[90:91]
	v_pk_mul_f32 v[216:217], v[68:69], v[84:85]
	v_pk_mul_f32 v[218:219], v[70:71], v[86:87]
	v_pk_mul_f32 v[220:221], v[76:77], v[80:81]
	v_pk_mul_f32 v[222:223], v[78:79], v[82:83]
	v_cvt_pk_bf16_f32 v244, v244, v245
	v_cvt_pk_bf16_f32 v245, v246, v247
	v_cvt_pk_bf16_f32 v246, v248, v249
	v_cvt_pk_bf16_f32 v247, v250, v251
	global_store_dwordx4 v208, v[244:247], s[28:29]
	v_cvt_pk_bf16_f32 v216, v216, v217
	v_cvt_pk_bf16_f32 v217, v218, v219
	v_cvt_pk_bf16_f32 v218, v220, v221
	v_cvt_pk_bf16_f32 v219, v222, v223
	global_store_dwordx4 v208, v[216:219], s[28:29] offset:256
; DI u32x4 pack8(const float* v) { u32x4 w; w.x = pk2(v[0], v[1]); w.y = pk2(v[2], v[3]); w.z = pk2(v[4], v[5]); w.w = pk2(v[6], v[7]); return w; }
; #define xor16_32(s) xor16_32_l((s), fr + 16 * fq)
;     DI void operator()(AccRef acc, const Unit& u, int wr, int wc, int fr, int fq) const {
;     ...
;             const int rb = u.pm * 256 + ai * 128 + wr * 64 + fr;
;             int mb, pos0, kv0; row_info(rb, mb, pos0, kv0);
;             f32x4 gt[2][2], gs[2][2];
; #pragma unroll
;             for (int bj = 0; bj < 2; ++bj)
; #pragma unroll
;                 for (int n = 0; n < 2; ++n) {
;                     const int c = u.pn * 256 + bj * 128 + cl + 4 * n;
;                     gt[bj][n] = *(const f32x4*)(gate + (size_t)mb * 6144 + c);
;                     if (ap) { const f32x4 g = *(const f32x4*)(gn + c), s = *(const f32x4*)(scn + (size_t)mb * 6144 + c); gs[bj][n] = g * (s + 1.f); }
;                 }
;     ...
;             for (int m = 0; m < 4; ++m) {
;                 const int row = rb + 16 * m;
;                 const float* xi = row < MP ? xin_p + (size_t)row * 1024 : xin_s + (size_t)(row - MP) * 1024;
;                 float s = 0.f;
; #pragma unroll
;                 for (int bj = 0; bj < 2; ++bj) {
;                     const int c = u.pn * 256 + bj * 128 + cl;
;                     float v[8];
; #pragma unroll
;                     for (int n = 0; n < 2; ++n) {
;                         const f32x4 x = *(const f32x4*)(xi + c + 4 * n);
;                         const f32x4 y = x + gt[bj][n] * acc[ai][bj][m][n];
;                         *(f32x4*)(xout + (size_t)row * 1024 + c + 4 * n) = y;
; #pragma unroll
;                         for (int j = 0; j < 4; ++j) { s += y[j] * y[j]; v[4 * n + j] = ap ? y[j] * gs[bj][n][j] : 0.f; }
;                     }
;                     if (ap) *(u32x4*)(ap + (size_t)row * 1024 + c) = pack8(v);
;                 }
;                 s = xor16_32(s);
;                 if (fq == 0) ssq[(size_t)row * 16 + u.pn * 4 + wc] = s;
.Lnoap_D_4:
	ds_bpermute_b32 v211, v214, v210
	v_permlane16_swap_b32_e32 v92, v88
	v_permlane16_swap_b32_e32 v93, v89
	v_permlane16_swap_b32_e32 v94, v90
	v_permlane16_swap_b32_e32 v95, v91
	v_permlane16_swap_b32_e32 v84, v80
	v_permlane16_swap_b32_e32 v85, v81
	v_permlane16_swap_b32_e32 v86, v82
	v_permlane16_swap_b32_e32 v87, v83
	v_permlane32_swap_b32_e32 v92, v88
	v_permlane32_swap_b32_e32 v93, v89
	v_permlane32_swap_b32_e32 v94, v90
	v_permlane32_swap_b32_e32 v95, v91
	v_permlane32_swap_b32_e32 v84, v80
	v_permlane32_swap_b32_e32 v85, v81
	v_permlane32_swap_b32_e32 v86, v82
	v_permlane32_swap_b32_e32 v87, v83
	s_nop 1
	v_mov_b32_dpp v248, v88 row_ror:8 row_mask:0xf bank_mask:0xf
	v_mov_b32_dpp v249, v89 row_ror:8 row_mask:0xf bank_mask:0xf
	v_mov_b32_dpp v250, v90 row_ror:8 row_mask:0xf bank_mask:0xf
	v_mov_b32_dpp v251, v91 row_ror:8 row_mask:0xf bank_mask:0xf
	v_mov_b32_dpp v220, v80 row_ror:8 row_mask:0xf bank_mask:0xf
	v_mov_b32_dpp v221, v81 row_ror:8 row_mask:0xf bank_mask:0xf
	v_mov_b32_dpp v222, v82 row_ror:8 row_mask:0xf bank_mask:0xf
	v_mov_b32_dpp v223, v83 row_ror:8 row_mask:0xf bank_mask:0xf
	s_mov_b32 vcc_lo, 0xff00ff
	s_mov_b32 vcc_hi, 0xff00ff
	v_mov_b32_e32 v204, 0xffff8040
	v_mov_b32_e32 v205, 0x8040
	v_cndmask_b32_e64 v204, v204, 0, vcc
	v_cndmask_b32_e64 v205, 0, v205, vcc
	v_add_u32_e32 v204, v204, v207
	v_add_u32_e32 v205, v205, v207
	v_cndmask_b32_e32 v244, v248, v92, vcc
	v_cndmask_b32_e32 v245, v249, v93, vcc
	v_cndmask_b32_e32 v246, v250, v94, vcc
	v_cndmask_b32_e32 v247, v251, v95, vcc
	v_cndmask_b32_e32 v216, v220, v84, vcc
	v_cndmask_b32_e32 v217, v221, v85, vcc
	v_cndmask_b32_e32 v218, v222, v86, vcc
	v_cndmask_b32_e32 v219, v223, v87, vcc
	v_cndmask_b32_e32 v92, v92, v248, vcc
	v_cndmask_b32_e32 v93, v93, v249, vcc
	v_cndmask_b32_e32 v94, v94, v250, vcc
	v_cndmask_b32_e32 v95, v95, v251, vcc
	v_cndmask_b32_e32 v84, v84, v220, vcc
	v_cndmask_b32_e32 v85, v85, v221, vcc
	v_cndmask_b32_e32 v86, v86, v222, vcc
	v_cndmask_b32_e32 v87, v87, v223, vcc
	global_store_dwordx4 v204, v[244:247], s[84:85]
	global_store_dwordx4 v204, v[216:219], s[84:85] offset:512
	global_store_dwordx4 v205, v[92:95], s[84:85]
	global_store_dwordx4 v205, v[84:87], s[84:85] offset:512
	v_add_u32_e32 v207, 0x50000, v207
	v_add_u32_e32 v206, 0x10000, v206
	global_load_dwordx4 v[248:251], v206, s[70:71] offset:64
	global_load_dwordx4 v[220:223], v206, s[70:71] offset:576
	global_load_dwordx4 v[244:247], v206, s[70:71]
	global_load_dwordx4 v[216:219], v206, s[70:71] offset:512
	s_waitcnt lgkmcnt(0)
	v_add_f32_e32 v211, v210, v211
	ds_bpermute_b32 v212, v215, v211
	v_add_u32_e32 v208, 0x28000, v208
	s_waitcnt lgkmcnt(0)
	v_add_f32_e32 v211, v211, v212
	s_mov_b64 exec, 0xffff
	global_store_dword v209, v211, s[72:73]
	s_mov_b64 exec, -1
	v_add_u32_e32 v209, 0x1400, v209
	v_add_u32_e32 v224, 0xffffc080, v176
	v_add_u32_e32 v96, 0x80, v176
	s_waitcnt lgkmcnt(0)
	v_lshrrev_b32_e32 v81, 6, v224
	v_cmp_gt_i32_e32 vcc, s94, v96
	v_ashrrev_i32_e32 v80, 11, v96
	v_add_u32_e32 v81, 8, v81
	v_cndmask_b32_e32 v84, v81, v80, vcc
	v_mov_b64_e32 v[80:81], s[18:19]
	v_mad_i64_i32 v[80:81], s[12:13], v84, s75, v[80:81]
	v_mov_b64_e32 v[82:83], s[26:27]
	v_lshl_add_u64 v[92:93], v[172:173], 2, v[80:81]
	v_mad_i64_i32 v[84:85], s[12:13], v84, s75, v[82:83]
	global_load_dwordx4 v[80:83], v[92:93], off
	s_movk_i32 s6, 0x3fff
	v_cmp_lt_i32_e64 s[6:7], s6, v96
	s_and_b64 vcc, exec, s[0:1]
	s_cbranch_vccnz .LBB0_2101
	v_lshl_add_u64 v[64:65], v[84:85], 0, v[174:175]
	global_load_dwordx4 v[64:67], v[64:65], off
	s_nop 0
	global_load_dwordx4 v[86:89], v[178:179], off
	s_waitcnt vmcnt(1)
	v_pk_add_f32 v[66:67], v[66:67], 1.0 op_sel_hi:[1,0]
	v_pk_add_f32 v[64:65], v[64:65], 1.0 op_sel_hi:[1,0]
	s_waitcnt vmcnt(0)
	v_pk_mul_f32 v[66:67], v[88:89], v[66:67]
	v_pk_mul_f32 v[64:65], v[86:87], v[64:65]
	global_load_dwordx4 v[88:91], v[92:93], off offset:16
	s_and_b64 vcc, exec, s[0:1]
	v_lshl_add_u64 v[98:99], v[172:173], 2, v[84:85]
	s_cbranch_vccz .LBB0_2102

; DI u32x4 pack8(const float* v) { u32x4 w; w.x = pk2(v[0], v[1]); w.y = pk2(v[2], v[3]); w.z = pk2(v[4], v[5]); w.w = pk2(v[6], v[7]); return w; }
; #define xor16_32(s) xor16_32_l((s), fr + 16 * fq)
;     DI void operator()(AccRef acc, const Unit& u, int wr, int wc, int fr, int fq) const {
;     ...
;             for (int m = 0; m < 4; ++m) {
;                 const int row = rb + 16 * m;
;                 const float* xi = row < MP ? xin_p + (size_t)row * 1024 : xin_s + (size_t)(row - MP) * 1024;
;                 float s = 0.f;
; #pragma unroll
;                 for (int bj = 0; bj < 2; ++bj) {
;                     const int c = u.pn * 256 + bj * 128 + cl;
;                     float v[8];
; #pragma unroll
;                     for (int n = 0; n < 2; ++n) {
;                         const f32x4 x = *(const f32x4*)(xi + c + 4 * n);
;                         const f32x4 y = x + gt[bj][n] * acc[ai][bj][m][n];
;                         *(f32x4*)(xout + (size_t)row * 1024 + c + 4 * n) = y;
; #pragma unroll
;                         for (int j = 0; j < 4; ++j) { s += y[j] * y[j]; v[4 * n + j] = ap ? y[j] * gs[bj][n][j] : 0.f; }
;                     }
;                     if (ap) *(u32x4*)(ap + (size_t)row * 1024 + c) = pack8(v);
;                 }
;                 s = xor16_32(s);
;                 if (fq == 0) ssq[(size_t)row * 16 + u.pn * 4 + wc] = s;
.Lnoap_D_5:
	ds_bpermute_b32 v211, v214, v210
	v_permlane16_swap_b32_e32 v60, v56
	v_permlane16_swap_b32_e32 v61, v57
	v_permlane16_swap_b32_e32 v62, v58
	v_permlane16_swap_b32_e32 v63, v59
	v_permlane16_swap_b32_e32 v52, v48
	v_permlane16_swap_b32_e32 v53, v49
	v_permlane16_swap_b32_e32 v54, v50
	v_permlane16_swap_b32_e32 v55, v51
	v_permlane32_swap_b32_e32 v60, v56
	v_permlane32_swap_b32_e32 v61, v57
	v_permlane32_swap_b32_e32 v62, v58
	v_permlane32_swap_b32_e32 v63, v59
	v_permlane32_swap_b32_e32 v52, v48
	v_permlane32_swap_b32_e32 v53, v49
	v_permlane32_swap_b32_e32 v54, v50
	v_permlane32_swap_b32_e32 v55, v51
	s_nop 1
	v_mov_b32_dpp v232, v56 row_ror:8 row_mask:0xf bank_mask:0xf
	v_mov_b32_dpp v233, v57 row_ror:8 row_mask:0xf bank_mask:0xf
	v_mov_b32_dpp v234, v58 row_ror:8 row_mask:0xf bank_mask:0xf
	v_mov_b32_dpp v235, v59 row_ror:8 row_mask:0xf bank_mask:0xf
	v_mov_b32_dpp v240, v48 row_ror:8 row_mask:0xf bank_mask:0xf
	v_mov_b32_dpp v241, v49 row_ror:8 row_mask:0xf bank_mask:0xf
	v_mov_b32_dpp v242, v50 row_ror:8 row_mask:0xf bank_mask:0xf
	v_mov_b32_dpp v243, v51 row_ror:8 row_mask:0xf bank_mask:0xf
	s_mov_b32 vcc_lo, 0xff00ff
	s_mov_b32 vcc_hi, 0xff00ff
	v_mov_b32_e32 v204, 0xffff8040
	v_mov_b32_e32 v205, 0x8040
	v_cndmask_b32_e64 v204, v204, 0, vcc
	v_cndmask_b32_e64 v205, 0, v205, vcc
	v_add_u32_e32 v204, v204, v207
	v_add_u32_e32 v205, v205, v207
	v_cndmask_b32_e32 v228, v232, v60, vcc
	v_cndmask_b32_e32 v229, v233, v61, vcc
	v_cndmask_b32_e32 v230, v234, v62, vcc
	v_cndmask_b32_e32 v231, v235, v63, vcc
	v_cndmask_b32_e32 v236, v240, v52, vcc
	v_cndmask_b32_e32 v237, v241, v53, vcc
	v_cndmask_b32_e32 v238, v242, v54, vcc
	v_cndmask_b32_e32 v239, v243, v55, vcc
	v_cndmask_b32_e32 v60, v60, v232, vcc
	v_cndmask_b32_e32 v61, v61, v233, vcc
	v_cndmask_b32_e32 v62, v62, v234, vcc
	v_cndmask_b32_e32 v63, v63, v235, vcc
	v_cndmask_b32_e32 v52, v52, v240, vcc
	v_cndmask_b32_e32 v53, v53, v241, vcc
	v_cndmask_b32_e32 v54, v54, v242, vcc
	v_cndmask_b32_e32 v55, v55, v243, vcc
	global_store_dwordx4 v204, v[228:231], s[84:85]
	global_store_dwordx4 v204, v[236:239], s[84:85] offset:512
	global_store_dwordx4 v205, v[60:63], s[84:85]
	global_store_dwordx4 v205, v[52:55], s[84:85] offset:512
	v_add_u32_e32 v207, 0x10000, v207
	v_add_u32_e32 v206, 0x10000, v206
	global_load_dwordx4 v[232:235], v206, s[70:71] offset:64
	global_load_dwordx4 v[240:243], v206, s[70:71] offset:576
	global_load_dwordx4 v[228:231], v206, s[70:71]
	global_load_dwordx4 v[236:239], v206, s[70:71] offset:512
	s_waitcnt lgkmcnt(0)
	v_add_f32_e32 v211, v210, v211
	ds_bpermute_b32 v212, v215, v211
	v_add_u32_e32 v208, 0x8000, v208
	s_waitcnt lgkmcnt(0)
	v_add_f32_e32 v211, v211, v212
	s_mov_b64 exec, 0xffff
	global_store_dword v209, v211, s[72:73]
	s_mov_b64 exec, -1
	v_add_u32_e32 v209, 0x400, v209
	v_permlane32_swap_b32_e32 v244, v248
	v_permlane32_swap_b32_e32 v245, v249
	v_permlane32_swap_b32_e32 v246, v250
	v_permlane32_swap_b32_e32 v247, v251
	v_permlane32_swap_b32_e32 v216, v220
	v_permlane32_swap_b32_e32 v217, v221
	v_permlane32_swap_b32_e32 v218, v222
	v_permlane32_swap_b32_e32 v219, v223
	v_permlane16_swap_b32_e32 v244, v248
	v_permlane16_swap_b32_e32 v245, v249
	v_permlane16_swap_b32_e32 v246, v250
	v_permlane16_swap_b32_e32 v247, v251
	v_permlane16_swap_b32_e32 v216, v220
	v_permlane16_swap_b32_e32 v217, v221
	v_permlane16_swap_b32_e32 v218, v222
	v_permlane16_swap_b32_e32 v219, v223
	v_pk_fma_f32 v[44:45], v[44:45], v[80:81], v[244:245]
	v_pk_fma_f32 v[46:47], v[46:47], v[82:83], v[246:247]
	v_mul_f32_e32 v210, v45, v45
	v_fmac_f32_e32 v210, v44, v44
	v_fmac_f32_e32 v210, v46, v46
	v_fmac_f32_e32 v210, v47, v47
	v_pk_fma_f32 v[40:41], v[40:41], v[88:89], v[248:249]
	v_pk_fma_f32 v[42:43], v[42:43], v[90:91], v[250:251]
	v_fmac_f32_e32 v210, v40, v40
	v_fmac_f32_e32 v210, v41, v41
	v_fmac_f32_e32 v210, v42, v42
	v_fmac_f32_e32 v210, v43, v43
	v_pk_fma_f32 v[36:37], v[36:37], v[84:85], v[216:217]
	v_pk_fma_f32 v[38:39], v[38:39], v[86:87], v[218:219]
	v_fmac_f32_e32 v210, v36, v36
	v_fmac_f32_e32 v210, v37, v37
	v_fmac_f32_e32 v210, v38, v38
	v_fmac_f32_e32 v210, v39, v39
	v_pk_fma_f32 v[32:33], v[32:33], v[92:93], v[220:221]
	v_pk_fma_f32 v[34:35], v[34:35], v[94:95], v[222:223]
	v_fmac_f32_e32 v210, v32, v32
	v_fmac_f32_e32 v210, v33, v33
	v_fmac_f32_e32 v210, v34, v34
	v_fmac_f32_e32 v210, v35, v35
	s_cmp_lg_u64 s[0:1], 0
	s_cbranch_scc1 .Lnoap_D_6
	v_pk_mul_f32 v[244:245], v[64:65], v[44:45]
	v_pk_mul_f32 v[246:247], v[66:67], v[46:47]
	v_pk_mul_f32 v[248:249], v[72:73], v[40:41]
	v_pk_mul_f32 v[250:251], v[74:75], v[42:43]
	v_pk_mul_f32 v[216:217], v[68:69], v[36:37]
	v_pk_mul_f32 v[218:219], v[70:71], v[38:39]
	v_pk_mul_f32 v[220:221], v[76:77], v[32:33]
	v_pk_mul_f32 v[222:223], v[78:79], v[34:35]
	v_cvt_pk_bf16_f32 v244, v244, v245
	v_cvt_pk_bf16_f32 v245, v246, v247
	v_cvt_pk_bf16_f32 v246, v248, v249
	v_cvt_pk_bf16_f32 v247, v250, v251
	global_store_dwordx4 v208, v[244:247], s[28:29]
	v_cvt_pk_bf16_f32 v216, v216, v217
	v_cvt_pk_bf16_f32 v217, v218, v219
	v_cvt_pk_bf16_f32 v218, v220, v221
	v_cvt_pk_bf16_f32 v219, v222, v223
	global_store_dwordx4 v208, v[216:219], s[28:29] offset:256
; DI u32x4 pack8(const float* v) { u32x4 w; w.x = pk2(v[0], v[1]); w.y = pk2(v[2], v[3]); w.z = pk2(v[4], v[5]); w.w = pk2(v[6], v[7]); return w; }
; #define xor16_32(s) xor16_32_l((s), fr + 16 * fq)
;     DI void operator()(AccRef acc, const Unit& u, int wr, int wc, int fr, int fq) const {
;     ...
;             for (int m = 0; m < 4; ++m) {
;                 const int row = rb + 16 * m;
;                 const float* xi = row < MP ? xin_p + (size_t)row * 1024 : xin_s + (size_t)(row - MP) * 1024;
;                 float s = 0.f;
; #pragma unroll
;                 for (int bj = 0; bj < 2; ++bj) {
;                     const int c = u.pn * 256 + bj * 128 + cl;
;                     float v[8];
; #pragma unroll
;                     for (int n = 0; n < 2; ++n) {
;                         const f32x4 x = *(const f32x4*)(xi + c + 4 * n);
;                         const f32x4 y = x + gt[bj][n] * acc[ai][bj][m][n];
;                         *(f32x4*)(xout + (size_t)row * 1024 + c + 4 * n) = y;
; #pragma unroll
;                         for (int j = 0; j < 4; ++j) { s += y[j] * y[j]; v[4 * n + j] = ap ? y[j] * gs[bj][n][j] : 0.f; }
;                     }
;                     if (ap) *(u32x4*)(ap + (size_t)row * 1024 + c) = pack8(v);
;                 }
;                 s = xor16_32(s);
;                 if (fq == 0) ssq[(size_t)row * 16 + u.pn * 4 + wc] = s;
.Lnoap_D_6:
	ds_bpermute_b32 v211, v214, v210
	v_permlane16_swap_b32_e32 v44, v40
	v_permlane16_swap_b32_e32 v45, v41
	v_permlane16_swap_b32_e32 v46, v42
	v_permlane16_swap_b32_e32 v47, v43
	v_permlane16_swap_b32_e32 v36, v32
	v_permlane16_swap_b32_e32 v37, v33
	v_permlane16_swap_b32_e32 v38, v34
	v_permlane16_swap_b32_e32 v39, v35
	v_permlane32_swap_b32_e32 v44, v40
	v_permlane32_swap_b32_e32 v45, v41
	v_permlane32_swap_b32_e32 v46, v42
	v_permlane32_swap_b32_e32 v47, v43
	v_permlane32_swap_b32_e32 v36, v32
	v_permlane32_swap_b32_e32 v37, v33
	v_permlane32_swap_b32_e32 v38, v34
	v_permlane32_swap_b32_e32 v39, v35
	s_nop 1
	v_mov_b32_dpp v248, v40 row_ror:8 row_mask:0xf bank_mask:0xf
	v_mov_b32_dpp v249, v41 row_ror:8 row_mask:0xf bank_mask:0xf
	v_mov_b32_dpp v250, v42 row_ror:8 row_mask:0xf bank_mask:0xf
	v_mov_b32_dpp v251, v43 row_ror:8 row_mask:0xf bank_mask:0xf
	v_mov_b32_dpp v220, v32 row_ror:8 row_mask:0xf bank_mask:0xf
	v_mov_b32_dpp v221, v33 row_ror:8 row_mask:0xf bank_mask:0xf
	v_mov_b32_dpp v222, v34 row_ror:8 row_mask:0xf bank_mask:0xf
	v_mov_b32_dpp v223, v35 row_ror:8 row_mask:0xf bank_mask:0xf
	s_mov_b32 vcc_lo, 0xff00ff
	s_mov_b32 vcc_hi, 0xff00ff
	v_mov_b32_e32 v204, 0xffff8040
	v_mov_b32_e32 v205, 0x8040
	v_cndmask_b32_e64 v204, v204, 0, vcc
	v_cndmask_b32_e64 v205, 0, v205, vcc
	v_add_u32_e32 v204, v204, v207
	v_add_u32_e32 v205, v205, v207
	v_cndmask_b32_e32 v244, v248, v44, vcc
	v_cndmask_b32_e32 v245, v249, v45, vcc
	v_cndmask_b32_e32 v246, v250, v46, vcc
	v_cndmask_b32_e32 v247, v251, v47, vcc
	v_cndmask_b32_e32 v216, v220, v36, vcc
	v_cndmask_b32_e32 v217, v221, v37, vcc
	v_cndmask_b32_e32 v218, v222, v38, vcc
	v_cndmask_b32_e32 v219, v223, v39, vcc
	v_cndmask_b32_e32 v44, v44, v248, vcc
	v_cndmask_b32_e32 v45, v45, v249, vcc
	v_cndmask_b32_e32 v46, v46, v250, vcc
	v_cndmask_b32_e32 v47, v47, v251, vcc
	v_cndmask_b32_e32 v36, v36, v220, vcc
	v_cndmask_b32_e32 v37, v37, v221, vcc
	v_cndmask_b32_e32 v38, v38, v222, vcc
	v_cndmask_b32_e32 v39, v39, v223, vcc
	global_store_dwordx4 v204, v[244:247], s[84:85]
	global_store_dwordx4 v204, v[216:219], s[84:85] offset:512
	global_store_dwordx4 v205, v[44:47], s[84:85]
	global_store_dwordx4 v205, v[36:39], s[84:85] offset:512
	v_add_u32_e32 v207, 0x10000, v207
	v_add_u32_e32 v206, 0x10000, v206
	global_load_dwordx4 v[248:251], v206, s[70:71] offset:64
	global_load_dwordx4 v[220:223], v206, s[70:71] offset:576
	global_load_dwordx4 v[244:247], v206, s[70:71]
	global_load_dwordx4 v[216:219], v206, s[70:71] offset:512
	s_waitcnt lgkmcnt(0)
	v_add_f32_e32 v211, v210, v211
	ds_bpermute_b32 v212, v215, v211
	v_add_u32_e32 v208, 0x8000, v208
	s_waitcnt lgkmcnt(0)
	v_add_f32_e32 v211, v211, v212
	s_mov_b64 exec, 0xffff
	global_store_dword v209, v211, s[72:73]
	s_mov_b64 exec, -1
	v_add_u32_e32 v209, 0x400, v209
	s_waitcnt vmcnt(10)
	v_permlane32_swap_b32_e32 v228, v232
	v_permlane32_swap_b32_e32 v229, v233
	v_permlane32_swap_b32_e32 v230, v234
	v_permlane32_swap_b32_e32 v231, v235
	v_permlane32_swap_b32_e32 v236, v240
	v_permlane32_swap_b32_e32 v237, v241
	v_permlane32_swap_b32_e32 v238, v242
	v_permlane32_swap_b32_e32 v239, v243
	v_permlane16_swap_b32_e32 v228, v232
	v_permlane16_swap_b32_e32 v229, v233
	v_permlane16_swap_b32_e32 v230, v234
	v_permlane16_swap_b32_e32 v231, v235
	v_permlane16_swap_b32_e32 v236, v240
	v_permlane16_swap_b32_e32 v237, v241
	v_permlane16_swap_b32_e32 v238, v242
	v_permlane16_swap_b32_e32 v239, v243
	v_pk_fma_f32 v[28:29], v[28:29], v[80:81], v[228:229]
	v_pk_fma_f32 v[30:31], v[30:31], v[82:83], v[230:231]
	v_mul_f32_e32 v210, v29, v29
	v_fmac_f32_e32 v210, v28, v28
	v_fmac_f32_e32 v210, v30, v30
	v_fmac_f32_e32 v210, v31, v31
	v_pk_fma_f32 v[24:25], v[24:25], v[88:89], v[232:233]
	v_pk_fma_f32 v[26:27], v[26:27], v[90:91], v[234:235]
	v_fmac_f32_e32 v210, v24, v24
	v_fmac_f32_e32 v210, v25, v25
	v_fmac_f32_e32 v210, v26, v26
	v_fmac_f32_e32 v210, v27, v27
	v_pk_fma_f32 v[20:21], v[20:21], v[84:85], v[236:237]
	v_pk_fma_f32 v[22:23], v[22:23], v[86:87], v[238:239]
	v_fmac_f32_e32 v210, v20, v20
	v_fmac_f32_e32 v210, v21, v21
	v_fmac_f32_e32 v210, v22, v22
	v_fmac_f32_e32 v210, v23, v23
	v_pk_fma_f32 v[16:17], v[16:17], v[92:93], v[240:241]
	v_pk_fma_f32 v[18:19], v[18:19], v[94:95], v[242:243]
	v_fmac_f32_e32 v210, v16, v16
	v_fmac_f32_e32 v210, v17, v17
	v_fmac_f32_e32 v210, v18, v18
	v_fmac_f32_e32 v210, v19, v19
	s_cmp_lg_u64 s[0:1], 0
	s_cbranch_scc1 .Lnoap_D_7
	v_pk_mul_f32 v[228:229], v[64:65], v[28:29]
	v_pk_mul_f32 v[230:231], v[66:67], v[30:31]
	v_pk_mul_f32 v[232:233], v[72:73], v[24:25]
	v_pk_mul_f32 v[234:235], v[74:75], v[26:27]
	v_pk_mul_f32 v[236:237], v[68:69], v[20:21]
	v_pk_mul_f32 v[238:239], v[70:71], v[22:23]
	v_pk_mul_f32 v[240:241], v[76:77], v[16:17]
	v_pk_mul_f32 v[242:243], v[78:79], v[18:19]
	v_cvt_pk_bf16_f32 v228, v228, v229
	v_cvt_pk_bf16_f32 v229, v230, v231
	v_cvt_pk_bf16_f32 v230, v232, v233
	v_cvt_pk_bf16_f32 v231, v234, v235
	global_store_dwordx4 v208, v[228:231], s[28:29]
	v_cvt_pk_bf16_f32 v236, v236, v237
	v_cvt_pk_bf16_f32 v237, v238, v239
	v_cvt_pk_bf16_f32 v238, v240, v241
	v_cvt_pk_bf16_f32 v239, v242, v243
	global_store_dwordx4 v208, v[236:239], s[28:29] offset:256
; DI u32x4 pack8(const float* v) { u32x4 w; w.x = pk2(v[0], v[1]); w.y = pk2(v[2], v[3]); w.z = pk2(v[4], v[5]); w.w = pk2(v[6], v[7]); return w; }
; #define xor16_32(s) xor16_32_l((s), fr + 16 * fq)
;     DI void operator()(AccRef acc, const Unit& u, int wr, int wc, int fr, int fq) const {
;     ...
;             for (int m = 0; m < 4; ++m) {
;                 const int row = rb + 16 * m;
;                 const float* xi = row < MP ? xin_p + (size_t)row * 1024 : xin_s + (size_t)(row - MP) * 1024;
;                 float s = 0.f;
; #pragma unroll
;                 for (int bj = 0; bj < 2; ++bj) {
;                     const int c = u.pn * 256 + bj * 128 + cl;
;                     float v[8];
; #pragma unroll
;                     for (int n = 0; n < 2; ++n) {
;                         const f32x4 x = *(const f32x4*)(xi + c + 4 * n);
;                         const f32x4 y = x + gt[bj][n] * acc[ai][bj][m][n];
;                         *(f32x4*)(xout + (size_t)row * 1024 + c + 4 * n) = y;
; #pragma unroll
;                         for (int j = 0; j < 4; ++j) { s += y[j] * y[j]; v[4 * n + j] = ap ? y[j] * gs[bj][n][j] : 0.f; }
;                     }
;                     if (ap) *(u32x4*)(ap + (size_t)row * 1024 + c) = pack8(v);
;                 }
;                 s = xor16_32(s);
;                 if (fq == 0) ssq[(size_t)row * 16 + u.pn * 4 + wc] = s;
.Lnoap_D_7:
	ds_bpermute_b32 v211, v214, v210
	v_permlane16_swap_b32_e32 v28, v24
	v_permlane16_swap_b32_e32 v29, v25
	v_permlane16_swap_b32_e32 v30, v26
	v_permlane16_swap_b32_e32 v31, v27
	v_permlane16_swap_b32_e32 v20, v16
	v_permlane16_swap_b32_e32 v21, v17
	v_permlane16_swap_b32_e32 v22, v18
	v_permlane16_swap_b32_e32 v23, v19
	v_permlane32_swap_b32_e32 v28, v24
	v_permlane32_swap_b32_e32 v29, v25
	v_permlane32_swap_b32_e32 v30, v26
	v_permlane32_swap_b32_e32 v31, v27
	v_permlane32_swap_b32_e32 v20, v16
	v_permlane32_swap_b32_e32 v21, v17
	v_permlane32_swap_b32_e32 v22, v18
	v_permlane32_swap_b32_e32 v23, v19
	s_nop 1
	v_mov_b32_dpp v232, v24 row_ror:8 row_mask:0xf bank_mask:0xf
	v_mov_b32_dpp v233, v25 row_ror:8 row_mask:0xf bank_mask:0xf
	v_mov_b32_dpp v234, v26 row_ror:8 row_mask:0xf bank_mask:0xf
	v_mov_b32_dpp v235, v27 row_ror:8 row_mask:0xf bank_mask:0xf
	v_mov_b32_dpp v240, v16 row_ror:8 row_mask:0xf bank_mask:0xf
	v_mov_b32_dpp v241, v17 row_ror:8 row_mask:0xf bank_mask:0xf
	v_mov_b32_dpp v242, v18 row_ror:8 row_mask:0xf bank_mask:0xf
	v_mov_b32_dpp v243, v19 row_ror:8 row_mask:0xf bank_mask:0xf
	s_mov_b32 vcc_lo, 0xff00ff
	s_mov_b32 vcc_hi, 0xff00ff
	v_mov_b32_e32 v204, 0xffff8040
	v_mov_b32_e32 v205, 0x8040
	v_cndmask_b32_e64 v204, v204, 0, vcc
	v_cndmask_b32_e64 v205, 0, v205, vcc
	v_add_u32_e32 v204, v204, v207
	v_add_u32_e32 v205, v205, v207
	v_cndmask_b32_e32 v228, v232, v28, vcc
	v_cndmask_b32_e32 v229, v233, v29, vcc
	v_cndmask_b32_e32 v230, v234, v30, vcc
	v_cndmask_b32_e32 v231, v235, v31, vcc
	v_cndmask_b32_e32 v236, v240, v20, vcc
	v_cndmask_b32_e32 v237, v241, v21, vcc
	v_cndmask_b32_e32 v238, v242, v22, vcc
	v_cndmask_b32_e32 v239, v243, v23, vcc
	v_cndmask_b32_e32 v28, v28, v232, vcc
	v_cndmask_b32_e32 v29, v29, v233, vcc
	v_cndmask_b32_e32 v30, v30, v234, vcc
	v_cndmask_b32_e32 v31, v31, v235, vcc
	v_cndmask_b32_e32 v20, v20, v240, vcc
	v_cndmask_b32_e32 v21, v21, v241, vcc
	v_cndmask_b32_e32 v22, v22, v242, vcc
	v_cndmask_b32_e32 v23, v23, v243, vcc
	global_store_dwordx4 v204, v[228:231], s[84:85]
	global_store_dwordx4 v204, v[236:239], s[84:85] offset:512
	global_store_dwordx4 v205, v[28:31], s[84:85]
	global_store_dwordx4 v205, v[20:23], s[84:85] offset:512
	v_add_u32_e32 v207, 0x10000, v207
	s_waitcnt lgkmcnt(0)
	v_add_f32_e32 v211, v210, v211
	ds_bpermute_b32 v212, v215, v211
	v_add_u32_e32 v208, 0x8000, v208
	s_waitcnt lgkmcnt(0)
	v_add_f32_e32 v211, v211, v212
	s_mov_b64 exec, 0xffff
	global_store_dword v209, v211, s[72:73]
	s_mov_b64 exec, -1
	v_add_u32_e32 v209, 0x400, v209
	s_waitcnt vmcnt(6)
	v_permlane32_swap_b32_e32 v244, v248
	v_permlane32_swap_b32_e32 v245, v249
	v_permlane32_swap_b32_e32 v246, v250
	v_permlane32_swap_b32_e32 v247, v251
	v_permlane32_swap_b32_e32 v216, v220
	v_permlane32_swap_b32_e32 v217, v221
	v_permlane32_swap_b32_e32 v218, v222
	v_permlane32_swap_b32_e32 v219, v223
	v_permlane16_swap_b32_e32 v244, v248
	v_permlane16_swap_b32_e32 v245, v249
	v_permlane16_swap_b32_e32 v246, v250
	v_permlane16_swap_b32_e32 v247, v251
	v_permlane16_swap_b32_e32 v216, v220
	v_permlane16_swap_b32_e32 v217, v221
	v_permlane16_swap_b32_e32 v218, v222
	v_permlane16_swap_b32_e32 v219, v223
	v_pk_fma_f32 v[12:13], v[12:13], v[80:81], v[244:245]
	v_pk_fma_f32 v[14:15], v[14:15], v[82:83], v[246:247]
	v_mul_f32_e32 v210, v13, v13
	v_fmac_f32_e32 v210, v12, v12
	v_fmac_f32_e32 v210, v14, v14
	v_fmac_f32_e32 v210, v15, v15
	v_pk_fma_f32 v[8:9], v[8:9], v[88:89], v[248:249]
	v_pk_fma_f32 v[10:11], v[10:11], v[90:91], v[250:251]
	v_fmac_f32_e32 v210, v8, v8
	v_fmac_f32_e32 v210, v9, v9
	v_fmac_f32_e32 v210, v10, v10
	v_fmac_f32_e32 v210, v11, v11
	v_pk_fma_f32 v[4:5], v[4:5], v[84:85], v[216:217]
	v_pk_fma_f32 v[6:7], v[6:7], v[86:87], v[218:219]
	v_fmac_f32_e32 v210, v4, v4
	v_fmac_f32_e32 v210, v5, v5
	v_fmac_f32_e32 v210, v6, v6
	v_fmac_f32_e32 v210, v7, v7
	v_pk_fma_f32 v[0:1], v[0:1], v[92:93], v[220:221]
	v_pk_fma_f32 v[2:3], v[2:3], v[94:95], v[222:223]
	v_fmac_f32_e32 v210, v0, v0
	v_fmac_f32_e32 v210, v1, v1
	v_fmac_f32_e32 v210, v2, v2
	v_fmac_f32_e32 v210, v3, v3
	s_cmp_lg_u64 s[0:1], 0
	s_cbranch_scc1 .Lnoap_D_8
	v_pk_mul_f32 v[244:245], v[64:65], v[12:13]
	v_pk_mul_f32 v[246:247], v[66:67], v[14:15]
	v_pk_mul_f32 v[248:249], v[72:73], v[8:9]
	v_pk_mul_f32 v[250:251], v[74:75], v[10:11]
	v_pk_mul_f32 v[216:217], v[68:69], v[4:5]
	v_pk_mul_f32 v[218:219], v[70:71], v[6:7]
	v_pk_mul_f32 v[220:221], v[76:77], v[0:1]
	v_pk_mul_f32 v[222:223], v[78:79], v[2:3]
	v_cvt_pk_bf16_f32 v244, v244, v245
	v_cvt_pk_bf16_f32 v245, v246, v247
	v_cvt_pk_bf16_f32 v246, v248, v249
	v_cvt_pk_bf16_f32 v247, v250, v251
	global_store_dwordx4 v208, v[244:247], s[28:29]
	v_cvt_pk_bf16_f32 v216, v216, v217
	v_cvt_pk_bf16_f32 v217, v218, v219
	v_cvt_pk_bf16_f32 v218, v220, v221
	v_cvt_pk_bf16_f32 v219, v222, v223
	global_store_dwordx4 v208, v[216:219], s[28:29] offset:256
; DI u32x4 pack8(const float* v) { u32x4 w; w.x = pk2(v[0], v[1]); w.y = pk2(v[2], v[3]); w.z = pk2(v[4], v[5]); w.w = pk2(v[6], v[7]); return w; }
; #define xor16_32(s) xor16_32_l((s), fr + 16 * fq)
;     DI void operator()(AccRef acc, const Unit& u, int wr, int wc, int fr, int fq) const {
;     ...
;                     for (int n = 0; n < 2; ++n) {
;                         const f32x4 x = *(const f32x4*)(xi + c + 4 * n);
;                         const f32x4 y = x + gt[bj][n] * acc[ai][bj][m][n];
;                         *(f32x4*)(xout + (size_t)row * 1024 + c + 4 * n) = y;
; #pragma unroll
;                         for (int j = 0; j < 4; ++j) { s += y[j] * y[j]; v[4 * n + j] = ap ? y[j] * gs[bj][n][j] : 0.f; }
;                     }
;                     if (ap) *(u32x4*)(ap + (size_t)row * 1024 + c) = pack8(v);
;                 }
;                 s = xor16_32(s);
;                 if (fq == 0) ssq[(size_t)row * 16 + u.pn * 4 + wc] = s;
;             }
.Lnoap_D_8:
	ds_bpermute_b32 v211, v214, v210
	v_permlane16_swap_b32_e32 v12, v8
	v_permlane16_swap_b32_e32 v13, v9
	v_permlane16_swap_b32_e32 v14, v10
	v_permlane16_swap_b32_e32 v15, v11
	v_permlane16_swap_b32_e32 v4, v0
	v_permlane16_swap_b32_e32 v5, v1
	v_permlane16_swap_b32_e32 v6, v2
	v_permlane16_swap_b32_e32 v7, v3
	v_permlane32_swap_b32_e32 v12, v8
	v_permlane32_swap_b32_e32 v13, v9
	v_permlane32_swap_b32_e32 v14, v10
	v_permlane32_swap_b32_e32 v15, v11
	v_permlane32_swap_b32_e32 v4, v0
	v_permlane32_swap_b32_e32 v5, v1
	v_permlane32_swap_b32_e32 v6, v2
	v_permlane32_swap_b32_e32 v7, v3
	s_nop 1
	v_mov_b32_dpp v248, v8 row_ror:8 row_mask:0xf bank_mask:0xf
	v_mov_b32_dpp v249, v9 row_ror:8 row_mask:0xf bank_mask:0xf
	v_mov_b32_dpp v250, v10 row_ror:8 row_mask:0xf bank_mask:0xf
	v_mov_b32_dpp v251, v11 row_ror:8 row_mask:0xf bank_mask:0xf
	v_mov_b32_dpp v220, v0 row_ror:8 row_mask:0xf bank_mask:0xf
	v_mov_b32_dpp v221, v1 row_ror:8 row_mask:0xf bank_mask:0xf
	v_mov_b32_dpp v222, v2 row_ror:8 row_mask:0xf bank_mask:0xf
	v_mov_b32_dpp v223, v3 row_ror:8 row_mask:0xf bank_mask:0xf
	s_mov_b32 vcc_lo, 0xff00ff
	s_mov_b32 vcc_hi, 0xff00ff
	v_mov_b32_e32 v204, 0xffff8040
	v_mov_b32_e32 v205, 0x8040
	v_cndmask_b32_e64 v204, v204, 0, vcc
	v_cndmask_b32_e64 v205, 0, v205, vcc
	v_add_u32_e32 v204, v204, v207
	v_add_u32_e32 v205, v205, v207
	v_cndmask_b32_e32 v244, v248, v12, vcc
	v_cndmask_b32_e32 v245, v249, v13, vcc
	v_cndmask_b32_e32 v246, v250, v14, vcc
	v_cndmask_b32_e32 v247, v251, v15, vcc
	v_cndmask_b32_e32 v216, v220, v4, vcc
	v_cndmask_b32_e32 v217, v221, v5, vcc
	v_cndmask_b32_e32 v218, v222, v6, vcc
	v_cndmask_b32_e32 v219, v223, v7, vcc
	v_cndmask_b32_e32 v12, v12, v248, vcc
	v_cndmask_b32_e32 v13, v13, v249, vcc
	v_cndmask_b32_e32 v14, v14, v250, vcc
	v_cndmask_b32_e32 v15, v15, v251, vcc
	v_cndmask_b32_e32 v4, v4, v220, vcc
	v_cndmask_b32_e32 v5, v5, v221, vcc
	v_cndmask_b32_e32 v6, v6, v222, vcc
	v_cndmask_b32_e32 v7, v7, v223, vcc
	global_store_dwordx4 v204, v[244:247], s[84:85]
	global_store_dwordx4 v204, v[216:219], s[84:85] offset:512
	global_store_dwordx4 v205, v[12:15], s[84:85]
	global_store_dwordx4 v205, v[4:7], s[84:85] offset:512
	s_waitcnt lgkmcnt(0)
	v_add_f32_e32 v211, v210, v211
	ds_bpermute_b32 v212, v215, v211
	s_waitcnt lgkmcnt(0)
	v_add_f32_e32 v211, v211, v212
	s_mov_b64 exec, 0xffff
	global_store_dword v209, v211, s[72:73]
	s_mov_b64 exec, -1
	s_and_b64 vcc, exec, s[2:3]
	s_mov_b64 s[2:3], -1
	s_cbranch_vccnz .LBB0_2034
	s_andn2_b64 vcc, exec, s[8:9]
	s_cbranch_vccnz .LBB0_2033
	s_barrier
	s_branch .LBB0_2033
